# MLA token loop: token rows prefetched one iteration ahead; SGU layer-norm writes packed 2 tokens per ds_write_b32; out-GEMM epilogue issue order avoids vmcnt saturation; dropped zero-gain edits
# speedup vs baseline: 1.0976x; 1.0039x over previous
; DEVI int crow(int r, int hi) { return (r & 3) + 8 * (r >> 2) + 4 * hi; }
;   DEVI void operator()(const f32x16 (&acc)[2][2], int m0, int n0, int wm, int wn, int r32, int hi, char* lds) const {
;     const int mb = m0 + wm * 64, nb = n0 + wn * 64;
;     int b = seq_of(mb);
;     const float* gate = (const float*)(p->ws + OFF_MOD) + ((size_t)layer * 18 + b) * 3072 + 2048;
; #pragma unroll
;     for (int i = 0; i < 2; ++i)
; #pragma unroll
;       for (int j = 0; j < 2; ++j) {
;         int col = nb + j * 32 + r32; float g = gate[col];
; #pragma unroll
;         for (int r = 0; r < 16; ++r) {
;           int row = mb + i * 32 + crow(r, hi);
;           float xv = xrow(*p, layer, row)[col];
;           p->out[(size_t)row * DM + col] = xv + g * acc[i][j][r];
;         }
;       }
;   }
.Lepi_x_done:
	v_lshl_add_u32 v67, v136, 2, v157
	v_lshlrev_b32_e32 v67, 12, v67
	v_lshl_add_u32 v67, v64, 2, v67
	s_add_u32 s16, s38, 0x0
	s_addc_u32 s17, s39, 0
	global_load_dword v72, v67, s[16:17]
	s_add_u32 s16, s38, 0x0
	s_addc_u32 s17, s39, 0
	global_load_dword v73, v67, s[16:17] offset:128
	s_add_u32 s16, s38, 0x1000
	s_addc_u32 s17, s39, 0
	global_load_dword v74, v67, s[16:17]
	s_add_u32 s16, s38, 0x1000
	s_addc_u32 s17, s39, 0
	global_load_dword v75, v67, s[16:17] offset:128
	s_add_u32 s16, s38, 0x2000
	s_addc_u32 s17, s39, 0
	global_load_dword v76, v67, s[16:17]
	s_add_u32 s16, s38, 0x2000
	s_addc_u32 s17, s39, 0
	global_load_dword v77, v67, s[16:17] offset:128
	s_add_u32 s16, s38, 0x3000
	s_addc_u32 s17, s39, 0
	global_load_dword v78, v67, s[16:17]
	s_add_u32 s16, s38, 0x3000
	s_addc_u32 s17, s39, 0
	global_load_dword v79, v67, s[16:17] offset:128
	s_add_u32 s16, s38, 0x8000
	s_addc_u32 s17, s39, 0
	global_load_dword v80, v67, s[16:17]
	s_add_u32 s16, s38, 0x8000
	s_addc_u32 s17, s39, 0
	global_load_dword v81, v67, s[16:17] offset:128
	s_add_u32 s16, s38, 0x9000
	s_addc_u32 s17, s39, 0
	global_load_dword v82, v67, s[16:17]
	s_add_u32 s16, s38, 0x9000
	s_addc_u32 s17, s39, 0
	global_load_dword v83, v67, s[16:17] offset:128
	s_add_u32 s16, s38, 0xa000
	s_addc_u32 s17, s39, 0
	global_load_dword v84, v67, s[16:17]
	s_add_u32 s16, s38, 0xa000
	s_addc_u32 s17, s39, 0
	global_load_dword v85, v67, s[16:17] offset:128
	s_add_u32 s16, s38, 0xb000
	s_addc_u32 s17, s39, 0
	global_load_dword v86, v67, s[16:17]
	s_add_u32 s16, s38, 0xb000
	s_addc_u32 s17, s39, 0
	global_load_dword v87, v67, s[16:17] offset:128
	s_add_u32 s16, s38, 0x10000
	s_addc_u32 s17, s39, 0
	global_load_dword v88, v67, s[16:17]
	s_add_u32 s16, s38, 0x10000
	s_addc_u32 s17, s39, 0
	global_load_dword v89, v67, s[16:17] offset:128
	s_add_u32 s16, s38, 0x11000
	s_addc_u32 s17, s39, 0
	global_load_dword v90, v67, s[16:17]
	s_add_u32 s16, s38, 0x11000
	s_addc_u32 s17, s39, 0
	global_load_dword v91, v67, s[16:17] offset:128
	s_add_u32 s16, s38, 0x12000
	s_addc_u32 s17, s39, 0
	global_load_dword v92, v67, s[16:17]
	s_add_u32 s16, s38, 0x12000
	s_addc_u32 s17, s39, 0
	global_load_dword v93, v67, s[16:17] offset:128
	s_add_u32 s16, s38, 0x13000
	s_addc_u32 s17, s39, 0
	global_load_dword v94, v67, s[16:17]
	s_add_u32 s16, s38, 0x13000
	s_addc_u32 s17, s39, 0
	global_load_dword v95, v67, s[16:17] offset:128
	s_add_u32 s16, s38, 0x18000
	s_addc_u32 s17, s39, 0
	global_load_dword v96, v67, s[16:17]
	s_add_u32 s16, s38, 0x18000
	s_addc_u32 s17, s39, 0
	global_load_dword v97, v67, s[16:17] offset:128
	s_add_u32 s16, s38, 0x19000
	s_addc_u32 s17, s39, 0
	global_load_dword v98, v67, s[16:17]
	s_add_u32 s16, s38, 0x19000
	s_addc_u32 s17, s39, 0
	global_load_dword v99, v67, s[16:17] offset:128
	s_add_u32 s16, s38, 0x1a000
	s_addc_u32 s17, s39, 0
	global_load_dword v100, v67, s[16:17]
	s_add_u32 s16, s38, 0x1a000
	s_addc_u32 s17, s39, 0
	global_load_dword v101, v67, s[16:17] offset:128
	s_add_u32 s16, s38, 0x1b000
	s_addc_u32 s17, s39, 0
	global_load_dword v102, v67, s[16:17]
	s_add_u32 s16, s38, 0x1b000
	s_addc_u32 s17, s39, 0
	global_load_dword v103, v67, s[16:17] offset:128
	s_add_u32 s16, s38, 0x20000
	s_addc_u32 s17, s39, 0
	global_load_dword v222, v67, s[16:17]
	s_add_u32 s16, s38, 0x20000
	s_addc_u32 s17, s39, 0
	global_load_dword v223, v67, s[16:17] offset:128
	s_add_u32 s16, s38, 0x21000
	s_addc_u32 s17, s39, 0
	global_load_dword v224, v67, s[16:17]
	s_add_u32 s16, s38, 0x21000
	s_addc_u32 s17, s39, 0
	global_load_dword v225, v67, s[16:17] offset:128
	s_add_u32 s16, s38, 0x22000
	s_addc_u32 s17, s39, 0
	global_load_dword v226, v67, s[16:17]
	s_add_u32 s16, s38, 0x22000
	s_addc_u32 s17, s39, 0
	global_load_dword v227, v67, s[16:17] offset:128
	s_add_u32 s16, s38, 0x23000
	s_addc_u32 s17, s39, 0
	global_load_dword v228, v67, s[16:17]
	s_add_u32 s16, s38, 0x23000
	s_addc_u32 s17, s39, 0
	global_load_dword v229, v67, s[16:17] offset:128
	s_add_u32 s16, s38, 0x28000
	s_addc_u32 s17, s39, 0
	global_load_dword v230, v67, s[16:17]
	s_add_u32 s16, s38, 0x28000
	s_addc_u32 s17, s39, 0
	global_load_dword v231, v67, s[16:17] offset:128
	s_add_u32 s16, s38, 0x29000
	s_addc_u32 s17, s39, 0
	global_load_dword v232, v67, s[16:17]
	s_add_u32 s16, s38, 0x29000
	s_addc_u32 s17, s39, 0
	global_load_dword v233, v67, s[16:17] offset:128
	s_add_u32 s16, s38, 0x2a000
	s_addc_u32 s17, s39, 0
	global_load_dword v234, v67, s[16:17]
	s_add_u32 s16, s38, 0x2a000
	s_addc_u32 s17, s39, 0
	global_load_dword v235, v67, s[16:17] offset:128
	s_add_u32 s16, s38, 0x2b000
	s_addc_u32 s17, s39, 0
	global_load_dword v236, v67, s[16:17]
	s_add_u32 s16, s38, 0x2b000
	s_addc_u32 s17, s39, 0
	global_load_dword v237, v67, s[16:17] offset:128
	s_add_u32 s16, s38, 0x30000
	s_addc_u32 s17, s39, 0
	global_load_dword v238, v67, s[16:17]
	s_add_u32 s16, s38, 0x30000
	s_addc_u32 s17, s39, 0
	global_load_dword v239, v67, s[16:17] offset:128
	s_add_u32 s16, s38, 0x31000
	s_addc_u32 s17, s39, 0
	global_load_dword v240, v67, s[16:17]
	s_add_u32 s16, s38, 0x31000
	s_addc_u32 s17, s39, 0
	global_load_dword v241, v67, s[16:17] offset:128
	s_add_u32 s16, s38, 0x32000
	s_addc_u32 s17, s39, 0
	global_load_dword v242, v67, s[16:17]
	s_add_u32 s16, s38, 0x32000
	s_addc_u32 s17, s39, 0
	global_load_dword v243, v67, s[16:17] offset:128
	s_add_u32 s16, s38, 0x33000
	s_addc_u32 s17, s39, 0
	global_load_dword v244, v67, s[16:17]
	s_add_u32 s16, s38, 0x33000
	s_addc_u32 s17, s39, 0
	global_load_dword v245, v67, s[16:17] offset:128
	s_add_u32 s16, s38, 0x38000
	s_addc_u32 s17, s39, 0
	global_load_dword v246, v67, s[16:17]
	s_add_u32 s16, s38, 0x38000
	s_addc_u32 s17, s39, 0
	global_load_dword v247, v67, s[16:17] offset:128
	s_add_u32 s16, s38, 0x39000
	s_addc_u32 s17, s39, 0
	global_load_dword v248, v67, s[16:17]
	s_add_u32 s16, s38, 0x39000
	s_addc_u32 s17, s39, 0
	global_load_dword v249, v67, s[16:17] offset:128
	s_add_u32 s16, s52, 0x0
	s_addc_u32 s17, s53, 0
	s_waitcnt vmcnt(59)
; DEVI int crow(int r, int hi) { return (r & 3) + 8 * (r >> 2) + 4 * hi; }
;   DEVI void operator()(const f32x16 (&acc)[2][2], int m0, int n0, int wm, int wn, int r32, int hi, char* lds) const {
;     const int mb = m0 + wm * 64, nb = n0 + wn * 64;
;     int b = seq_of(mb);
;     const float* gate = (const float*)(p->ws + OFF_MOD) + ((size_t)layer * 18 + b) * 3072 + 2048;
; #pragma unroll
;     for (int i = 0; i < 2; ++i)
; #pragma unroll
;       for (int j = 0; j < 2; ++j) {
;         int col = nb + j * 32 + r32; float g = gate[col];
; #pragma unroll
;         for (int r = 0; r < 16; ++r) {
;           int row = mb + i * 32 + crow(r, hi);
;           float xv = xrow(*p, layer, row)[col];
;           p->out[(size_t)row * DM + col] = xv + g * acc[i][j][r];
;         }
;       }
;   }
	v_fmac_f32_e32 v72, v48, v126
	global_store_dword v67, v72, s[16:17]
	s_add_u32 s16, s38, 0x3a000
	s_addc_u32 s17, s39, 0
	global_load_dword v250, v67, s[16:17]
	s_add_u32 s16, s52, 0x0
	s_addc_u32 s17, s53, 0
	s_waitcnt vmcnt(60)
	v_fmac_f32_e32 v73, v32, v127
	global_store_dword v67, v73, s[16:17] offset:128
	s_add_u32 s16, s38, 0x3a000
	s_addc_u32 s17, s39, 0
	global_load_dword v251, v67, s[16:17] offset:128
	s_add_u32 s16, s52, 0x1000
	s_addc_u32 s17, s53, 0
	s_waitcnt vmcnt(61)
	v_fmac_f32_e32 v74, v49, v126
	global_store_dword v67, v74, s[16:17]
	s_add_u32 s16, s38, 0x3b000
	s_addc_u32 s17, s39, 0
	global_load_dword v252, v67, s[16:17]
	s_add_u32 s16, s52, 0x1000
	s_addc_u32 s17, s53, 0
	s_waitcnt vmcnt(62)
	v_fmac_f32_e32 v75, v33, v127
	global_store_dword v67, v75, s[16:17] offset:128
	s_add_u32 s16, s38, 0x3b000
	s_addc_u32 s17, s39, 0
	global_load_dword v253, v67, s[16:17] offset:128
	s_add_u32 s16, s52, 0x2000
	s_addc_u32 s17, s53, 0
	s_waitcnt vmcnt(63)
	v_fmac_f32_e32 v76, v50, v126
	global_store_dword v67, v76, s[16:17]
	s_add_u32 s16, s52, 0x2000
	s_addc_u32 s17, s53, 0
	s_waitcnt vmcnt(63)
	v_fmac_f32_e32 v77, v34, v127
	global_store_dword v67, v77, s[16:17] offset:128
	s_add_u32 s16, s52, 0x3000
	s_addc_u32 s17, s53, 0
	s_waitcnt vmcnt(63)
	v_fmac_f32_e32 v78, v51, v126
	global_store_dword v67, v78, s[16:17]
	s_add_u32 s16, s52, 0x3000
	s_addc_u32 s17, s53, 0
	s_waitcnt vmcnt(63)
	v_fmac_f32_e32 v79, v35, v127
	global_store_dword v67, v79, s[16:17] offset:128
	s_add_u32 s16, s52, 0x8000
	s_addc_u32 s17, s53, 0
	s_waitcnt vmcnt(63)
	v_fmac_f32_e32 v80, v52, v126
	global_store_dword v67, v80, s[16:17]
	s_add_u32 s16, s52, 0x8000
	s_addc_u32 s17, s53, 0
	s_waitcnt vmcnt(63)
	v_fmac_f32_e32 v81, v36, v127
	global_store_dword v67, v81, s[16:17] offset:128
	s_add_u32 s16, s52, 0x9000
	s_addc_u32 s17, s53, 0
	s_waitcnt vmcnt(63)
	v_fmac_f32_e32 v82, v53, v126
	global_store_dword v67, v82, s[16:17]
	s_add_u32 s16, s52, 0x9000
	s_addc_u32 s17, s53, 0
	s_waitcnt vmcnt(63)
	v_fmac_f32_e32 v83, v37, v127
	global_store_dword v67, v83, s[16:17] offset:128
	s_add_u32 s16, s52, 0xa000
	s_addc_u32 s17, s53, 0
	s_waitcnt vmcnt(63)
	v_fmac_f32_e32 v84, v54, v126
	global_store_dword v67, v84, s[16:17]
	s_add_u32 s16, s52, 0xa000
	s_addc_u32 s17, s53, 0
	s_waitcnt vmcnt(63)
	v_fmac_f32_e32 v85, v38, v127
	global_store_dword v67, v85, s[16:17] offset:128
	s_add_u32 s16, s52, 0xb000
	s_addc_u32 s17, s53, 0
	s_waitcnt vmcnt(63)
	v_fmac_f32_e32 v86, v55, v126
	global_store_dword v67, v86, s[16:17]
	s_add_u32 s16, s52, 0xb000
	s_addc_u32 s17, s53, 0
	s_waitcnt vmcnt(63)
	v_fmac_f32_e32 v87, v39, v127
	global_store_dword v67, v87, s[16:17] offset:128
	s_add_u32 s16, s52, 0x10000
	s_addc_u32 s17, s53, 0
	s_waitcnt vmcnt(63)
	v_fmac_f32_e32 v88, v56, v126
	global_store_dword v67, v88, s[16:17]
	s_add_u32 s16, s52, 0x10000
	s_addc_u32 s17, s53, 0
	s_waitcnt vmcnt(63)
	v_fmac_f32_e32 v89, v40, v127
	global_store_dword v67, v89, s[16:17] offset:128
	s_add_u32 s16, s52, 0x11000
	s_addc_u32 s17, s53, 0
	s_waitcnt vmcnt(63)
	v_fmac_f32_e32 v90, v57, v126
	global_store_dword v67, v90, s[16:17]
	s_add_u32 s16, s52, 0x11000
	s_addc_u32 s17, s53, 0
	s_waitcnt vmcnt(63)
	v_fmac_f32_e32 v91, v41, v127
	global_store_dword v67, v91, s[16:17] offset:128
	s_add_u32 s16, s52, 0x12000
	s_addc_u32 s17, s53, 0
	s_waitcnt vmcnt(63)
	v_fmac_f32_e32 v92, v58, v126
	global_store_dword v67, v92, s[16:17]
	s_add_u32 s16, s52, 0x12000
	s_addc_u32 s17, s53, 0
	s_waitcnt vmcnt(63)
	v_fmac_f32_e32 v93, v42, v127
	global_store_dword v67, v93, s[16:17] offset:128
	s_add_u32 s16, s52, 0x13000
	s_addc_u32 s17, s53, 0
	s_waitcnt vmcnt(63)
	v_fmac_f32_e32 v94, v59, v126
	global_store_dword v67, v94, s[16:17]
	s_add_u32 s16, s52, 0x13000
	s_addc_u32 s17, s53, 0
	s_waitcnt vmcnt(63)
	v_fmac_f32_e32 v95, v43, v127
	global_store_dword v67, v95, s[16:17] offset:128
	s_add_u32 s16, s52, 0x18000
	s_addc_u32 s17, s53, 0
	s_waitcnt vmcnt(63)
	v_fmac_f32_e32 v96, v60, v126
	global_store_dword v67, v96, s[16:17]
	s_add_u32 s16, s52, 0x18000
	s_addc_u32 s17, s53, 0
	s_waitcnt vmcnt(63)
	v_fmac_f32_e32 v97, v44, v127
	global_store_dword v67, v97, s[16:17] offset:128
	s_add_u32 s16, s52, 0x19000
	s_addc_u32 s17, s53, 0
	s_waitcnt vmcnt(63)
	v_fmac_f32_e32 v98, v61, v126
	global_store_dword v67, v98, s[16:17]
	s_add_u32 s16, s52, 0x19000
	s_addc_u32 s17, s53, 0
	s_waitcnt vmcnt(63)
	v_fmac_f32_e32 v99, v45, v127
	global_store_dword v67, v99, s[16:17] offset:128
	s_add_u32 s16, s52, 0x1a000
	s_addc_u32 s17, s53, 0
	s_waitcnt vmcnt(63)
	v_fmac_f32_e32 v100, v62, v126
	global_store_dword v67, v100, s[16:17]
	s_add_u32 s16, s52, 0x1a000
	s_addc_u32 s17, s53, 0
	s_waitcnt vmcnt(63)
	v_fmac_f32_e32 v101, v46, v127
	global_store_dword v67, v101, s[16:17] offset:128
	s_add_u32 s16, s52, 0x1b000
	s_addc_u32 s17, s53, 0
	s_waitcnt vmcnt(63)
	v_fmac_f32_e32 v102, v63, v126
	global_store_dword v67, v102, s[16:17]
	s_add_u32 s16, s52, 0x1b000
	s_addc_u32 s17, s53, 0
	s_waitcnt vmcnt(63)
	v_fmac_f32_e32 v103, v47, v127
	global_store_dword v67, v103, s[16:17] offset:128
	s_add_u32 s16, s52, 0x20000
	s_addc_u32 s17, s53, 0
	s_waitcnt vmcnt(63)
; DEVI int crow(int r, int hi) { return (r & 3) + 8 * (r >> 2) + 4 * hi; }
;   DEVI void operator()(const f32x16 (&acc)[2][2], int m0, int n0, int wm, int wn, int r32, int hi, char* lds) const {
;     ...
; #pragma unroll
;     for (int i = 0; i < 2; ++i)
; #pragma unroll
;       for (int j = 0; j < 2; ++j) {
;         int col = nb + j * 32 + r32; float g = gate[col];
; #pragma unroll
;         for (int r = 0; r < 16; ++r) {
;           int row = mb + i * 32 + crow(r, hi);
;           float xv = xrow(*p, layer, row)[col];
;           p->out[(size_t)row * DM + col] = xv + g * acc[i][j][r];
;         }
;       }
; template <class AS, class EP>
; DEVI void gemm_phase(const AS& as, const u16* Bt, int K, int mtiles, int ntiles, const EP& ep, char* lds) {
;     ...
;     for (int lt = j; lt < ltot; lt += nb) {
;       int mt = (lt / ntiles) * 8 + x, nt = lt % ntiles;
;       gemm_tile(as, Bt, K, mt * 256, nt * 128, ep, lds);
;     }
	v_fmac_f32_e32 v222, v16, v126
	global_store_dword v67, v222, s[16:17]
	s_add_u32 s16, s52, 0x20000
	s_addc_u32 s17, s53, 0
	s_waitcnt vmcnt(63)
	v_fmac_f32_e32 v223, v0, v127
	global_store_dword v67, v223, s[16:17] offset:128
	s_add_u32 s16, s52, 0x21000
	s_addc_u32 s17, s53, 0
	s_waitcnt vmcnt(63)
	v_fmac_f32_e32 v224, v17, v126
	global_store_dword v67, v224, s[16:17]
	s_add_u32 s16, s52, 0x21000
	s_addc_u32 s17, s53, 0
	s_waitcnt vmcnt(63)
	v_fmac_f32_e32 v225, v1, v127
	global_store_dword v67, v225, s[16:17] offset:128
	s_add_u32 s16, s52, 0x22000
	s_addc_u32 s17, s53, 0
	s_waitcnt vmcnt(63)
	v_fmac_f32_e32 v226, v18, v126
	global_store_dword v67, v226, s[16:17]
	s_add_u32 s16, s52, 0x22000
	s_addc_u32 s17, s53, 0
	s_waitcnt vmcnt(63)
	v_fmac_f32_e32 v227, v2, v127
	global_store_dword v67, v227, s[16:17] offset:128
	s_add_u32 s16, s52, 0x23000
	s_addc_u32 s17, s53, 0
	s_waitcnt vmcnt(63)
	v_fmac_f32_e32 v228, v19, v126
	global_store_dword v67, v228, s[16:17]
	s_add_u32 s16, s52, 0x23000
	s_addc_u32 s17, s53, 0
	s_waitcnt vmcnt(63)
	v_fmac_f32_e32 v229, v3, v127
	global_store_dword v67, v229, s[16:17] offset:128
	s_add_u32 s16, s52, 0x28000
	s_addc_u32 s17, s53, 0
	s_waitcnt vmcnt(63)
	v_fmac_f32_e32 v230, v20, v126
	global_store_dword v67, v230, s[16:17]
	s_add_u32 s16, s52, 0x28000
	s_addc_u32 s17, s53, 0
	s_waitcnt vmcnt(63)
	v_fmac_f32_e32 v231, v4, v127
	global_store_dword v67, v231, s[16:17] offset:128
	s_add_u32 s16, s52, 0x29000
	s_addc_u32 s17, s53, 0
	s_waitcnt vmcnt(63)
	v_fmac_f32_e32 v232, v21, v126
	global_store_dword v67, v232, s[16:17]
	s_add_u32 s16, s52, 0x29000
	s_addc_u32 s17, s53, 0
	s_waitcnt vmcnt(63)
	v_fmac_f32_e32 v233, v5, v127
	global_store_dword v67, v233, s[16:17] offset:128
	s_add_u32 s16, s52, 0x2a000
	s_addc_u32 s17, s53, 0
	s_waitcnt vmcnt(63)
	v_fmac_f32_e32 v234, v22, v126
	global_store_dword v67, v234, s[16:17]
	s_add_u32 s16, s52, 0x2a000
	s_addc_u32 s17, s53, 0
	s_waitcnt vmcnt(63)
	v_fmac_f32_e32 v235, v6, v127
	global_store_dword v67, v235, s[16:17] offset:128
	s_add_u32 s16, s52, 0x2b000
	s_addc_u32 s17, s53, 0
	s_waitcnt vmcnt(63)
	v_fmac_f32_e32 v236, v23, v126
	global_store_dword v67, v236, s[16:17]
	s_add_u32 s16, s52, 0x2b000
	s_addc_u32 s17, s53, 0
	s_waitcnt vmcnt(63)
	v_fmac_f32_e32 v237, v7, v127
	global_store_dword v67, v237, s[16:17] offset:128
	s_add_u32 s16, s52, 0x30000
	s_addc_u32 s17, s53, 0
	s_waitcnt vmcnt(63)
	v_fmac_f32_e32 v238, v24, v126
	global_store_dword v67, v238, s[16:17]
	s_add_u32 s16, s52, 0x30000
	s_addc_u32 s17, s53, 0
	s_waitcnt vmcnt(63)
	v_fmac_f32_e32 v239, v8, v127
	global_store_dword v67, v239, s[16:17] offset:128
	s_add_u32 s16, s52, 0x31000
	s_addc_u32 s17, s53, 0
	s_waitcnt vmcnt(63)
	v_fmac_f32_e32 v240, v25, v126
	global_store_dword v67, v240, s[16:17]
	s_add_u32 s16, s52, 0x31000
	s_addc_u32 s17, s53, 0
	s_waitcnt vmcnt(63)
	v_fmac_f32_e32 v241, v9, v127
	global_store_dword v67, v241, s[16:17] offset:128
	s_add_u32 s16, s52, 0x32000
	s_addc_u32 s17, s53, 0
	s_waitcnt vmcnt(63)
	v_fmac_f32_e32 v242, v26, v126
	global_store_dword v67, v242, s[16:17]
	s_add_u32 s16, s52, 0x32000
	s_addc_u32 s17, s53, 0
	s_waitcnt vmcnt(63)
	v_fmac_f32_e32 v243, v10, v127
	global_store_dword v67, v243, s[16:17] offset:128
	s_add_u32 s16, s52, 0x33000
	s_addc_u32 s17, s53, 0
	s_waitcnt vmcnt(63)
	v_fmac_f32_e32 v244, v27, v126
	global_store_dword v67, v244, s[16:17]
	s_add_u32 s16, s52, 0x33000
	s_addc_u32 s17, s53, 0
	s_waitcnt vmcnt(63)
	v_fmac_f32_e32 v245, v11, v127
	global_store_dword v67, v245, s[16:17] offset:128
	s_add_u32 s16, s52, 0x38000
	s_addc_u32 s17, s53, 0
	s_waitcnt vmcnt(63)
	v_fmac_f32_e32 v246, v28, v126
	global_store_dword v67, v246, s[16:17]
	s_add_u32 s16, s52, 0x38000
	s_addc_u32 s17, s53, 0
	s_waitcnt vmcnt(63)
	v_fmac_f32_e32 v247, v12, v127
	global_store_dword v67, v247, s[16:17] offset:128
	s_add_u32 s16, s52, 0x39000
	s_addc_u32 s17, s53, 0
	s_waitcnt vmcnt(63)
	v_fmac_f32_e32 v248, v29, v126
	global_store_dword v67, v248, s[16:17]
	s_add_u32 s16, s52, 0x39000
	s_addc_u32 s17, s53, 0
	s_waitcnt vmcnt(63)
	v_fmac_f32_e32 v249, v13, v127
	global_store_dword v67, v249, s[16:17] offset:128
	s_add_u32 s16, s52, 0x3a000
	s_addc_u32 s17, s53, 0
	s_waitcnt vmcnt(62)
	v_fmac_f32_e32 v250, v30, v126
	global_store_dword v67, v250, s[16:17]
	s_add_u32 s16, s52, 0x3a000
	s_addc_u32 s17, s53, 0
	s_waitcnt vmcnt(61)
	v_fmac_f32_e32 v251, v14, v127
	global_store_dword v67, v251, s[16:17] offset:128
	s_add_u32 s16, s52, 0x3b000
	s_addc_u32 s17, s53, 0
	s_waitcnt vmcnt(60)
	v_fmac_f32_e32 v252, v31, v126
	global_store_dword v67, v252, s[16:17]
	s_add_u32 s16, s52, 0x3b000
	s_addc_u32 s17, s53, 0
	s_waitcnt vmcnt(59)
	v_fmac_f32_e32 v253, v15, v127
	global_store_dword v67, v253, s[16:17] offset:128
	v_readlane_b32 s52, v219, 5
	v_readlane_b32 s53, v219, 6
	v_readlane_b32 s54, v219, 7
	v_readlane_b32 s55, v219, 8
	v_readlane_b32 s56, v219, 9
	v_readlane_b32 s57, v219, 10
	v_readlane_b32 s58, v219, 11
	v_readlane_b32 s59, v219, 12
	v_readlane_b32 s60, v219, 13
	v_readlane_b32 s61, v219, 14
	v_readlane_b32 s62, v219, 15
	v_readlane_b32 s63, v219, 16
	v_readlane_b32 s4, v221, 21
	s_add_i32 s44, s44, s4
	s_add_i32 s28, s28, s29
	s_cmpk_gt_i32 s44, 0x17f
	s_cbranch_scc1 .LBB0_698
	s_branch .LBB0_363

; DEVI unsigned cvtpk(float lo, float hi) { unsigned r; asm volatile("v_cvt_pk_bf16_f32 %0, %1, %2" : "=v"(r) : "v"(lo), "v"(hi)); return r; }
; DEVI float siluf_(float x) { return x / (1.f + __expf(-x)); }
; DEVI void prepMLA_tile(const Params& p, int l, int g, int tile, char* lds) {
;     ...
; #pragma unroll
;   for (int i = 0; i < 6; ++i) {
;     int it = tid + i * 512; int tok = it / 48, ch = it % 48;
;     h16x8 z = *(const h16x8*)(Z + (size_t)tok * NBC + 352 + ch * 8);
;     u32x4 w; w.x = cvtpk(siluf_((float)z[0]), siluf_((float)z[1])); w.y = cvtpk(siluf_((float)z[2]), siluf_((float)z[3]));
;     w.z = cvtpk(siluf_((float)z[4]), siluf_((float)z[5])); w.w = cvtpk(siluf_((float)z[6]), siluf_((float)z[7]));
;     *(u32x4*)(Yb + (size_t)(t0 + tok) * 384 + ch * 8) = w;
;   }
.LBB0_779:
	s_cmpk_gt_i32 s12, 0x2ff
	s_cbranch_scc1 .LBB0_798
	s_lshl_b32 s0, s12, 6
	s_add_i32 s17, s0, s13
	s_mul_i32 s1, s12, 0x2f000
	s_mul_hi_i32 s38, s0, 0xbc0
	s_add_u32 s0, s14, s1
	s_waitcnt vmcnt(19)
	v_mov_b32_e32 v55, v131
	s_addc_u32 s1, s15, s38
	s_mov_b32 s38, 0x2aaaaaab
	v_mov_b64_e32 v[4:5], s[0:1]
	v_mul_hi_i32 v0, v55, s38
	v_lshrrev_b32_e32 v1, 31, v0
	v_ashrrev_i32_e32 v0, 3, v0
	v_add_u32_e32 v6, v0, v1
	v_mul_lo_u32 v0, v6, 48
	v_sub_u32_e32 v2, v55, v0
	v_lshlrev_b32_e32 v2, 3, v2
	v_ashrrev_i32_e32 v3, 31, v2
	v_mad_i64_i32 v[0:1], s[0:1], v6, s23, v[4:5]
	v_lshlrev_b64 v[8:9], 1, v[2:3]
	v_lshl_add_u64 v[0:1], v[0:1], 0, v[8:9]
	global_load_dwordx4 v[0:3], v[0:1], off offset:704
	v_and_b32_e32 v54, 63, v55
	v_ashrrev_i32_e32 v52, 6, v55
	v_lshlrev_b32_e32 v128, 2, v54
	s_waitcnt vmcnt(0)
	v_cvt_f32_f16_e32 v7, v0
	v_cvt_f32_f16_sdwa v0, v0 dst_sel:DWORD dst_unused:UNUSED_PAD src0_sel:WORD_1
	v_mul_f32_e32 v10, 0xbfb8aa3b, v7
	v_exp_f32_e32 v10, v10
	s_nop 0
	v_add_f32_e32 v10, 1.0, v10
	v_div_scale_f32 v11, s[0:1], v10, v10, v7
	v_rcp_f32_e32 v12, v11
	s_nop 0
	v_fma_f32 v13, -v11, v12, 1.0
	v_fmac_f32_e32 v12, v13, v12
	v_div_scale_f32 v13, vcc, v7, v10, v7
	v_mul_f32_e32 v14, v13, v12
	v_fma_f32 v15, -v11, v14, v13
	v_fmac_f32_e32 v14, v15, v12
	v_fma_f32 v11, -v11, v14, v13
	v_div_fmas_f32 v11, v11, v12, v14
	v_div_fixup_f32 v7, v11, v10, v7
	v_mul_f32_e32 v10, 0xbfb8aa3b, v0
	v_exp_f32_e32 v10, v10
	s_nop 0
	v_add_f32_e32 v10, 1.0, v10
	v_div_scale_f32 v11, s[0:1], v10, v10, v0
	v_rcp_f32_e32 v12, v11
	s_nop 0
	v_fma_f32 v13, -v11, v12, 1.0
	v_fmac_f32_e32 v12, v13, v12
	v_div_scale_f32 v13, vcc, v0, v10, v0
	v_mul_f32_e32 v14, v13, v12
	v_fma_f32 v15, -v11, v14, v13
	v_fmac_f32_e32 v14, v15, v12
	v_fma_f32 v11, -v11, v14, v13
	v_div_fmas_f32 v11, v11, v12, v14
	v_div_fixup_f32 v0, v11, v10, v0
	v_cvt_pk_bf16_f32 v0, v7, v0
	v_cvt_f32_f16_e32 v7, v1
	v_cvt_f32_f16_sdwa v1, v1 dst_sel:DWORD dst_unused:UNUSED_PAD src0_sel:WORD_1
	v_mul_f32_e32 v10, 0xbfb8aa3b, v7
	v_exp_f32_e32 v10, v10
	s_nop 0
	v_add_f32_e32 v10, 1.0, v10
	v_div_scale_f32 v11, s[0:1], v10, v10, v7
	v_rcp_f32_e32 v12, v11
	s_nop 0
	v_fma_f32 v13, -v11, v12, 1.0
	v_fmac_f32_e32 v12, v13, v12
	v_div_scale_f32 v13, vcc, v7, v10, v7
	v_mul_f32_e32 v14, v13, v12
	v_fma_f32 v15, -v11, v14, v13
	v_fmac_f32_e32 v14, v15, v12
	v_fma_f32 v11, -v11, v14, v13
	v_div_fmas_f32 v11, v11, v12, v14
	v_div_fixup_f32 v7, v11, v10, v7
	v_mul_f32_e32 v10, 0xbfb8aa3b, v1
	v_exp_f32_e32 v10, v10
	s_nop 0
	v_add_f32_e32 v10, 1.0, v10
	v_div_scale_f32 v11, s[0:1], v10, v10, v1
	v_rcp_f32_e32 v12, v11
	s_nop 0
	v_fma_f32 v13, -v11, v12, 1.0
	v_fmac_f32_e32 v12, v13, v12
	v_div_scale_f32 v13, vcc, v1, v10, v1
	v_mul_f32_e32 v14, v13, v12
	v_fma_f32 v15, -v11, v14, v13
	v_fmac_f32_e32 v14, v15, v12
	v_fma_f32 v11, -v11, v14, v13
	v_div_fmas_f32 v11, v11, v12, v14
	v_div_fixup_f32 v1, v11, v10, v1
	v_cvt_pk_bf16_f32 v1, v7, v1
	v_cvt_f32_f16_e32 v7, v2
	v_cvt_f32_f16_sdwa v2, v2 dst_sel:DWORD dst_unused:UNUSED_PAD src0_sel:WORD_1
	v_mul_f32_e32 v10, 0xbfb8aa3b, v7
	v_exp_f32_e32 v10, v10
	s_nop 0
	v_add_f32_e32 v10, 1.0, v10
	v_div_scale_f32 v11, s[0:1], v10, v10, v7
	v_rcp_f32_e32 v12, v11
	s_nop 0
	v_fma_f32 v13, -v11, v12, 1.0
	v_fmac_f32_e32 v12, v13, v12
	v_div_scale_f32 v13, vcc, v7, v10, v7
	v_mul_f32_e32 v14, v13, v12
	v_fma_f32 v15, -v11, v14, v13
	v_fmac_f32_e32 v14, v15, v12
	v_fma_f32 v11, -v11, v14, v13
	v_div_fmas_f32 v11, v11, v12, v14
	v_div_fixup_f32 v7, v11, v10, v7
	v_mul_f32_e32 v10, 0xbfb8aa3b, v2
	v_exp_f32_e32 v10, v10
	s_nop 0
	v_add_f32_e32 v10, 1.0, v10
	v_div_scale_f32 v11, s[0:1], v10, v10, v2
	v_rcp_f32_e32 v12, v11
	s_nop 0
	v_fma_f32 v13, -v11, v12, 1.0
	v_fmac_f32_e32 v12, v13, v12
	v_div_scale_f32 v13, vcc, v2, v10, v2
	v_mul_f32_e32 v14, v13, v12
	v_fma_f32 v15, -v11, v14, v13
	v_fmac_f32_e32 v14, v15, v12
	v_fma_f32 v11, -v11, v14, v13
	v_div_fmas_f32 v11, v11, v12, v14
	v_div_fixup_f32 v2, v11, v10, v2
	v_cvt_pk_bf16_f32 v2, v7, v2
	v_cvt_f32_f16_e32 v7, v3
	v_cvt_f32_f16_sdwa v3, v3 dst_sel:DWORD dst_unused:UNUSED_PAD src0_sel:WORD_1
	v_mul_f32_e32 v10, 0xbfb8aa3b, v7
	v_exp_f32_e32 v10, v10
	s_nop 0
	v_add_f32_e32 v10, 1.0, v10
	v_div_scale_f32 v11, s[0:1], v10, v10, v7
	v_rcp_f32_e32 v12, v11
	s_nop 0
	v_fma_f32 v13, -v11, v12, 1.0
	v_fmac_f32_e32 v12, v13, v12
	v_div_scale_f32 v13, vcc, v7, v10, v7
	v_mul_f32_e32 v14, v13, v12
	v_fma_f32 v15, -v11, v14, v13
	v_fmac_f32_e32 v14, v15, v12
	v_fma_f32 v11, -v11, v14, v13
	v_div_fmas_f32 v11, v11, v12, v14
	v_div_fixup_f32 v7, v11, v10, v7
	v_mul_f32_e32 v10, 0xbfb8aa3b, v3
	v_exp_f32_e32 v10, v10
	s_nop 0
	v_add_f32_e32 v10, 1.0, v10
	v_div_scale_f32 v11, s[0:1], v10, v10, v3
	v_rcp_f32_e32 v12, v11
	s_nop 0
	v_fma_f32 v13, -v11, v12, 1.0
	v_fmac_f32_e32 v12, v13, v12
	v_div_scale_f32 v13, vcc, v3, v10, v3
	v_mul_f32_e32 v14, v13, v12
	v_fma_f32 v15, -v11, v14, v13
	v_fmac_f32_e32 v14, v15, v12
	v_fma_f32 v11, -v11, v14, v13
	v_div_fmas_f32 v11, v11, v12, v14
	v_div_fixup_f32 v3, v11, v10, v3
	v_cvt_pk_bf16_f32 v3, v7, v3
	v_add_u32_e32 v10, s17, v6
	v_mov_b64_e32 v[6:7], s[6:7]
	v_mad_i64_i32 v[10:11], s[0:1], v10, s35, v[6:7]
	v_lshl_add_u64 v[8:9], v[10:11], 0, v[8:9]
	global_store_dwordx4 v[8:9], v[0:3], off
	s_nop 1
	v_add_u32_e32 v0, 0x200, v55
	v_mul_hi_i32 v1, v0, s38
	v_lshrrev_b32_e32 v2, 31, v1
	v_ashrrev_i32_e32 v1, 3, v1
	v_add_u32_e32 v10, v1, v2
	v_mul_lo_u32 v1, v10, 48
	v_sub_u32_e32 v2, v0, v1
	v_lshlrev_b32_e32 v2, 3, v2
	v_ashrrev_i32_e32 v3, 31, v2
	v_mad_i64_i32 v[0:1], s[0:1], v10, s23, v[4:5]
	v_lshlrev_b64 v[8:9], 1, v[2:3]
	v_lshl_add_u64 v[0:1], v[0:1], 0, v[8:9]
	global_load_dwordx4 v[0:3], v[0:1], off offset:704
	v_add_u32_e32 v10, s17, v10
	s_waitcnt vmcnt(0)
; DEVI unsigned cvtpk(float lo, float hi) { unsigned r; asm volatile("v_cvt_pk_bf16_f32 %0, %1, %2" : "=v"(r) : "v"(lo), "v"(hi)); return r; }
; DEVI float siluf_(float x) { return x / (1.f + __expf(-x)); }
; DEVI void prepMLA_tile(const Params& p, int l, int g, int tile, char* lds) {
;     ...
; #pragma unroll
;   for (int i = 0; i < 6; ++i) {
;     int it = tid + i * 512; int tok = it / 48, ch = it % 48;
;     h16x8 z = *(const h16x8*)(Z + (size_t)tok * NBC + 352 + ch * 8);
;     u32x4 w; w.x = cvtpk(siluf_((float)z[0]), siluf_((float)z[1])); w.y = cvtpk(siluf_((float)z[2]), siluf_((float)z[3]));
;     w.z = cvtpk(siluf_((float)z[4]), siluf_((float)z[5])); w.w = cvtpk(siluf_((float)z[6]), siluf_((float)z[7]));
;     *(u32x4*)(Yb + (size_t)(t0 + tok) * 384 + ch * 8) = w;
;   }
	v_cvt_f32_f16_e32 v11, v0
	v_cvt_f32_f16_sdwa v0, v0 dst_sel:DWORD dst_unused:UNUSED_PAD src0_sel:WORD_1
	v_mul_f32_e32 v12, 0xbfb8aa3b, v11
	v_exp_f32_e32 v12, v12
	s_nop 0
	v_add_f32_e32 v12, 1.0, v12
	v_div_scale_f32 v13, s[0:1], v12, v12, v11
	v_rcp_f32_e32 v14, v13
	s_nop 0
	v_fma_f32 v15, -v13, v14, 1.0
	v_fmac_f32_e32 v14, v15, v14
	v_div_scale_f32 v15, vcc, v11, v12, v11
	v_mul_f32_e32 v16, v15, v14
	v_fma_f32 v17, -v13, v16, v15
	v_fmac_f32_e32 v16, v17, v14
	v_fma_f32 v13, -v13, v16, v15
	v_div_fmas_f32 v13, v13, v14, v16
	v_div_fixup_f32 v11, v13, v12, v11
	v_mul_f32_e32 v12, 0xbfb8aa3b, v0
	v_exp_f32_e32 v12, v12
	s_nop 0
	v_add_f32_e32 v12, 1.0, v12
	v_div_scale_f32 v13, s[0:1], v12, v12, v0
	v_rcp_f32_e32 v14, v13
	s_nop 0
	v_fma_f32 v15, -v13, v14, 1.0
	v_fmac_f32_e32 v14, v15, v14
	v_div_scale_f32 v15, vcc, v0, v12, v0
	v_mul_f32_e32 v16, v15, v14
	v_fma_f32 v17, -v13, v16, v15
	v_fmac_f32_e32 v16, v17, v14
	v_fma_f32 v13, -v13, v16, v15
	v_div_fmas_f32 v13, v13, v14, v16
	v_div_fixup_f32 v0, v13, v12, v0
	v_cvt_pk_bf16_f32 v0, v11, v0
	v_cvt_f32_f16_e32 v11, v1
	v_cvt_f32_f16_sdwa v1, v1 dst_sel:DWORD dst_unused:UNUSED_PAD src0_sel:WORD_1
	v_mul_f32_e32 v12, 0xbfb8aa3b, v11
	v_exp_f32_e32 v12, v12
	s_nop 0
	v_add_f32_e32 v12, 1.0, v12
	v_div_scale_f32 v13, s[0:1], v12, v12, v11
	v_rcp_f32_e32 v14, v13
	s_nop 0
	v_fma_f32 v15, -v13, v14, 1.0
	v_fmac_f32_e32 v14, v15, v14
	v_div_scale_f32 v15, vcc, v11, v12, v11
	v_mul_f32_e32 v16, v15, v14
	v_fma_f32 v17, -v13, v16, v15
	v_fmac_f32_e32 v16, v17, v14
	v_fma_f32 v13, -v13, v16, v15
	v_div_fmas_f32 v13, v13, v14, v16
	v_div_fixup_f32 v11, v13, v12, v11
	v_mul_f32_e32 v12, 0xbfb8aa3b, v1
	v_exp_f32_e32 v12, v12
	s_nop 0
	v_add_f32_e32 v12, 1.0, v12
	v_div_scale_f32 v13, s[0:1], v12, v12, v1
	v_rcp_f32_e32 v14, v13
	s_nop 0
	v_fma_f32 v15, -v13, v14, 1.0
	v_fmac_f32_e32 v14, v15, v14
	v_div_scale_f32 v15, vcc, v1, v12, v1
	v_mul_f32_e32 v16, v15, v14
	v_fma_f32 v17, -v13, v16, v15
	v_fmac_f32_e32 v16, v17, v14
	v_fma_f32 v13, -v13, v16, v15
	v_div_fmas_f32 v13, v13, v14, v16
	v_div_fixup_f32 v1, v13, v12, v1
	v_cvt_pk_bf16_f32 v1, v11, v1
	v_cvt_f32_f16_e32 v11, v2
	v_cvt_f32_f16_sdwa v2, v2 dst_sel:DWORD dst_unused:UNUSED_PAD src0_sel:WORD_1
	v_mul_f32_e32 v12, 0xbfb8aa3b, v11
	v_exp_f32_e32 v12, v12
	s_nop 0
	v_add_f32_e32 v12, 1.0, v12
	v_div_scale_f32 v13, s[0:1], v12, v12, v11
	v_rcp_f32_e32 v14, v13
	s_nop 0
	v_fma_f32 v15, -v13, v14, 1.0
	v_fmac_f32_e32 v14, v15, v14
	v_div_scale_f32 v15, vcc, v11, v12, v11
	v_mul_f32_e32 v16, v15, v14
	v_fma_f32 v17, -v13, v16, v15
	v_fmac_f32_e32 v16, v17, v14
	v_fma_f32 v13, -v13, v16, v15
	v_div_fmas_f32 v13, v13, v14, v16
	v_div_fixup_f32 v11, v13, v12, v11
	v_mul_f32_e32 v12, 0xbfb8aa3b, v2
	v_exp_f32_e32 v12, v12
	s_nop 0
	v_add_f32_e32 v12, 1.0, v12
	v_div_scale_f32 v13, s[0:1], v12, v12, v2
	v_rcp_f32_e32 v14, v13
	s_nop 0
	v_fma_f32 v15, -v13, v14, 1.0
	v_fmac_f32_e32 v14, v15, v14
	v_div_scale_f32 v15, vcc, v2, v12, v2
	v_mul_f32_e32 v16, v15, v14
	v_fma_f32 v17, -v13, v16, v15
	v_fmac_f32_e32 v16, v17, v14
	v_fma_f32 v13, -v13, v16, v15
	v_div_fmas_f32 v13, v13, v14, v16
	v_div_fixup_f32 v2, v13, v12, v2
	v_cvt_pk_bf16_f32 v2, v11, v2
	v_cvt_f32_f16_e32 v11, v3
	v_cvt_f32_f16_sdwa v3, v3 dst_sel:DWORD dst_unused:UNUSED_PAD src0_sel:WORD_1
	v_mul_f32_e32 v12, 0xbfb8aa3b, v11
	v_exp_f32_e32 v12, v12
	s_nop 0
	v_add_f32_e32 v12, 1.0, v12
	v_div_scale_f32 v13, s[0:1], v12, v12, v11
	v_rcp_f32_e32 v14, v13
	s_nop 0
	v_fma_f32 v15, -v13, v14, 1.0
	v_fmac_f32_e32 v14, v15, v14
	v_div_scale_f32 v15, vcc, v11, v12, v11
	v_mul_f32_e32 v16, v15, v14
	v_fma_f32 v17, -v13, v16, v15
	v_fmac_f32_e32 v16, v17, v14
	v_fma_f32 v13, -v13, v16, v15
	v_div_fmas_f32 v13, v13, v14, v16
	v_div_fixup_f32 v11, v13, v12, v11
	v_mul_f32_e32 v12, 0xbfb8aa3b, v3
	v_exp_f32_e32 v12, v12
	s_nop 0
	v_add_f32_e32 v12, 1.0, v12
	v_div_scale_f32 v13, s[0:1], v12, v12, v3
	v_rcp_f32_e32 v14, v13
	s_nop 0
	v_fma_f32 v15, -v13, v14, 1.0
	v_fmac_f32_e32 v14, v15, v14
	v_div_scale_f32 v15, vcc, v3, v12, v3
	v_mul_f32_e32 v16, v15, v14
	v_fma_f32 v17, -v13, v16, v15
	v_fmac_f32_e32 v16, v17, v14
	v_fma_f32 v13, -v13, v16, v15
	v_div_fmas_f32 v13, v13, v14, v16
	v_div_fixup_f32 v3, v13, v12, v3
	v_cvt_pk_bf16_f32 v3, v11, v3
	v_mad_i64_i32 v[10:11], s[0:1], v10, s35, v[6:7]
	v_lshl_add_u64 v[8:9], v[10:11], 0, v[8:9]
	global_store_dwordx4 v[8:9], v[0:3], off
	s_nop 1
	v_add_u32_e32 v0, 0x400, v55
	v_mul_hi_i32 v1, v0, s38
	v_lshrrev_b32_e32 v2, 31, v1
	v_ashrrev_i32_e32 v1, 3, v1
	v_add_u32_e32 v10, v1, v2
	v_mul_lo_u32 v1, v10, 48
	v_sub_u32_e32 v2, v0, v1
	v_lshlrev_b32_e32 v2, 3, v2
	v_ashrrev_i32_e32 v3, 31, v2
	v_mad_i64_i32 v[0:1], s[0:1], v10, s23, v[4:5]
	v_lshlrev_b64 v[8:9], 1, v[2:3]
	v_lshl_add_u64 v[0:1], v[0:1], 0, v[8:9]
	global_load_dwordx4 v[0:3], v[0:1], off offset:704
	v_add_u32_e32 v10, s17, v10
	s_waitcnt vmcnt(0)
; DEVI unsigned cvtpk(float lo, float hi) { unsigned r; asm volatile("v_cvt_pk_bf16_f32 %0, %1, %2" : "=v"(r) : "v"(lo), "v"(hi)); return r; }
; DEVI float siluf_(float x) { return x / (1.f + __expf(-x)); }
; DEVI void prepMLA_tile(const Params& p, int l, int g, int tile, char* lds) {
;     ...
; #pragma unroll
;   for (int i = 0; i < 6; ++i) {
;     int it = tid + i * 512; int tok = it / 48, ch = it % 48;
;     h16x8 z = *(const h16x8*)(Z + (size_t)tok * NBC + 352 + ch * 8);
;     u32x4 w; w.x = cvtpk(siluf_((float)z[0]), siluf_((float)z[1])); w.y = cvtpk(siluf_((float)z[2]), siluf_((float)z[3]));
;     w.z = cvtpk(siluf_((float)z[4]), siluf_((float)z[5])); w.w = cvtpk(siluf_((float)z[6]), siluf_((float)z[7]));
;     *(u32x4*)(Yb + (size_t)(t0 + tok) * 384 + ch * 8) = w;
;   }
	v_cvt_f32_f16_e32 v11, v0
	v_cvt_f32_f16_sdwa v0, v0 dst_sel:DWORD dst_unused:UNUSED_PAD src0_sel:WORD_1
	v_mul_f32_e32 v12, 0xbfb8aa3b, v11
	v_exp_f32_e32 v12, v12
	s_nop 0
	v_add_f32_e32 v12, 1.0, v12
	v_div_scale_f32 v13, s[0:1], v12, v12, v11
	v_rcp_f32_e32 v14, v13
	s_nop 0
	v_fma_f32 v15, -v13, v14, 1.0
	v_fmac_f32_e32 v14, v15, v14
	v_div_scale_f32 v15, vcc, v11, v12, v11
	v_mul_f32_e32 v16, v15, v14
	v_fma_f32 v17, -v13, v16, v15
	v_fmac_f32_e32 v16, v17, v14
	v_fma_f32 v13, -v13, v16, v15
	v_div_fmas_f32 v13, v13, v14, v16
	v_div_fixup_f32 v11, v13, v12, v11
	v_mul_f32_e32 v12, 0xbfb8aa3b, v0
	v_exp_f32_e32 v12, v12
	s_nop 0
	v_add_f32_e32 v12, 1.0, v12
	v_div_scale_f32 v13, s[0:1], v12, v12, v0
	v_rcp_f32_e32 v14, v13
	s_nop 0
	v_fma_f32 v15, -v13, v14, 1.0
	v_fmac_f32_e32 v14, v15, v14
	v_div_scale_f32 v15, vcc, v0, v12, v0
	v_mul_f32_e32 v16, v15, v14
	v_fma_f32 v17, -v13, v16, v15
	v_fmac_f32_e32 v16, v17, v14
	v_fma_f32 v13, -v13, v16, v15
	v_div_fmas_f32 v13, v13, v14, v16
	v_div_fixup_f32 v0, v13, v12, v0
	v_cvt_pk_bf16_f32 v0, v11, v0
	v_cvt_f32_f16_e32 v11, v1
	v_cvt_f32_f16_sdwa v1, v1 dst_sel:DWORD dst_unused:UNUSED_PAD src0_sel:WORD_1
	v_mul_f32_e32 v12, 0xbfb8aa3b, v11
	v_exp_f32_e32 v12, v12
	s_nop 0
	v_add_f32_e32 v12, 1.0, v12
	v_div_scale_f32 v13, s[0:1], v12, v12, v11
	v_rcp_f32_e32 v14, v13
	s_nop 0
	v_fma_f32 v15, -v13, v14, 1.0
	v_fmac_f32_e32 v14, v15, v14
	v_div_scale_f32 v15, vcc, v11, v12, v11
	v_mul_f32_e32 v16, v15, v14
	v_fma_f32 v17, -v13, v16, v15
	v_fmac_f32_e32 v16, v17, v14
	v_fma_f32 v13, -v13, v16, v15
	v_div_fmas_f32 v13, v13, v14, v16
	v_div_fixup_f32 v11, v13, v12, v11
	v_mul_f32_e32 v12, 0xbfb8aa3b, v1
	v_exp_f32_e32 v12, v12
	s_nop 0
	v_add_f32_e32 v12, 1.0, v12
	v_div_scale_f32 v13, s[0:1], v12, v12, v1
	v_rcp_f32_e32 v14, v13
	s_nop 0
	v_fma_f32 v15, -v13, v14, 1.0
	v_fmac_f32_e32 v14, v15, v14
	v_div_scale_f32 v15, vcc, v1, v12, v1
	v_mul_f32_e32 v16, v15, v14
	v_fma_f32 v17, -v13, v16, v15
	v_fmac_f32_e32 v16, v17, v14
	v_fma_f32 v13, -v13, v16, v15
	v_div_fmas_f32 v13, v13, v14, v16
	v_div_fixup_f32 v1, v13, v12, v1
	v_cvt_pk_bf16_f32 v1, v11, v1
	v_cvt_f32_f16_e32 v11, v2
	v_cvt_f32_f16_sdwa v2, v2 dst_sel:DWORD dst_unused:UNUSED_PAD src0_sel:WORD_1
	v_mul_f32_e32 v12, 0xbfb8aa3b, v11
	v_exp_f32_e32 v12, v12
	s_nop 0
	v_add_f32_e32 v12, 1.0, v12
	v_div_scale_f32 v13, s[0:1], v12, v12, v11
	v_rcp_f32_e32 v14, v13
	s_nop 0
	v_fma_f32 v15, -v13, v14, 1.0
	v_fmac_f32_e32 v14, v15, v14
	v_div_scale_f32 v15, vcc, v11, v12, v11
	v_mul_f32_e32 v16, v15, v14
	v_fma_f32 v17, -v13, v16, v15
	v_fmac_f32_e32 v16, v17, v14
	v_fma_f32 v13, -v13, v16, v15
	v_div_fmas_f32 v13, v13, v14, v16
	v_div_fixup_f32 v11, v13, v12, v11
	v_mul_f32_e32 v12, 0xbfb8aa3b, v2
	v_exp_f32_e32 v12, v12
	s_nop 0
	v_add_f32_e32 v12, 1.0, v12
	v_div_scale_f32 v13, s[0:1], v12, v12, v2
	v_rcp_f32_e32 v14, v13
	s_nop 0
	v_fma_f32 v15, -v13, v14, 1.0
	v_fmac_f32_e32 v14, v15, v14
	v_div_scale_f32 v15, vcc, v2, v12, v2
	v_mul_f32_e32 v16, v15, v14
	v_fma_f32 v17, -v13, v16, v15
	v_fmac_f32_e32 v16, v17, v14
	v_fma_f32 v13, -v13, v16, v15
	v_div_fmas_f32 v13, v13, v14, v16
	v_div_fixup_f32 v2, v13, v12, v2
	v_cvt_pk_bf16_f32 v2, v11, v2
	v_cvt_f32_f16_e32 v11, v3
	v_cvt_f32_f16_sdwa v3, v3 dst_sel:DWORD dst_unused:UNUSED_PAD src0_sel:WORD_1
	v_mul_f32_e32 v12, 0xbfb8aa3b, v11
	v_exp_f32_e32 v12, v12
	s_nop 0
	v_add_f32_e32 v12, 1.0, v12
	v_div_scale_f32 v13, s[0:1], v12, v12, v11
	v_rcp_f32_e32 v14, v13
	s_nop 0
	v_fma_f32 v15, -v13, v14, 1.0
	v_fmac_f32_e32 v14, v15, v14
	v_div_scale_f32 v15, vcc, v11, v12, v11
	v_mul_f32_e32 v16, v15, v14
	v_fma_f32 v17, -v13, v16, v15
	v_fmac_f32_e32 v16, v17, v14
	v_fma_f32 v13, -v13, v16, v15
	v_div_fmas_f32 v13, v13, v14, v16
	v_div_fixup_f32 v11, v13, v12, v11
	v_mul_f32_e32 v12, 0xbfb8aa3b, v3
	v_exp_f32_e32 v12, v12
	s_nop 0
	v_add_f32_e32 v12, 1.0, v12
	v_div_scale_f32 v13, s[0:1], v12, v12, v3
	v_rcp_f32_e32 v14, v13
	s_nop 0
	v_fma_f32 v15, -v13, v14, 1.0
	v_fmac_f32_e32 v14, v15, v14
	v_div_scale_f32 v15, vcc, v3, v12, v3
	v_mul_f32_e32 v16, v15, v14
	v_fma_f32 v17, -v13, v16, v15
	v_fmac_f32_e32 v16, v17, v14
	v_fma_f32 v13, -v13, v16, v15
	v_div_fmas_f32 v13, v13, v14, v16
	v_div_fixup_f32 v3, v13, v12, v3
	v_cvt_pk_bf16_f32 v3, v11, v3
	v_mad_i64_i32 v[10:11], s[0:1], v10, s35, v[6:7]
	v_lshl_add_u64 v[8:9], v[10:11], 0, v[8:9]
	global_store_dwordx4 v[8:9], v[0:3], off
	s_nop 1
	v_add_u32_e32 v0, 0x600, v55
	v_mul_hi_i32 v1, v0, s38
	v_lshrrev_b32_e32 v2, 31, v1
	v_ashrrev_i32_e32 v1, 3, v1
	v_add_u32_e32 v10, v1, v2
	v_mul_lo_u32 v1, v10, 48
	v_sub_u32_e32 v2, v0, v1
	v_lshlrev_b32_e32 v2, 3, v2
	v_ashrrev_i32_e32 v3, 31, v2
	v_mad_i64_i32 v[0:1], s[0:1], v10, s23, v[4:5]
	v_lshlrev_b64 v[8:9], 1, v[2:3]
	v_lshl_add_u64 v[0:1], v[0:1], 0, v[8:9]
	global_load_dwordx4 v[0:3], v[0:1], off offset:704
	v_add_u32_e32 v10, s17, v10
	s_waitcnt vmcnt(0)
; DEVI unsigned cvtpk(float lo, float hi) { unsigned r; asm volatile("v_cvt_pk_bf16_f32 %0, %1, %2" : "=v"(r) : "v"(lo), "v"(hi)); return r; }
; DEVI float siluf_(float x) { return x / (1.f + __expf(-x)); }
; DEVI void prepMLA_tile(const Params& p, int l, int g, int tile, char* lds) {
;     ...
; #pragma unroll
;   for (int i = 0; i < 6; ++i) {
;     int it = tid + i * 512; int tok = it / 48, ch = it % 48;
;     h16x8 z = *(const h16x8*)(Z + (size_t)tok * NBC + 352 + ch * 8);
;     u32x4 w; w.x = cvtpk(siluf_((float)z[0]), siluf_((float)z[1])); w.y = cvtpk(siluf_((float)z[2]), siluf_((float)z[3]));
;     w.z = cvtpk(siluf_((float)z[4]), siluf_((float)z[5])); w.w = cvtpk(siluf_((float)z[6]), siluf_((float)z[7]));
;     *(u32x4*)(Yb + (size_t)(t0 + tok) * 384 + ch * 8) = w;
;   }
	v_cvt_f32_f16_e32 v11, v0
	v_cvt_f32_f16_sdwa v0, v0 dst_sel:DWORD dst_unused:UNUSED_PAD src0_sel:WORD_1
	v_mul_f32_e32 v12, 0xbfb8aa3b, v11
	v_exp_f32_e32 v12, v12
	s_nop 0
	v_add_f32_e32 v12, 1.0, v12
	v_div_scale_f32 v13, s[0:1], v12, v12, v11
	v_rcp_f32_e32 v14, v13
	s_nop 0
	v_fma_f32 v15, -v13, v14, 1.0
	v_fmac_f32_e32 v14, v15, v14
	v_div_scale_f32 v15, vcc, v11, v12, v11
	v_mul_f32_e32 v16, v15, v14
	v_fma_f32 v17, -v13, v16, v15
	v_fmac_f32_e32 v16, v17, v14
	v_fma_f32 v13, -v13, v16, v15
	v_div_fmas_f32 v13, v13, v14, v16
	v_div_fixup_f32 v11, v13, v12, v11
	v_mul_f32_e32 v12, 0xbfb8aa3b, v0
	v_exp_f32_e32 v12, v12
	s_nop 0
	v_add_f32_e32 v12, 1.0, v12
	v_div_scale_f32 v13, s[0:1], v12, v12, v0
	v_rcp_f32_e32 v14, v13
	s_nop 0
	v_fma_f32 v15, -v13, v14, 1.0
	v_fmac_f32_e32 v14, v15, v14
	v_div_scale_f32 v15, vcc, v0, v12, v0
	v_mul_f32_e32 v16, v15, v14
	v_fma_f32 v17, -v13, v16, v15
	v_fmac_f32_e32 v16, v17, v14
	v_fma_f32 v13, -v13, v16, v15
	v_div_fmas_f32 v13, v13, v14, v16
	v_div_fixup_f32 v0, v13, v12, v0
	v_cvt_pk_bf16_f32 v0, v11, v0
	v_cvt_f32_f16_e32 v11, v1
	v_cvt_f32_f16_sdwa v1, v1 dst_sel:DWORD dst_unused:UNUSED_PAD src0_sel:WORD_1
	v_mul_f32_e32 v12, 0xbfb8aa3b, v11
	v_exp_f32_e32 v12, v12
	s_nop 0
	v_add_f32_e32 v12, 1.0, v12
	v_div_scale_f32 v13, s[0:1], v12, v12, v11
	v_rcp_f32_e32 v14, v13
	s_nop 0
	v_fma_f32 v15, -v13, v14, 1.0
	v_fmac_f32_e32 v14, v15, v14
	v_div_scale_f32 v15, vcc, v11, v12, v11
	v_mul_f32_e32 v16, v15, v14
	v_fma_f32 v17, -v13, v16, v15
	v_fmac_f32_e32 v16, v17, v14
	v_fma_f32 v13, -v13, v16, v15
	v_div_fmas_f32 v13, v13, v14, v16
	v_div_fixup_f32 v11, v13, v12, v11
	v_mul_f32_e32 v12, 0xbfb8aa3b, v1
	v_exp_f32_e32 v12, v12
	s_nop 0
	v_add_f32_e32 v12, 1.0, v12
	v_div_scale_f32 v13, s[0:1], v12, v12, v1
	v_rcp_f32_e32 v14, v13
	s_nop 0
	v_fma_f32 v15, -v13, v14, 1.0
	v_fmac_f32_e32 v14, v15, v14
	v_div_scale_f32 v15, vcc, v1, v12, v1
	v_mul_f32_e32 v16, v15, v14
	v_fma_f32 v17, -v13, v16, v15
	v_fmac_f32_e32 v16, v17, v14
	v_fma_f32 v13, -v13, v16, v15
	v_div_fmas_f32 v13, v13, v14, v16
	v_div_fixup_f32 v1, v13, v12, v1
	v_cvt_pk_bf16_f32 v1, v11, v1
	v_cvt_f32_f16_e32 v11, v2
	v_cvt_f32_f16_sdwa v2, v2 dst_sel:DWORD dst_unused:UNUSED_PAD src0_sel:WORD_1
	v_mul_f32_e32 v12, 0xbfb8aa3b, v11
	v_exp_f32_e32 v12, v12
	s_nop 0
	v_add_f32_e32 v12, 1.0, v12
	v_div_scale_f32 v13, s[0:1], v12, v12, v11
	v_rcp_f32_e32 v14, v13
	s_nop 0
	v_fma_f32 v15, -v13, v14, 1.0
	v_fmac_f32_e32 v14, v15, v14
	v_div_scale_f32 v15, vcc, v11, v12, v11
	v_mul_f32_e32 v16, v15, v14
	v_fma_f32 v17, -v13, v16, v15
	v_fmac_f32_e32 v16, v17, v14
	v_fma_f32 v13, -v13, v16, v15
	v_div_fmas_f32 v13, v13, v14, v16
	v_div_fixup_f32 v11, v13, v12, v11
	v_mul_f32_e32 v12, 0xbfb8aa3b, v2
	v_exp_f32_e32 v12, v12
	s_nop 0
	v_add_f32_e32 v12, 1.0, v12
	v_div_scale_f32 v13, s[0:1], v12, v12, v2
	v_rcp_f32_e32 v14, v13
	s_nop 0
	v_fma_f32 v15, -v13, v14, 1.0
	v_fmac_f32_e32 v14, v15, v14
	v_div_scale_f32 v15, vcc, v2, v12, v2
	v_mul_f32_e32 v16, v15, v14
	v_fma_f32 v17, -v13, v16, v15
	v_fmac_f32_e32 v16, v17, v14
	v_fma_f32 v13, -v13, v16, v15
	v_div_fmas_f32 v13, v13, v14, v16
	v_div_fixup_f32 v2, v13, v12, v2
	v_cvt_pk_bf16_f32 v2, v11, v2
	v_cvt_f32_f16_e32 v11, v3
	v_cvt_f32_f16_sdwa v3, v3 dst_sel:DWORD dst_unused:UNUSED_PAD src0_sel:WORD_1
	v_mul_f32_e32 v12, 0xbfb8aa3b, v11
	v_exp_f32_e32 v12, v12
	s_nop 0
	v_add_f32_e32 v12, 1.0, v12
	v_div_scale_f32 v13, s[0:1], v12, v12, v11
	v_rcp_f32_e32 v14, v13
	s_nop 0
	v_fma_f32 v15, -v13, v14, 1.0
	v_fmac_f32_e32 v14, v15, v14
	v_div_scale_f32 v15, vcc, v11, v12, v11
	v_mul_f32_e32 v16, v15, v14
	v_fma_f32 v17, -v13, v16, v15
	v_fmac_f32_e32 v16, v17, v14
	v_fma_f32 v13, -v13, v16, v15
	v_div_fmas_f32 v13, v13, v14, v16
	v_div_fixup_f32 v11, v13, v12, v11
	v_mul_f32_e32 v12, 0xbfb8aa3b, v3
	v_exp_f32_e32 v12, v12
	s_nop 0
	v_add_f32_e32 v12, 1.0, v12
	v_div_scale_f32 v13, s[0:1], v12, v12, v3
	v_rcp_f32_e32 v14, v13
	s_nop 0
	v_fma_f32 v15, -v13, v14, 1.0
	v_fmac_f32_e32 v14, v15, v14
	v_div_scale_f32 v15, vcc, v3, v12, v3
	v_mul_f32_e32 v16, v15, v14
	v_fma_f32 v17, -v13, v16, v15
	v_fmac_f32_e32 v16, v17, v14
	v_fma_f32 v13, -v13, v16, v15
	v_div_fmas_f32 v13, v13, v14, v16
	v_div_fixup_f32 v3, v13, v12, v3
	v_cvt_pk_bf16_f32 v3, v11, v3
	v_mad_i64_i32 v[10:11], s[0:1], v10, s35, v[6:7]
	v_lshl_add_u64 v[8:9], v[10:11], 0, v[8:9]
	global_store_dwordx4 v[8:9], v[0:3], off
	s_nop 1
	v_add_u32_e32 v0, 0x800, v55
	v_mul_hi_i32 v1, v0, s38
	v_lshrrev_b32_e32 v2, 31, v1
	v_ashrrev_i32_e32 v1, 3, v1
	v_add_u32_e32 v10, v1, v2
	v_mul_lo_u32 v1, v10, 48
	v_sub_u32_e32 v2, v0, v1
	v_lshlrev_b32_e32 v2, 3, v2
	v_ashrrev_i32_e32 v3, 31, v2
	v_mad_i64_i32 v[0:1], s[0:1], v10, s23, v[4:5]
	v_lshlrev_b64 v[8:9], 1, v[2:3]
	v_lshl_add_u64 v[0:1], v[0:1], 0, v[8:9]
	global_load_dwordx4 v[0:3], v[0:1], off offset:704
	v_add_u32_e32 v10, s17, v10
	s_waitcnt vmcnt(0)
; DEVI unsigned cvtpk(float lo, float hi) { unsigned r; asm volatile("v_cvt_pk_bf16_f32 %0, %1, %2" : "=v"(r) : "v"(lo), "v"(hi)); return r; }
; DEVI float siluf_(float x) { return x / (1.f + __expf(-x)); }
; DEVI void prepMLA_tile(const Params& p, int l, int g, int tile, char* lds) {
;     ...
; #pragma unroll
;   for (int i = 0; i < 6; ++i) {
;     int it = tid + i * 512; int tok = it / 48, ch = it % 48;
;     h16x8 z = *(const h16x8*)(Z + (size_t)tok * NBC + 352 + ch * 8);
;     u32x4 w; w.x = cvtpk(siluf_((float)z[0]), siluf_((float)z[1])); w.y = cvtpk(siluf_((float)z[2]), siluf_((float)z[3]));
;     w.z = cvtpk(siluf_((float)z[4]), siluf_((float)z[5])); w.w = cvtpk(siluf_((float)z[6]), siluf_((float)z[7]));
;     *(u32x4*)(Yb + (size_t)(t0 + tok) * 384 + ch * 8) = w;
;   }
	v_cvt_f32_f16_e32 v11, v0
	v_cvt_f32_f16_sdwa v0, v0 dst_sel:DWORD dst_unused:UNUSED_PAD src0_sel:WORD_1
	v_mul_f32_e32 v12, 0xbfb8aa3b, v11
	v_exp_f32_e32 v12, v12
	s_nop 0
	v_add_f32_e32 v12, 1.0, v12
	v_div_scale_f32 v13, s[0:1], v12, v12, v11
	v_rcp_f32_e32 v14, v13
	s_nop 0
	v_fma_f32 v15, -v13, v14, 1.0
	v_fmac_f32_e32 v14, v15, v14
	v_div_scale_f32 v15, vcc, v11, v12, v11
	v_mul_f32_e32 v16, v15, v14
	v_fma_f32 v17, -v13, v16, v15
	v_fmac_f32_e32 v16, v17, v14
	v_fma_f32 v13, -v13, v16, v15
	v_div_fmas_f32 v13, v13, v14, v16
	v_div_fixup_f32 v11, v13, v12, v11
	v_mul_f32_e32 v12, 0xbfb8aa3b, v0
	v_exp_f32_e32 v12, v12
	s_nop 0
	v_add_f32_e32 v12, 1.0, v12
	v_div_scale_f32 v13, s[0:1], v12, v12, v0
	v_rcp_f32_e32 v14, v13
	s_nop 0
	v_fma_f32 v15, -v13, v14, 1.0
	v_fmac_f32_e32 v14, v15, v14
	v_div_scale_f32 v15, vcc, v0, v12, v0
	v_mul_f32_e32 v16, v15, v14
	v_fma_f32 v17, -v13, v16, v15
	v_fmac_f32_e32 v16, v17, v14
	v_fma_f32 v13, -v13, v16, v15
	v_div_fmas_f32 v13, v13, v14, v16
	v_div_fixup_f32 v0, v13, v12, v0
	v_cvt_pk_bf16_f32 v0, v11, v0
	v_cvt_f32_f16_e32 v11, v1
	v_cvt_f32_f16_sdwa v1, v1 dst_sel:DWORD dst_unused:UNUSED_PAD src0_sel:WORD_1
	v_mul_f32_e32 v12, 0xbfb8aa3b, v11
	v_exp_f32_e32 v12, v12
	s_nop 0
	v_add_f32_e32 v12, 1.0, v12
	v_div_scale_f32 v13, s[0:1], v12, v12, v11
	v_rcp_f32_e32 v14, v13
	s_nop 0
	v_fma_f32 v15, -v13, v14, 1.0
	v_fmac_f32_e32 v14, v15, v14
	v_div_scale_f32 v15, vcc, v11, v12, v11
	v_mul_f32_e32 v16, v15, v14
	v_fma_f32 v17, -v13, v16, v15
	v_fmac_f32_e32 v16, v17, v14
	v_fma_f32 v13, -v13, v16, v15
	v_div_fmas_f32 v13, v13, v14, v16
	v_div_fixup_f32 v11, v13, v12, v11
	v_mul_f32_e32 v12, 0xbfb8aa3b, v1
	v_exp_f32_e32 v12, v12
	s_nop 0
	v_add_f32_e32 v12, 1.0, v12
	v_div_scale_f32 v13, s[0:1], v12, v12, v1
	v_rcp_f32_e32 v14, v13
	s_nop 0
	v_fma_f32 v15, -v13, v14, 1.0
	v_fmac_f32_e32 v14, v15, v14
	v_div_scale_f32 v15, vcc, v1, v12, v1
	v_mul_f32_e32 v16, v15, v14
	v_fma_f32 v17, -v13, v16, v15
	v_fmac_f32_e32 v16, v17, v14
	v_fma_f32 v13, -v13, v16, v15
	v_div_fmas_f32 v13, v13, v14, v16
	v_div_fixup_f32 v1, v13, v12, v1
	v_cvt_pk_bf16_f32 v1, v11, v1
	v_cvt_f32_f16_e32 v11, v2
	v_cvt_f32_f16_sdwa v2, v2 dst_sel:DWORD dst_unused:UNUSED_PAD src0_sel:WORD_1
	v_mul_f32_e32 v12, 0xbfb8aa3b, v11
	v_exp_f32_e32 v12, v12
	s_nop 0
	v_add_f32_e32 v12, 1.0, v12
	v_div_scale_f32 v13, s[0:1], v12, v12, v11
	v_rcp_f32_e32 v14, v13
	s_nop 0
	v_fma_f32 v15, -v13, v14, 1.0
	v_fmac_f32_e32 v14, v15, v14
	v_div_scale_f32 v15, vcc, v11, v12, v11
	v_mul_f32_e32 v16, v15, v14
	v_fma_f32 v17, -v13, v16, v15
	v_fmac_f32_e32 v16, v17, v14
	v_fma_f32 v13, -v13, v16, v15
	v_div_fmas_f32 v13, v13, v14, v16
	v_div_fixup_f32 v11, v13, v12, v11
	v_mul_f32_e32 v12, 0xbfb8aa3b, v2
	v_exp_f32_e32 v12, v12
	s_nop 0
	v_add_f32_e32 v12, 1.0, v12
	v_div_scale_f32 v13, s[0:1], v12, v12, v2
	v_rcp_f32_e32 v14, v13
	s_nop 0
	v_fma_f32 v15, -v13, v14, 1.0
	v_fmac_f32_e32 v14, v15, v14
	v_div_scale_f32 v15, vcc, v2, v12, v2
	v_mul_f32_e32 v16, v15, v14
	v_fma_f32 v17, -v13, v16, v15
	v_fmac_f32_e32 v16, v17, v14
	v_fma_f32 v13, -v13, v16, v15
	v_div_fmas_f32 v13, v13, v14, v16
	v_div_fixup_f32 v2, v13, v12, v2
	v_cvt_pk_bf16_f32 v2, v11, v2
	v_cvt_f32_f16_e32 v11, v3
	v_cvt_f32_f16_sdwa v3, v3 dst_sel:DWORD dst_unused:UNUSED_PAD src0_sel:WORD_1
	v_mul_f32_e32 v12, 0xbfb8aa3b, v11
	v_exp_f32_e32 v12, v12
	s_nop 0
	v_add_f32_e32 v12, 1.0, v12
	v_div_scale_f32 v13, s[0:1], v12, v12, v11
	v_rcp_f32_e32 v14, v13
	s_nop 0
	v_fma_f32 v15, -v13, v14, 1.0
	v_fmac_f32_e32 v14, v15, v14
	v_div_scale_f32 v15, vcc, v11, v12, v11
	v_mul_f32_e32 v16, v15, v14
	v_fma_f32 v17, -v13, v16, v15
	v_fmac_f32_e32 v16, v17, v14
	v_fma_f32 v13, -v13, v16, v15
	v_div_fmas_f32 v13, v13, v14, v16
	v_div_fixup_f32 v11, v13, v12, v11
	v_mul_f32_e32 v12, 0xbfb8aa3b, v3
	v_exp_f32_e32 v12, v12
	s_nop 0
	v_add_f32_e32 v12, 1.0, v12
	v_div_scale_f32 v13, s[0:1], v12, v12, v3
	v_rcp_f32_e32 v14, v13
	s_nop 0
	v_fma_f32 v15, -v13, v14, 1.0
	v_fmac_f32_e32 v14, v15, v14
	v_div_scale_f32 v15, vcc, v3, v12, v3
	v_mul_f32_e32 v16, v15, v14
	v_fma_f32 v17, -v13, v16, v15
	v_fmac_f32_e32 v16, v17, v14
	v_fma_f32 v13, -v13, v16, v15
	v_div_fmas_f32 v13, v13, v14, v16
	v_div_fixup_f32 v3, v13, v12, v3
	v_cvt_pk_bf16_f32 v3, v11, v3
	v_mad_i64_i32 v[10:11], s[0:1], v10, s35, v[6:7]
	v_lshl_add_u64 v[8:9], v[10:11], 0, v[8:9]
	global_store_dwordx4 v[8:9], v[0:3], off
	s_nop 1
	v_add_u32_e32 v0, 0xa00, v55
	v_mul_hi_i32 v1, v0, s38
	v_lshrrev_b32_e32 v2, 31, v1
	v_ashrrev_i32_e32 v1, 3, v1
	v_add_u32_e32 v8, v1, v2
	v_mul_lo_u32 v1, v8, 48
	v_sub_u32_e32 v2, v0, v1
	v_lshlrev_b32_e32 v2, 3, v2
	v_ashrrev_i32_e32 v3, 31, v2
	v_mad_i64_i32 v[0:1], s[0:1], v8, s23, v[4:5]
	v_lshlrev_b64 v[4:5], 1, v[2:3]
	v_lshl_add_u64 v[0:1], v[0:1], 0, v[4:5]
	global_load_dwordx4 v[0:3], v[0:1], off offset:704
	v_add_u32_e32 v8, s17, v8
	v_mad_i64_i32 v[6:7], s[0:1], v8, s35, v[6:7]
	v_lshl_add_u64 v[4:5], v[6:7], 0, v[4:5]
	s_mov_b32 s38, 0
	s_waitcnt vmcnt(0)
; DEVI unsigned cvtpk(float lo, float hi) { unsigned r; asm volatile("v_cvt_pk_bf16_f32 %0, %1, %2" : "=v"(r) : "v"(lo), "v"(hi)); return r; }
; DEVI u16 f2bf(float f) { return (u16)(cvtpk(f, 0.f) & 0xffffu); }
; DEVI float siluf_(float x) { return x / (1.f + __expf(-x)); }
; DEVI void prepMLA_tile(const Params& p, int l, int g, int tile, char* lds) {
;     ...
; #pragma unroll
;   for (int i = 0; i < 6; ++i) {
;     int it = tid + i * 512; int tok = it / 48, ch = it % 48;
;     h16x8 z = *(const h16x8*)(Z + (size_t)tok * NBC + 352 + ch * 8);
;     u32x4 w; w.x = cvtpk(siluf_((float)z[0]), siluf_((float)z[1])); w.y = cvtpk(siluf_((float)z[2]), siluf_((float)z[3]));
;     w.z = cvtpk(siluf_((float)z[4]), siluf_((float)z[5])); w.w = cvtpk(siluf_((float)z[6]), siluf_((float)z[7]));
;     *(u32x4*)(Yb + (size_t)(t0 + tok) * 384 + ch * 8) = w;
;   }
;     ...
;     const float* qnw = p.q_norm_w + l * 192; const float* kvnw = p.kv_norm_w + l * 128;
; #pragma unroll 1
;     for (int i = 0; i < 8; ++i) {
;       int tok = wid * 8 + i; const h16* zr = Z + (size_t)tok * NBC;
;       float e0 = (float)zr[lane], e1 = (float)zr[64 + lane], e2 = (float)zr[128 + lane];
;       float f0 = (float)zr[192 + lane], f1 = (float)zr[256 + lane];
;       float sq = wave_sum(e0 * e0 + e1 * e1 + e2 * e2), sk = wave_sum(f0 * f0 + f1 * f1);
;       float rq = rsqrtf(sq * (1.f / 192.f) + 1e-6f), rk = rsqrtf(sk * (1.f / 128.f) + 1e-6f);
;       u16* aq = (u16*)(Aq + tok * RSQ); u16* ak = (u16*)(Akv + tok * RSKV);
;       aq[lane] = f2bf(e0 * rq * qnw[lane]); aq[64 + lane] = f2bf(e1 * rq * qnw[64 + lane]); aq[128 + lane] = f2bf(e2 * rq * qnw[128 + lane]);
;       ak[lane] = f2bf(f0 * rk * kvnw[lane]); ak[64 + lane] = f2bf(f1 * rk * kvnw[64 + lane]);
;       if (lane < 32) kro[tok * 32 + lane] = (float)zr[320 + lane];
	v_cvt_f32_f16_e32 v9, v0
	v_cvt_f32_f16_sdwa v0, v0 dst_sel:DWORD dst_unused:UNUSED_PAD src0_sel:WORD_1
	v_mul_f32_e32 v10, 0xbfb8aa3b, v9
	v_exp_f32_e32 v10, v10
	s_nop 0
	v_add_f32_e32 v10, 1.0, v10
	v_div_scale_f32 v11, s[0:1], v10, v10, v9
	v_rcp_f32_e32 v12, v11
	s_nop 0
	v_fma_f32 v13, -v11, v12, 1.0
	v_fmac_f32_e32 v12, v13, v12
	v_div_scale_f32 v13, vcc, v9, v10, v9
	v_mul_f32_e32 v14, v13, v12
	v_fma_f32 v15, -v11, v14, v13
	v_fmac_f32_e32 v14, v15, v12
	v_fma_f32 v11, -v11, v14, v13
	v_div_fmas_f32 v11, v11, v12, v14
	v_div_fixup_f32 v9, v11, v10, v9
	v_mul_f32_e32 v10, 0xbfb8aa3b, v0
	v_exp_f32_e32 v10, v10
	s_nop 0
	v_add_f32_e32 v10, 1.0, v10
	v_div_scale_f32 v11, s[0:1], v10, v10, v0
	v_rcp_f32_e32 v12, v11
	s_nop 0
	v_fma_f32 v13, -v11, v12, 1.0
	v_fmac_f32_e32 v12, v13, v12
	v_div_scale_f32 v13, vcc, v0, v10, v0
	v_mul_f32_e32 v14, v13, v12
	v_fma_f32 v15, -v11, v14, v13
	v_fmac_f32_e32 v14, v15, v12
	v_fma_f32 v11, -v11, v14, v13
	v_div_fmas_f32 v11, v11, v12, v14
	v_div_fixup_f32 v0, v11, v10, v0
	v_cvt_pk_bf16_f32 v0, v9, v0
	v_cvt_f32_f16_e32 v9, v1
	v_cvt_f32_f16_sdwa v1, v1 dst_sel:DWORD dst_unused:UNUSED_PAD src0_sel:WORD_1
	v_mul_f32_e32 v10, 0xbfb8aa3b, v9
	v_exp_f32_e32 v10, v10
	s_nop 0
	v_add_f32_e32 v10, 1.0, v10
	v_div_scale_f32 v11, s[0:1], v10, v10, v9
	v_rcp_f32_e32 v12, v11
	s_nop 0
	v_fma_f32 v13, -v11, v12, 1.0
	v_fmac_f32_e32 v12, v13, v12
	v_div_scale_f32 v13, vcc, v9, v10, v9
	v_mul_f32_e32 v14, v13, v12
	v_fma_f32 v15, -v11, v14, v13
	v_fmac_f32_e32 v14, v15, v12
	v_fma_f32 v11, -v11, v14, v13
	v_div_fmas_f32 v11, v11, v12, v14
	v_div_fixup_f32 v9, v11, v10, v9
	v_mul_f32_e32 v10, 0xbfb8aa3b, v1
	v_exp_f32_e32 v10, v10
	s_nop 0
	v_add_f32_e32 v10, 1.0, v10
	v_div_scale_f32 v11, s[0:1], v10, v10, v1
	v_rcp_f32_e32 v12, v11
	s_nop 0
	v_fma_f32 v13, -v11, v12, 1.0
	v_fmac_f32_e32 v12, v13, v12
	v_div_scale_f32 v13, vcc, v1, v10, v1
	v_mul_f32_e32 v14, v13, v12
	v_fma_f32 v15, -v11, v14, v13
	v_fmac_f32_e32 v14, v15, v12
	v_fma_f32 v11, -v11, v14, v13
	v_div_fmas_f32 v11, v11, v12, v14
	v_div_fixup_f32 v1, v11, v10, v1
	v_cvt_pk_bf16_f32 v1, v9, v1
	v_cvt_f32_f16_e32 v9, v2
	v_cvt_f32_f16_sdwa v2, v2 dst_sel:DWORD dst_unused:UNUSED_PAD src0_sel:WORD_1
	v_mul_f32_e32 v10, 0xbfb8aa3b, v9
	v_exp_f32_e32 v10, v10
	s_nop 0
	v_add_f32_e32 v10, 1.0, v10
	v_div_scale_f32 v11, s[0:1], v10, v10, v9
	v_rcp_f32_e32 v12, v11
	s_nop 0
	v_fma_f32 v13, -v11, v12, 1.0
	v_fmac_f32_e32 v12, v13, v12
	v_div_scale_f32 v13, vcc, v9, v10, v9
	v_mul_f32_e32 v14, v13, v12
	v_fma_f32 v15, -v11, v14, v13
	v_fmac_f32_e32 v14, v15, v12
	v_fma_f32 v11, -v11, v14, v13
	v_div_fmas_f32 v11, v11, v12, v14
	v_div_fixup_f32 v9, v11, v10, v9
	v_mul_f32_e32 v10, 0xbfb8aa3b, v2
	v_exp_f32_e32 v10, v10
	s_nop 0
	v_add_f32_e32 v10, 1.0, v10
	v_div_scale_f32 v11, s[0:1], v10, v10, v2
	v_rcp_f32_e32 v12, v11
	s_nop 0
	v_fma_f32 v13, -v11, v12, 1.0
	v_fmac_f32_e32 v12, v13, v12
	v_div_scale_f32 v13, vcc, v2, v10, v2
	v_mul_f32_e32 v14, v13, v12
	v_fma_f32 v15, -v11, v14, v13
	v_fmac_f32_e32 v14, v15, v12
	v_fma_f32 v11, -v11, v14, v13
	v_div_fmas_f32 v11, v11, v12, v14
	v_div_fixup_f32 v2, v11, v10, v2
	v_cvt_pk_bf16_f32 v2, v9, v2
	v_cvt_f32_f16_e32 v9, v3
	v_cvt_f32_f16_sdwa v3, v3 dst_sel:DWORD dst_unused:UNUSED_PAD src0_sel:WORD_1
	v_mul_f32_e32 v10, 0xbfb8aa3b, v9
	v_exp_f32_e32 v10, v10
	s_nop 0
	v_add_f32_e32 v10, 1.0, v10
	v_div_scale_f32 v11, s[0:1], v10, v10, v9
	v_rcp_f32_e32 v12, v11
	s_nop 0
	v_fma_f32 v13, -v11, v12, 1.0
	v_fmac_f32_e32 v12, v13, v12
	v_div_scale_f32 v13, vcc, v9, v10, v9
	v_mul_f32_e32 v14, v13, v12
	v_fma_f32 v15, -v11, v14, v13
	v_fmac_f32_e32 v14, v15, v12
	v_fma_f32 v11, -v11, v14, v13
	v_div_fmas_f32 v11, v11, v12, v14
	v_div_fixup_f32 v9, v11, v10, v9
	v_mul_f32_e32 v10, 0xbfb8aa3b, v3
	v_exp_f32_e32 v10, v10
	s_nop 0
	v_add_f32_e32 v10, 1.0, v10
	v_div_scale_f32 v11, s[0:1], v10, v10, v3
	v_rcp_f32_e32 v12, v11
	v_readlane_b32 s0, v220, 48
	v_fma_f32 v13, -v11, v12, 1.0
	v_fmac_f32_e32 v12, v13, v12
	v_div_scale_f32 v13, vcc, v3, v10, v3
	v_mul_f32_e32 v14, v13, v12
	v_fma_f32 v15, -v11, v14, v13
	v_fmac_f32_e32 v14, v15, v12
	v_fma_f32 v11, -v11, v14, v13
	v_div_fmas_f32 v11, v11, v12, v14
	v_div_fixup_f32 v3, v11, v10, v3
	v_cvt_pk_bf16_f32 v3, v9, v3
	global_store_dwordx4 v[4:5], v[0:3], off
	v_lshl_or_b32 v5, v52, 10, v128
	v_add_u32_e32 v6, s0, v5
	s_movk_i32 s0, 0x880
	v_mul_lo_u32 v5, v52, s0
	v_readlane_b32 s0, v220, 49
	v_lshlrev_b32_e32 v4, 3, v52
	v_lshl_add_u64 v[0:1], s[50:51], 0, v[128:129]
	v_add_u32_e32 v7, s0, v5
	s_movk_i32 s0, 0xc80
	v_mul_lo_u32 v5, v52, s0
	v_add_u32_e32 v8, 16, v5
	v_mad_i64_i32 v[4:5], s[0:1], v4, s23, 0
	v_lshl_add_u64 v[2:3], s[10:11], 0, v[128:129]
	v_lshlrev_b32_e32 v128, 1, v54
	v_mad_i64_i32 v[4:5], s[0:1], s16, v142, v[4:5]
	v_lshl_add_u64 v[4:5], v[4:5], 0, v[128:129]
	v_cmp_gt_u32_e32 vcc, 32, v54
	v_lshl_add_u64 v[4:5], s[30:31], 0, v[4:5]
	global_load_dword v162, v[0:1], off
	global_load_dword v163, v[0:1], off offset:256
	global_load_dword v164, v[0:1], off offset:512
	global_load_dword v165, v[2:3], off
	global_load_dword v166, v[2:3], off offset:256
	global_load_ushort v168, v[4:5], off offset:-256
	global_load_ushort v169, v[4:5], off offset:128
	global_load_ushort v170, v[4:5], off offset:-128
	global_load_ushort v171, v[4:5], off offset:-384
	global_load_ushort v172, v[4:5], off
	global_load_ushort v173, v[4:5], off offset:256
	s_branch .LBB0_782

; DEVI u16 f2bf(float f) { return (u16)(cvtpk(f, 0.f) & 0xffffu); }
; DEVI void prepMLA_tile(const Params& p, int l, int g, int tile, char* lds) {
;     ...
;     for (int i = 0; i < 8; ++i) {
;       int tok = wid * 8 + i; const h16* zr = Z + (size_t)tok * NBC;
;       float e0 = (float)zr[lane], e1 = (float)zr[64 + lane], e2 = (float)zr[128 + lane];
;       float f0 = (float)zr[192 + lane], f1 = (float)zr[256 + lane];
;       float sq = wave_sum(e0 * e0 + e1 * e1 + e2 * e2), sk = wave_sum(f0 * f0 + f1 * f1);
;       float rq = rsqrtf(sq * (1.f / 192.f) + 1e-6f), rk = rsqrtf(sk * (1.f / 128.f) + 1e-6f);
;       u16* aq = (u16*)(Aq + tok * RSQ); u16* ak = (u16*)(Akv + tok * RSKV);
;       aq[lane] = f2bf(e0 * rq * qnw[lane]); aq[64 + lane] = f2bf(e1 * rq * qnw[64 + lane]); aq[128 + lane] = f2bf(e2 * rq * qnw[128 + lane]);
;       ak[lane] = f2bf(f0 * rk * kvnw[lane]); ak[64 + lane] = f2bf(f1 * rk * kvnw[64 + lane]);
;       if (lane < 32) kro[tok * 32 + lane] = (float)zr[320 + lane];
.LBB0_782:
	s_waitcnt vmcnt(0)
	v_mov_b32_e32 v9, v168
	v_mov_b32_e32 v10, v169
	v_mov_b32_e32 v14, v170
	v_mov_b32_e32 v15, v171
	v_mov_b32_e32 v16, v172
	v_mov_b32_e32 v167, v173
	global_load_ushort v168, v[4:5], off offset:2752
	global_load_ushort v169, v[4:5], off offset:3136
	global_load_ushort v170, v[4:5], off offset:2880
	global_load_ushort v171, v[4:5], off offset:2624
	global_load_ushort v172, v[4:5], off offset:3008
	global_load_ushort v173, v[4:5], off offset:3264
	s_brev_b32 s0, 60
	s_mov_b32 s1, 0x3baaaaab
	v_cvt_f32_f16_e32 v9, v9
	v_cvt_f32_f16_e32 v18, v10
	v_mul_f32_e32 v10, v9, v9
	v_mul_f32_e32 v11, v18, v18
	v_fma_mix_f32 v10, v15, v15, v10 op_sel_hi:[1,1,0]
	v_fma_mix_f32 v11, v16, v16, v11 op_sel_hi:[1,1,0]
	v_fma_mix_f32 v10, v14, v14, v10 op_sel_hi:[1,1,0]
	s_nop 0
	v_add_f32_dpp v11, v11, v11 quad_perm:[1,0,3,2] row_mask:0xf bank_mask:0xf bound_ctrl:1
	v_add_f32_dpp v10, v10, v10 quad_perm:[1,0,3,2] row_mask:0xf bank_mask:0xf bound_ctrl:1
	s_nop 0
	v_add_f32_dpp v11, v11, v11 quad_perm:[2,3,0,1] row_mask:0xf bank_mask:0xf bound_ctrl:1
	v_add_f32_dpp v10, v10, v10 quad_perm:[2,3,0,1] row_mask:0xf bank_mask:0xf bound_ctrl:1
	s_nop 0
	v_add_f32_dpp v11, v11, v11 row_half_mirror row_mask:0xf bank_mask:0xf bound_ctrl:1
	v_add_f32_dpp v10, v10, v10 row_half_mirror row_mask:0xf bank_mask:0xf bound_ctrl:1
	s_nop 0
	v_add_f32_dpp v11, v11, v11 row_mirror row_mask:0xf bank_mask:0xf bound_ctrl:1
	v_add_f32_dpp v12, v10, v10 row_mirror row_mask:0xf bank_mask:0xf bound_ctrl:1
	v_mov_b32_e32 v10, v11
	v_mov_b32_e32 v13, v12
	s_nop 0
	v_permlane16_swap_b32_e32 v11, v10
	v_permlane16_swap_b32_e32 v12, v13
	v_add_f32_e32 v10, v11, v10
	v_add_f32_e32 v11, v12, v13
	v_mov_b32_e32 v12, v10
	v_mov_b32_e32 v13, v11
	s_nop 0
	v_permlane32_swap_b32_e32 v10, v12
	v_permlane32_swap_b32_e32 v11, v13
	v_pk_add_f32 v[10:11], v[10:11], v[12:13]
	s_nop 0
	v_pk_fma_f32 v[10:11], v[10:11], s[0:1], v[130:131] op_sel_hi:[1,1,0]
	s_nop 0
	v_mul_f32_e32 v12, 0x4b800000, v11
	v_cmp_gt_f32_e64 s[0:1], s26, v11
	s_nop 1
	v_cndmask_b32_e64 v11, v11, v12, s[0:1]
	v_rsq_f32_e32 v11, v11
	v_cvt_f32_f16_e32 v12, v15
	v_add_u32_e32 v15, v8, v128
	v_mul_f32_e32 v13, 0x45800000, v11
	v_cndmask_b32_e64 v11, v11, v13, s[0:1]
	v_mul_f32_e32 v12, v11, v12
	v_mul_f32_e32 v12, v162, v12
	v_cvt_pk_bf16_f32 v12, v12, v129
	v_mul_f32_e32 v9, v11, v9
	ds_write_b16 v15, v12
	v_cmp_gt_f32_e64 s[0:1], s26, v10
	v_mul_f32_e32 v9, v163, v9
	v_cvt_pk_bf16_f32 v9, v9, v129
	v_cvt_f32_f16_e32 v13, v14
	ds_write_b16 v15, v9 offset:128
	v_mul_f32_e32 v11, v11, v13
	v_mul_f32_e32 v9, v11, v164
	v_cvt_pk_bf16_f32 v9, v9, v129
	v_mul_f32_e32 v12, 0x4b800000, v10
	v_cndmask_b32_e64 v10, v10, v12, s[0:1]
	v_rsq_f32_e32 v10, v10
	v_cvt_f32_f16_e32 v12, v16
	ds_write_b16 v15, v9 offset:256
	v_mul_f32_e32 v13, 0x45800000, v10
	v_cndmask_b32_e64 v10, v10, v13, s[0:1]
	v_mul_f32_e32 v12, v10, v12
	v_mul_f32_e32 v9, v165, v12
	v_cvt_pk_bf16_f32 v9, v9, v129
	v_add_u32_e32 v12, v7, v128
	ds_write_b16 v12, v9
	v_mul_f32_e32 v9, v10, v18
	v_mul_f32_e32 v9, v9, v166
	v_cvt_pk_bf16_f32 v9, v9, v129
	ds_write_b16 v12, v9 offset:128
	s_and_saveexec_b64 s[0:1], vcc
	s_cbranch_execz .LBB0_781
	v_add_u32_e32 v9, s38, v6
	v_cvt_f32_f16_e32 v10, v167
	ds_write_b32 v9, v10
	s_branch .LBB0_781

; DEVI u16 f2bf(float f) { return (u16)(cvtpk(f, 0.f) & 0xffffu); }
; DEVI void prepSGU_tile(const Params& p, int l, int g, int tile, char* lds) {
;     ...
; #pragma unroll 2
;     for (int i = 0; i < 16; ++i) {
;       int q = wid * 16 + i;
;       h16x4 z = *(const h16x4*)(Z + (size_t)q * NBC + 992 + lane * 4);
;       float x0 = (float)z[0], x1 = (float)z[1], x2 = (float)z[2], x3 = (float)z[3];
;       float mu = wave_sum(x0 + x1 + x2 + x3) * (1.f / 256.f);
;       float d0 = x0 - mu, d1 = x1 - mu, d2 = x2 - mu, d3 = x3 - mu;
;       float var = wave_sum(d0 * d0 + d1 * d1 + d2 * d2 + d3 * d3) * (1.f / 256.f);
;       float rstd = rsqrtf(var + 1e-6f);
;       int c = lane * 4;
;       *(u16*)(lds + (c + 0) * RS + q * 2) = f2bf(d0 * rstd * lw[c + 0] + lb[c + 0]);
;       *(u16*)(lds + (c + 1) * RS + q * 2) = f2bf(d1 * rstd * lw[c + 1] + lb[c + 1]);
;       *(u16*)(lds + (c + 2) * RS + q * 2) = f2bf(d2 * rstd * lw[c + 2] + lb[c + 2]);
;       *(u16*)(lds + (c + 3) * RS + q * 2) = f2bf(d3 * rstd * lw[c + 3] + lb[c + 3]);
;     }
.LBB0_800:
	s_mov_b64 s[38:39], 0x1780
	s_waitcnt vmcnt(0)
	v_mov_b32_e32 v10, v242
	v_mov_b32_e32 v11, v243
	v_mov_b32_e32 v236, v244
	v_mov_b32_e32 v237, v245
	v_lshl_add_u64 v[4:5], v[4:5], 0, s[38:39]
	global_load_dwordx2 v[242:243], v[4:5], off offset:-3008
	global_load_dwordx2 v[244:245], v[4:5], off
	v_cvt_f32_f16_e32 v9, v10
	v_cvt_f32_f16_sdwa v12, v10 dst_sel:DWORD dst_unused:UNUSED_PAD src0_sel:WORD_1
	v_cvt_f32_f16_e32 v13, v11
	v_cvt_f32_f16_sdwa v14, v11 dst_sel:DWORD dst_unused:UNUSED_PAD src0_sel:WORD_1
	v_add_f32_e32 v9, v9, v12
	v_add_f32_e32 v9, v9, v13
	v_add_f32_e32 v9, v9, v14
	s_nop 1
	v_add_f32_dpp v9, v9, v9 quad_perm:[1,0,3,2] row_mask:0xf bank_mask:0xf bound_ctrl:1
	s_nop 1
	v_add_f32_dpp v9, v9, v9 quad_perm:[2,3,0,1] row_mask:0xf bank_mask:0xf bound_ctrl:1
	s_nop 1
	v_add_f32_dpp v9, v9, v9 row_half_mirror row_mask:0xf bank_mask:0xf bound_ctrl:1
	s_nop 1
	v_add_f32_dpp v9, v9, v9 row_mirror row_mask:0xf bank_mask:0xf bound_ctrl:1
	v_mov_b32_e32 v12, v9
	s_nop 1
	v_permlane16_swap_b32_e32 v9, v12
	v_add_f32_e32 v9, v9, v12
	v_mov_b32_e32 v12, v9
	s_nop 1
	v_permlane32_swap_b32_e32 v9, v12
	v_add_f32_e32 v9, v9, v12
	v_fma_mix_f32 v12, v9, s21, v10 op_sel_hi:[0,0,1]
	v_fma_mix_f32 v10, v9, s21, v10 op_sel:[0,0,1] op_sel_hi:[0,0,1]
	v_fma_mix_f32 v13, v9, s21, v11 op_sel_hi:[0,0,1]
	v_fma_mix_f32 v11, v9, s21, v11 op_sel:[0,0,1] op_sel_hi:[0,0,1]
	v_mul_f32_e32 v9, v10, v10
	v_fmac_f32_e32 v9, v12, v12
	v_fmac_f32_e32 v9, v13, v13
	v_fmac_f32_e32 v9, v11, v11
	s_nop 1
	v_add_f32_dpp v9, v9, v9 quad_perm:[1,0,3,2] row_mask:0xf bank_mask:0xf bound_ctrl:1
	s_nop 1
	v_add_f32_dpp v9, v9, v9 quad_perm:[2,3,0,1] row_mask:0xf bank_mask:0xf bound_ctrl:1
	s_nop 1
	v_add_f32_dpp v9, v9, v9 row_half_mirror row_mask:0xf bank_mask:0xf bound_ctrl:1
	s_nop 1
	v_add_f32_dpp v9, v9, v9 row_mirror row_mask:0xf bank_mask:0xf bound_ctrl:1
	v_mov_b32_e32 v14, v9
	s_nop 1
	v_permlane16_swap_b32_e32 v9, v14
	v_add_f32_e32 v9, v9, v14
	v_mov_b32_e32 v14, v9
	s_nop 1
	v_permlane32_swap_b32_e32 v9, v14
	v_add_f32_e32 v9, v9, v14
	v_fmamk_f32 v9, v9, 0x3b800000, v130
	v_cmp_gt_f32_e32 vcc, s26, v9
	v_mul_f32_e32 v14, 0x4b800000, v9
	s_nop 0
	v_cndmask_b32_e32 v9, v9, v14, vcc
	v_rsq_f32_e32 v9, v9
	s_nop 0
	v_mul_f32_e32 v14, 0x45800000, v9
	v_cndmask_b32_e32 v14, v9, v14, vcc
	v_mul_f32_e32 v9, v12, v14
	v_fma_f32 v15, v246, v9, v250
	v_add_u32_e32 v12, s0, v8
	v_mov_b32_e32 v232, v15
	v_mul_f32_e32 v9, v10, v14
	v_fma_f32 v15, v247, v9, v251
	v_add_u32_e32 v9, s0, v7
	v_mov_b32_e32 v233, v15
	v_mul_f32_e32 v10, v13, v14
	s_add_i32 s0, s0, 4
	s_cmp_eq_u32 s0, 0
	v_fma_f32 v15, v248, v10, v252
	v_mov_b32_e32 v234, v15
	v_mul_f32_e32 v10, v11, v14
	v_fma_f32 v13, v249, v10, v253
	v_mov_b32_e32 v235, v13
	v_cvt_f32_f16_e32 v13, v236
	v_cvt_f32_f16_sdwa v14, v236 dst_sel:DWORD dst_unused:UNUSED_PAD src0_sel:WORD_1
	v_cvt_f32_f16_e32 v15, v237
	v_cvt_f32_f16_sdwa v16, v237 dst_sel:DWORD dst_unused:UNUSED_PAD src0_sel:WORD_1
	v_add_f32_e32 v13, v13, v14
	v_add_f32_e32 v13, v13, v15
	v_add_f32_e32 v13, v13, v16
	s_nop 1
	v_add_f32_dpp v13, v13, v13 quad_perm:[1,0,3,2] row_mask:0xf bank_mask:0xf bound_ctrl:1
	s_nop 1
	v_add_f32_dpp v13, v13, v13 quad_perm:[2,3,0,1] row_mask:0xf bank_mask:0xf bound_ctrl:1
	s_nop 1
	v_add_f32_dpp v13, v13, v13 row_half_mirror row_mask:0xf bank_mask:0xf bound_ctrl:1
	s_nop 1
	v_add_f32_dpp v13, v13, v13 row_mirror row_mask:0xf bank_mask:0xf bound_ctrl:1
	v_mov_b32_e32 v14, v13
	s_nop 1
	v_permlane16_swap_b32_e32 v13, v14
	v_add_f32_e32 v13, v13, v14
	v_mov_b32_e32 v14, v13
	s_nop 1
	v_permlane32_swap_b32_e32 v13, v14
	v_add_f32_e32 v13, v13, v14
	v_fma_mix_f32 v14, v13, s21, v236 op_sel_hi:[0,0,1]
	v_fma_mix_f32 v10, v13, s21, v236 op_sel:[0,0,1] op_sel_hi:[0,0,1]
	v_fma_mix_f32 v15, v13, s21, v237 op_sel_hi:[0,0,1]
	v_fma_mix_f32 v11, v13, s21, v237 op_sel:[0,0,1] op_sel_hi:[0,0,1]
	v_mul_f32_e32 v13, v10, v10
	v_fmac_f32_e32 v13, v14, v14
	v_fmac_f32_e32 v13, v15, v15
	v_fmac_f32_e32 v13, v11, v11
	s_nop 1
	v_add_f32_dpp v13, v13, v13 quad_perm:[1,0,3,2] row_mask:0xf bank_mask:0xf bound_ctrl:1
	s_nop 1
	v_add_f32_dpp v13, v13, v13 quad_perm:[2,3,0,1] row_mask:0xf bank_mask:0xf bound_ctrl:1
	s_nop 1
	v_add_f32_dpp v13, v13, v13 row_half_mirror row_mask:0xf bank_mask:0xf bound_ctrl:1
	s_nop 1
	v_add_f32_dpp v13, v13, v13 row_mirror row_mask:0xf bank_mask:0xf bound_ctrl:1
	v_mov_b32_e32 v16, v13
	s_nop 1
	v_permlane16_swap_b32_e32 v13, v16
	v_add_f32_e32 v13, v13, v16
	v_mov_b32_e32 v16, v13
	s_nop 1
	v_permlane32_swap_b32_e32 v13, v16
	v_add_f32_e32 v13, v13, v16
	v_fmamk_f32 v13, v13, 0x3b800000, v130
	v_cmp_gt_f32_e32 vcc, s26, v13
	v_mul_f32_e32 v16, 0x4b800000, v13
	s_nop 0
	v_cndmask_b32_e32 v13, v13, v16, vcc
	v_rsq_f32_e32 v13, v13
	s_nop 0
	v_mul_f32_e32 v16, 0x45800000, v13
	v_cndmask_b32_e32 v13, v13, v16, vcc
	v_mul_f32_e32 v14, v14, v13
	v_mul_f32_e32 v10, v10, v13
	v_fma_f32 v17, v246, v14, v250
	v_cvt_pk_bf16_f32 v14, v232, v17
	ds_write_b32 v12, v14 offset:32
	v_fma_f32 v14, v247, v10, v251
	v_cvt_pk_bf16_f32 v10, v233, v14
	ds_write_b32 v9, v10 offset:32
	v_mul_f32_e32 v10, v15, v13
	v_fma_f32 v14, v248, v10, v252
	v_cvt_pk_bf16_f32 v10, v234, v14
	ds_write_b32 v9, v10 offset:304
	v_mul_f32_e32 v10, v11, v13
	v_fma_f32 v12, v249, v10, v253
	v_cvt_pk_bf16_f32 v10, v235, v12
	ds_write_b32 v9, v10 offset:576
	s_cbranch_scc0 .LBB0_800
; DEVI void prepSGU_tile(const Params& p, int l, int g, int tile, char* lds) {
;     ...
; #pragma unroll 1
;     for (int ks = 0; ks < 4; ++ks) {
;       bf16x8 bfr[4];
; #pragma unroll
;       for (int nb = 0; nb < 4; ++nb) bfr[nb] = *(const bf16x8*)(lds + (gi * 64 + nb * 16 + l15) * RS + ks * 64 + l4 * 16);
; #pragma unroll
;       for (int mb = 0; mb < 4; ++mb) {
;         bf16x8 a = *(const bf16x8*)(Ws + (size_t)(mh * 64 + mb * 16 + l15) * 128 + ks * 32 + l4 * 8);
; #pragma unroll
;         for (int nb = 0; nb < 4; ++nb) acc[mb][nb] = __builtin_amdgcn_mfma_f32_16x16x32_bf16(a, bfr[nb], acc[mb][nb], 0, 0, 0);
;       }
;     }
;     const float* bs = p.b_s + ((size_t)l * 4 + gi) * 128;
;     u16* Yc = (u16*)(p.ws + OFF_YC);
; #pragma unroll
;     for (int mb = 0; mb < 4; ++mb)
; #pragma unroll
;       for (int j = 0; j < 4; ++j) {
;         int pp = mh * 64 + mb * 16 + l4 * 4 + j; float bv = bs[pp];
;         const h16* zr = Z + (size_t)pp * NBC;
	v_ashrrev_i32_e32 v66, 7, v6
	v_and_b32_e32 v70, 15, v6
	v_ashrrev_i32_e32 v67, 31, v66
	v_bfe_u32 v65, v6, 6, 1
	v_lshlrev_b32_e32 v4, 8, v70
	v_lshlrev_b64 v[0:1], 15, v[66:67]
	v_and_b32_e32 v3, 48, v64
	v_lshl_or_b32 v4, v65, 14, v4
	v_or3_b32 v0, v0, v3, v4
	s_movk_i32 s0, 0x4400
	v_lshl_add_u64 v[68:69], s[18:19], 0, v[0:1]
	v_mul_lo_u32 v0, v66, s0
	v_and_b32_e32 v2, 48, v6
	v_mad_u32_u24 v0, v70, s27, v0
	v_mov_b32_e32 v16, 0
	v_add3_u32 v71, v0, v2, 16
	s_mov_b64 s[0:1], 0
	v_mov_b32_e32 v17, v16
	v_mov_b32_e32 v18, v16
	v_mov_b32_e32 v19, v16
	v_mov_b32_e32 v20, v16
	v_mov_b32_e32 v21, v16
	v_mov_b32_e32 v22, v16
	v_mov_b32_e32 v23, v16
	v_mov_b32_e32 v24, v16
	v_mov_b32_e32 v25, v16
	v_mov_b32_e32 v26, v16
	v_mov_b32_e32 v27, v16
	v_mov_b32_e32 v28, v16
	v_mov_b32_e32 v29, v16
	v_mov_b32_e32 v30, v16
	v_mov_b32_e32 v31, v16
	v_mov_b32_e32 v32, v16
	v_mov_b32_e32 v33, v16
	v_mov_b32_e32 v34, v16
	v_mov_b32_e32 v35, v16
	v_mov_b32_e32 v36, v16
	v_mov_b32_e32 v37, v16
	v_mov_b32_e32 v38, v16
	v_mov_b32_e32 v39, v16
	v_mov_b32_e32 v40, v16
	v_mov_b32_e32 v41, v16
	v_mov_b32_e32 v42, v16
	v_mov_b32_e32 v43, v16
	v_mov_b32_e32 v44, v16
	v_mov_b32_e32 v45, v16
	v_mov_b32_e32 v46, v16
	v_mov_b32_e32 v47, v16
	v_mov_b32_e32 v48, v16
	v_mov_b32_e32 v49, v16
	v_mov_b32_e32 v50, v16
	v_mov_b32_e32 v51, v16
	v_mov_b32_e32 v52, v16
	v_mov_b32_e32 v53, v16
	v_mov_b32_e32 v54, v16
	v_mov_b32_e32 v55, v16
	v_mov_b32_e32 v56, v16
	v_mov_b32_e32 v57, v16
	v_mov_b32_e32 v58, v16
	v_mov_b32_e32 v59, v16
	v_mov_b32_e32 v60, v16
	v_mov_b32_e32 v61, v16
	v_mov_b32_e32 v62, v16
	v_mov_b32_e32 v63, v16
	v_mov_b32_e32 v12, v16
	v_mov_b32_e32 v13, v16
	v_mov_b32_e32 v14, v16
	v_mov_b32_e32 v15, v16
	v_mov_b32_e32 v8, v16
	v_mov_b32_e32 v9, v16
	v_mov_b32_e32 v10, v16
	v_mov_b32_e32 v11, v16
	v_mov_b32_e32 v4, v16
	v_mov_b32_e32 v5, v16
	v_mov_b32_e32 v6, v16
	v_mov_b32_e32 v7, v16
	v_mov_b32_e32 v0, v16
	v_mov_b32_e32 v1, v16
	v_mov_b32_e32 v2, v16
	v_mov_b32_e32 v3, v16
	s_waitcnt lgkmcnt(0)
	s_barrier
.LBB0_802:
	v_lshl_add_u64 v[92:93], v[68:69], 0, s[0:1]
	s_mov_b32 s17, 0x2459000
	v_add_co_u32_e32 v94, vcc, s17, v92
	ds_read_b128 v[72:75], v71
	ds_read_b128 v[76:79], v71 offset:4352
	ds_read_b128 v[80:83], v71 offset:8704
	ds_read_b128 v[84:87], v71 offset:13056
	v_addc_co_u32_e32 v95, vcc, 0, v93, vcc
	global_load_dwordx4 v[88:91], v[94:95], off offset:-4096
	s_mov_b32 s17, 0x245b000
	v_add_co_u32_e32 v92, vcc, s17, v92
	s_add_u32 s0, s0, 64
	s_nop 0
	v_addc_co_u32_e32 v93, vcc, 0, v93, vcc
	s_addc_u32 s1, s1, 0
	v_add_u32_e32 v71, 64, v71
	s_cmpk_lg_i32 s0, 0x100
	s_waitcnt vmcnt(0) lgkmcnt(3)
	v_mfma_f32_16x16x32_bf16 v[60:63], v[88:91], v[72:75], v[60:63]
	s_waitcnt lgkmcnt(2)
	v_mfma_f32_16x16x32_bf16 v[56:59], v[88:91], v[76:79], v[56:59]
	s_waitcnt lgkmcnt(1)
	v_mfma_f32_16x16x32_bf16 v[52:55], v[88:91], v[80:83], v[52:55]
	s_waitcnt lgkmcnt(0)
	v_mfma_f32_16x16x32_bf16 v[48:51], v[88:91], v[84:87], v[48:51]
	global_load_dwordx4 v[88:91], v[94:95], off
	s_waitcnt vmcnt(0)
	v_mfma_f32_16x16x32_bf16 v[44:47], v[88:91], v[72:75], v[44:47]
	v_mfma_f32_16x16x32_bf16 v[40:43], v[88:91], v[76:79], v[40:43]
	v_mfma_f32_16x16x32_bf16 v[36:39], v[88:91], v[80:83], v[36:39]
	v_mfma_f32_16x16x32_bf16 v[32:35], v[88:91], v[84:87], v[32:35]
	global_load_dwordx4 v[88:91], v[92:93], off offset:-4096
	s_waitcnt vmcnt(0)
	v_mfma_f32_16x16x32_bf16 v[28:31], v[88:91], v[72:75], v[28:31]
	v_mfma_f32_16x16x32_bf16 v[24:27], v[88:91], v[76:79], v[24:27]
	v_mfma_f32_16x16x32_bf16 v[20:23], v[88:91], v[80:83], v[20:23]
	v_mfma_f32_16x16x32_bf16 v[16:19], v[88:91], v[84:87], v[16:19]
	global_load_dwordx4 v[88:91], v[92:93], off
	s_waitcnt vmcnt(0)
	v_mfma_f32_16x16x32_bf16 v[12:15], v[88:91], v[72:75], v[12:15]
	v_mfma_f32_16x16x32_bf16 v[8:11], v[88:91], v[76:79], v[8:11]
	v_mfma_f32_16x16x32_bf16 v[4:7], v[88:91], v[80:83], v[4:7]
	v_mfma_f32_16x16x32_bf16 v[0:3], v[88:91], v[84:87], v[0:3]
	s_cbranch_scc1 .LBB0_802
	v_readlane_b32 s38, v220, 61
	s_add_i32 s17, s12, 0xfffffd00
	v_readlane_b32 s39, v220, 62
	s_mul_i32 s0, s17, 0x2f000
	s_mov_b32 s1, s39
	s_lshl_b64 s[0:1], s[0:1], 1
	s_add_u32 s0, s14, s0
	v_lshrrev_b32_e32 v64, 2, v64
	v_lshl_or_b32 v72, v66, 6, v70
	s_addc_u32 s1, s15, s1
	v_and_b32_e32 v64, 12, v64
	v_lshl_or_b32 v70, v65, 6, v64
	v_ashrrev_i32_e32 v73, 31, v72
	v_mov_b64_e32 v[68:69], s[0:1]
	v_mad_u64_u32 v[74:75], s[0:1], v70, s23, v[68:69]
	v_lshlrev_b64 v[64:65], 1, v[72:73]
	v_lshl_add_u64 v[72:73], v[74:75], 0, v[64:65]
	v_lshlrev_b64 v[66:67], 7, v[66:67]
	v_readlane_b32 s40, v221, 11
	v_lshl_add_u64 v[66:67], v[66:67], 0, s[62:63]
	v_readlane_b32 s46, v221, 17
	v_readlane_b32 s47, v221, 18
	v_lshlrev_b32_e32 v128, 2, v70
	v_readlane_b32 s41, v221, 12
	v_lshl_add_u64 v[66:67], v[66:67], 2, s[46:47]
	v_lshl_add_u64 v[66:67], v[66:67], 0, v[128:129]
	v_readlane_b32 s42, v221, 13
	v_readlane_b32 s43, v221, 14
	v_readlane_b32 s44, v221, 15
	v_readlane_b32 s45, v221, 16
	s_lshl_b32 s0, s17, 7
	s_add_i32 s0, s0, s13
	v_mov_b32_e32 v238, v72
	v_mov_b32_e32 v239, v73
	v_add_co_u32_e32 v240, vcc, 0xbc0, v72
	s_nop 1
	v_addc_co_u32_e32 v241, vcc, 0, v73, vcc
	v_add_co_u32_e32 v242, vcc, 0x1780, v72
	s_nop 1
	v_addc_co_u32_e32 v243, vcc, 0, v73, vcc
	v_add_co_u32_e32 v244, vcc, 0x2340, v72
	s_nop 1
	v_addc_co_u32_e32 v245, vcc, 0, v73, vcc
	global_load_ushort v162, v[238:239], off offset:2496
	global_load_ushort v163, v[238:239], off offset:1472
	global_load_ushort v164, v[238:239], off offset:2528
	global_load_ushort v165, v[238:239], off offset:1504
	global_load_ushort v166, v[238:239], off offset:2560
	global_load_ushort v167, v[238:239], off offset:1536
; DEVI u16 f2bf(float f) { return (u16)(cvtpk(f, 0.f) & 0xffffu); }
; DEVI float siluf_(float x) { return x / (1.f + __expf(-x)); }
; DEVI void prepSGU_tile(const Params& p, int l, int g, int tile, char* lds) {
;     ...
;     const float* bs = p.b_s + ((size_t)l * 4 + gi) * 128;
;     u16* Yc = (u16*)(p.ws + OFF_YC);
; #pragma unroll
;     for (int mb = 0; mb < 4; ++mb)
; #pragma unroll
;       for (int j = 0; j < 4; ++j) {
;         int pp = mh * 64 + mb * 16 + l4 * 4 + j; float bv = bs[pp];
;         const h16* zr = Z + (size_t)pp * NBC;
; #pragma unroll
;         for (int nb = 0; nb < 4; ++nb) {
;           int c = gi * 64 + nb * 16 + l15;
;           float u = (float)zr[736 + c], gc = (float)zr[1248 + c];
;           Yc[(size_t)(t0 + pp) * 256 + c] = f2bf(u * (acc[mb][nb][j] + bv) * siluf_(gc));
;         }
;       }
	global_load_ushort v168, v[238:239], off offset:2592
	global_load_ushort v169, v[238:239], off offset:1568
	global_load_ushort v170, v[240:241], off offset:2496
	global_load_ushort v171, v[240:241], off offset:1472
	global_load_ushort v172, v[240:241], off offset:2528
	global_load_ushort v173, v[240:241], off offset:1504
	global_load_ushort v174, v[240:241], off offset:2560
	global_load_ushort v175, v[240:241], off offset:1536
	global_load_ushort v176, v[240:241], off offset:2592
	global_load_ushort v177, v[240:241], off offset:1568
	global_load_ushort v178, v[242:243], off offset:2496
	global_load_ushort v179, v[242:243], off offset:1472
	global_load_ushort v180, v[242:243], off offset:2528
	global_load_ushort v181, v[242:243], off offset:1504
	global_load_ushort v182, v[242:243], off offset:2560
	global_load_ushort v183, v[242:243], off offset:1536
	global_load_ushort v184, v[242:243], off offset:2592
	global_load_ushort v185, v[242:243], off offset:1568
	global_load_ushort v186, v[244:245], off offset:2496
	global_load_ushort v187, v[244:245], off offset:1472
	global_load_ushort v188, v[244:245], off offset:2528
	global_load_ushort v189, v[244:245], off offset:1504
	global_load_ushort v190, v[244:245], off offset:2560
	global_load_ushort v191, v[244:245], off offset:1536
	global_load_ushort v192, v[244:245], off offset:2592
	global_load_ushort v193, v[244:245], off offset:1568
	global_load_dword v194, v[66:67], off
	global_load_dword v195, v[66:67], off offset:4
	global_load_dword v196, v[66:67], off offset:8
	global_load_dword v197, v[66:67], off offset:12
	v_add_co_u32_e32 v238, vcc, 0xbc00, v72
	s_nop 1
	v_addc_co_u32_e32 v239, vcc, 0, v73, vcc
	v_add_co_u32_e32 v240, vcc, 0xc7c0, v72
	s_nop 1
	v_addc_co_u32_e32 v241, vcc, 0, v73, vcc
	v_add_co_u32_e32 v242, vcc, 0xd380, v72
	s_nop 1
	v_addc_co_u32_e32 v243, vcc, 0, v73, vcc
	v_add_co_u32_e32 v244, vcc, 0xdf40, v72
	s_nop 1
	v_addc_co_u32_e32 v245, vcc, 0, v73, vcc
	global_load_ushort v198, v[238:239], off offset:2496
	global_load_ushort v199, v[238:239], off offset:1472
	global_load_ushort v200, v[238:239], off offset:2528
	global_load_ushort v201, v[238:239], off offset:1504
	global_load_ushort v202, v[238:239], off offset:2560
	global_load_ushort v203, v[238:239], off offset:1536
	global_load_ushort v204, v[238:239], off offset:2592
	global_load_ushort v205, v[238:239], off offset:1568
	global_load_ushort v206, v[240:241], off offset:2496
	global_load_ushort v207, v[240:241], off offset:1472
	global_load_ushort v208, v[240:241], off offset:2528
	global_load_ushort v209, v[240:241], off offset:1504
	global_load_ushort v210, v[240:241], off offset:2560
	global_load_ushort v211, v[240:241], off offset:1536
	global_load_ushort v212, v[240:241], off offset:2592
	global_load_ushort v213, v[240:241], off offset:1568
	global_load_ushort v214, v[242:243], off offset:2496
	global_load_ushort v215, v[242:243], off offset:1472
	global_load_ushort v216, v[242:243], off offset:2528
	global_load_ushort v217, v[242:243], off offset:1504
	global_load_ushort v222, v[242:243], off offset:2560
	global_load_ushort v223, v[242:243], off offset:1536
	global_load_ushort v224, v[242:243], off offset:2592
	global_load_ushort v225, v[242:243], off offset:1568
	global_load_ushort v226, v[244:245], off offset:2496
	global_load_ushort v227, v[244:245], off offset:1472
	global_load_ushort v228, v[244:245], off offset:2528
	global_load_ushort v229, v[244:245], off offset:1504
	global_load_ushort v230, v[244:245], off offset:2560
	global_load_ushort v231, v[244:245], off offset:1536
	global_load_ushort v232, v[244:245], off offset:2592
	global_load_ushort v233, v[244:245], off offset:1568
	global_load_dword v234, v[66:67], off offset:64
	global_load_dword v235, v[66:67], off offset:68
	global_load_dword v236, v[66:67], off offset:72
	global_load_dword v237, v[66:67], off offset:76
	s_waitcnt vmcnt(36)
	v_or_b32_e32 v128, s0, v70
	v_lshlrev_b64 v[74:75], 9, v[128:129]
	v_lshl_add_u64 v[74:75], s[28:29], 0, v[74:75]
	v_lshl_add_u64 v[74:75], v[74:75], 0, v[64:65]
	v_cvt_f32_f16_e32 v246, v162
	v_cvt_f32_f16_e32 v247, v163
	v_mul_f32_e32 v248, 0xbfb8aa3b, v246
	v_exp_f32_e32 v248, v248
	v_add_f32_e32 v60, v60, v194
	v_add_f32_e32 v248, 1.0, v248
	v_div_scale_f32 v249, s[38:39], v248, v248, v246
	v_rcp_f32_e32 v250, v249
	v_mul_f32_e32 v60, v60, v247
	v_div_scale_f32 v251, vcc, v246, v248, v246
	v_fma_f32 v252, -v249, v250, 1.0
	v_fmac_f32_e32 v250, v252, v250
	v_mul_f32_e32 v252, v251, v250
	v_fma_f32 v253, -v249, v252, v251
	v_fmac_f32_e32 v252, v253, v250
	v_fma_f32 v251, -v249, v252, v251
	v_div_fmas_f32 v251, v251, v250, v252
	v_div_fixup_f32 v251, v251, v248, v246
	v_mul_f32_e32 v60, v60, v251
	v_cvt_pk_bf16_f32 v60, v60, v129
	global_store_short v[74:75], v60, off
	v_cvt_f32_f16_e32 v246, v164
	v_cvt_f32_f16_e32 v247, v165
	v_mul_f32_e32 v248, 0xbfb8aa3b, v246
	v_exp_f32_e32 v248, v248
	v_add_f32_e32 v56, v56, v194
	v_add_f32_e32 v248, 1.0, v248
	v_div_scale_f32 v249, s[38:39], v248, v248, v246
	v_rcp_f32_e32 v250, v249
	v_mul_f32_e32 v56, v56, v247
	v_div_scale_f32 v251, vcc, v246, v248, v246
	v_fma_f32 v252, -v249, v250, 1.0
	v_fmac_f32_e32 v250, v252, v250
	v_mul_f32_e32 v252, v251, v250
	v_fma_f32 v253, -v249, v252, v251
	v_fmac_f32_e32 v252, v253, v250
	v_fma_f32 v251, -v249, v252, v251
	v_div_fmas_f32 v251, v251, v250, v252
	v_div_fixup_f32 v251, v251, v248, v246
	v_mul_f32_e32 v56, v56, v251
	v_cvt_pk_bf16_f32 v56, v56, v129
	global_store_short v[74:75], v56, off offset:32
	v_cvt_f32_f16_e32 v246, v166
	v_cvt_f32_f16_e32 v247, v167
	v_mul_f32_e32 v248, 0xbfb8aa3b, v246
	v_exp_f32_e32 v248, v248
; DEVI u16 f2bf(float f) { return (u16)(cvtpk(f, 0.f) & 0xffffu); }
; DEVI float siluf_(float x) { return x / (1.f + __expf(-x)); }
; DEVI void prepSGU_tile(const Params& p, int l, int g, int tile, char* lds) {
;     ...
; #pragma unroll
;         for (int nb = 0; nb < 4; ++nb) {
;           int c = gi * 64 + nb * 16 + l15;
;           float u = (float)zr[736 + c], gc = (float)zr[1248 + c];
;           Yc[(size_t)(t0 + pp) * 256 + c] = f2bf(u * (acc[mb][nb][j] + bv) * siluf_(gc));
;         }
	v_add_f32_e32 v52, v52, v194
	v_add_f32_e32 v248, 1.0, v248
	v_div_scale_f32 v249, s[38:39], v248, v248, v246
	v_rcp_f32_e32 v250, v249
	v_mul_f32_e32 v52, v52, v247
	v_div_scale_f32 v251, vcc, v246, v248, v246
	v_fma_f32 v252, -v249, v250, 1.0
	v_fmac_f32_e32 v250, v252, v250
	v_mul_f32_e32 v252, v251, v250
	v_fma_f32 v253, -v249, v252, v251
	v_fmac_f32_e32 v252, v253, v250
	v_fma_f32 v251, -v249, v252, v251
	v_div_fmas_f32 v251, v251, v250, v252
	v_div_fixup_f32 v251, v251, v248, v246
	v_mul_f32_e32 v52, v52, v251
	v_cvt_pk_bf16_f32 v52, v52, v129
	global_store_short v[74:75], v52, off offset:64
	v_cvt_f32_f16_e32 v246, v168
	v_cvt_f32_f16_e32 v247, v169
	v_mul_f32_e32 v248, 0xbfb8aa3b, v246
	v_exp_f32_e32 v248, v248
	v_add_f32_e32 v48, v48, v194
	v_add_f32_e32 v248, 1.0, v248
	v_div_scale_f32 v249, s[38:39], v248, v248, v246
	v_rcp_f32_e32 v250, v249
	v_mul_f32_e32 v48, v48, v247
	v_div_scale_f32 v251, vcc, v246, v248, v246
	v_fma_f32 v252, -v249, v250, 1.0
	v_fmac_f32_e32 v250, v252, v250
	v_mul_f32_e32 v252, v251, v250
	v_fma_f32 v253, -v249, v252, v251
	v_fmac_f32_e32 v252, v253, v250
	v_fma_f32 v251, -v249, v252, v251
	v_div_fmas_f32 v251, v251, v250, v252
	v_div_fixup_f32 v251, v251, v248, v246
	v_mul_f32_e32 v48, v48, v251
	v_cvt_pk_bf16_f32 v48, v48, v129
	global_store_short v[74:75], v48, off offset:96
	v_cvt_f32_f16_e32 v246, v170
	v_cvt_f32_f16_e32 v247, v171
	v_mul_f32_e32 v248, 0xbfb8aa3b, v246
	v_exp_f32_e32 v248, v248
	v_add_f32_e32 v61, v61, v195
	v_add_f32_e32 v248, 1.0, v248
	v_div_scale_f32 v249, s[38:39], v248, v248, v246
	v_rcp_f32_e32 v250, v249
	v_mul_f32_e32 v61, v61, v247
	v_div_scale_f32 v251, vcc, v246, v248, v246
	v_fma_f32 v252, -v249, v250, 1.0
	v_fmac_f32_e32 v250, v252, v250
	v_mul_f32_e32 v252, v251, v250
	v_fma_f32 v253, -v249, v252, v251
	v_fmac_f32_e32 v252, v253, v250
	v_fma_f32 v251, -v249, v252, v251
	v_div_fmas_f32 v251, v251, v250, v252
	v_div_fixup_f32 v251, v251, v248, v246
	v_mul_f32_e32 v61, v61, v251
	v_cvt_pk_bf16_f32 v61, v61, v129
	global_store_short v[74:75], v61, off offset:512
	v_cvt_f32_f16_e32 v246, v172
	v_cvt_f32_f16_e32 v247, v173
	v_mul_f32_e32 v248, 0xbfb8aa3b, v246
	v_exp_f32_e32 v248, v248
	v_add_f32_e32 v57, v57, v195
	v_add_f32_e32 v248, 1.0, v248
	v_div_scale_f32 v249, s[38:39], v248, v248, v246
	v_rcp_f32_e32 v250, v249
	v_mul_f32_e32 v57, v57, v247
	v_div_scale_f32 v251, vcc, v246, v248, v246
	v_fma_f32 v252, -v249, v250, 1.0
	v_fmac_f32_e32 v250, v252, v250
	v_mul_f32_e32 v252, v251, v250
	v_fma_f32 v253, -v249, v252, v251
	v_fmac_f32_e32 v252, v253, v250
	v_fma_f32 v251, -v249, v252, v251
	v_div_fmas_f32 v251, v251, v250, v252
	v_div_fixup_f32 v251, v251, v248, v246
	v_mul_f32_e32 v57, v57, v251
	v_cvt_pk_bf16_f32 v57, v57, v129
	global_store_short v[74:75], v57, off offset:544
	v_cvt_f32_f16_e32 v246, v174
	v_cvt_f32_f16_e32 v247, v175
	v_mul_f32_e32 v248, 0xbfb8aa3b, v246
	v_exp_f32_e32 v248, v248
	v_add_f32_e32 v53, v53, v195
	v_add_f32_e32 v248, 1.0, v248
	v_div_scale_f32 v249, s[38:39], v248, v248, v246
	v_rcp_f32_e32 v250, v249
	v_mul_f32_e32 v53, v53, v247
	v_div_scale_f32 v251, vcc, v246, v248, v246
	v_fma_f32 v252, -v249, v250, 1.0
	v_fmac_f32_e32 v250, v252, v250
	v_mul_f32_e32 v252, v251, v250
	v_fma_f32 v253, -v249, v252, v251
	v_fmac_f32_e32 v252, v253, v250
	v_fma_f32 v251, -v249, v252, v251
	v_div_fmas_f32 v251, v251, v250, v252
	v_div_fixup_f32 v251, v251, v248, v246
	v_mul_f32_e32 v53, v53, v251
	v_cvt_pk_bf16_f32 v53, v53, v129
	global_store_short v[74:75], v53, off offset:576
	v_cvt_f32_f16_e32 v246, v176
	v_cvt_f32_f16_e32 v247, v177
	v_mul_f32_e32 v248, 0xbfb8aa3b, v246
	v_exp_f32_e32 v248, v248
	v_add_f32_e32 v49, v49, v195
	v_add_f32_e32 v248, 1.0, v248
	v_div_scale_f32 v249, s[38:39], v248, v248, v246
	v_rcp_f32_e32 v250, v249
	v_mul_f32_e32 v49, v49, v247
	v_div_scale_f32 v251, vcc, v246, v248, v246
	v_fma_f32 v252, -v249, v250, 1.0
	v_fmac_f32_e32 v250, v252, v250
	v_mul_f32_e32 v252, v251, v250
	v_fma_f32 v253, -v249, v252, v251
	v_fmac_f32_e32 v252, v253, v250
	v_fma_f32 v251, -v249, v252, v251
	v_div_fmas_f32 v251, v251, v250, v252
	v_div_fixup_f32 v251, v251, v248, v246
	v_mul_f32_e32 v49, v49, v251
	v_cvt_pk_bf16_f32 v49, v49, v129
	global_store_short v[74:75], v49, off offset:608
	v_cvt_f32_f16_e32 v246, v178
	v_cvt_f32_f16_e32 v247, v179
	v_mul_f32_e32 v248, 0xbfb8aa3b, v246
	v_exp_f32_e32 v248, v248
	v_add_f32_e32 v62, v62, v196
	v_add_f32_e32 v248, 1.0, v248
	v_div_scale_f32 v249, s[38:39], v248, v248, v246
	v_rcp_f32_e32 v250, v249
	v_mul_f32_e32 v62, v62, v247
	v_div_scale_f32 v251, vcc, v246, v248, v246
	v_fma_f32 v252, -v249, v250, 1.0
	v_fmac_f32_e32 v250, v252, v250
	v_mul_f32_e32 v252, v251, v250
	v_fma_f32 v253, -v249, v252, v251
	v_fmac_f32_e32 v252, v253, v250
	v_fma_f32 v251, -v249, v252, v251
	v_div_fmas_f32 v251, v251, v250, v252
	v_div_fixup_f32 v251, v251, v248, v246
	v_mul_f32_e32 v62, v62, v251
	v_cvt_pk_bf16_f32 v62, v62, v129
	global_store_short v[74:75], v62, off offset:1024
	v_cvt_f32_f16_e32 v246, v180
	v_cvt_f32_f16_e32 v247, v181
	v_mul_f32_e32 v248, 0xbfb8aa3b, v246
	v_exp_f32_e32 v248, v248
	v_add_f32_e32 v58, v58, v196
	v_add_f32_e32 v248, 1.0, v248
	v_div_scale_f32 v249, s[38:39], v248, v248, v246
	v_rcp_f32_e32 v250, v249
	v_mul_f32_e32 v58, v58, v247
	v_div_scale_f32 v251, vcc, v246, v248, v246
	v_fma_f32 v252, -v249, v250, 1.0
	v_fmac_f32_e32 v250, v252, v250
	v_mul_f32_e32 v252, v251, v250
	v_fma_f32 v253, -v249, v252, v251
	v_fmac_f32_e32 v252, v253, v250
	v_fma_f32 v251, -v249, v252, v251
	v_div_fmas_f32 v251, v251, v250, v252
	v_div_fixup_f32 v251, v251, v248, v246
	v_mul_f32_e32 v58, v58, v251
; DEVI u16 f2bf(float f) { return (u16)(cvtpk(f, 0.f) & 0xffffu); }
; DEVI float siluf_(float x) { return x / (1.f + __expf(-x)); }
; DEVI void prepSGU_tile(const Params& p, int l, int g, int tile, char* lds) {
;     ...
; #pragma unroll
;         for (int nb = 0; nb < 4; ++nb) {
;           int c = gi * 64 + nb * 16 + l15;
;           float u = (float)zr[736 + c], gc = (float)zr[1248 + c];
;           Yc[(size_t)(t0 + pp) * 256 + c] = f2bf(u * (acc[mb][nb][j] + bv) * siluf_(gc));
;         }
	v_cvt_pk_bf16_f32 v58, v58, v129
	global_store_short v[74:75], v58, off offset:1056
	v_cvt_f32_f16_e32 v246, v182
	v_cvt_f32_f16_e32 v247, v183
	v_mul_f32_e32 v248, 0xbfb8aa3b, v246
	v_exp_f32_e32 v248, v248
	v_add_f32_e32 v54, v54, v196
	v_add_f32_e32 v248, 1.0, v248
	v_div_scale_f32 v249, s[38:39], v248, v248, v246
	v_rcp_f32_e32 v250, v249
	v_mul_f32_e32 v54, v54, v247
	v_div_scale_f32 v251, vcc, v246, v248, v246
	v_fma_f32 v252, -v249, v250, 1.0
	v_fmac_f32_e32 v250, v252, v250
	v_mul_f32_e32 v252, v251, v250
	v_fma_f32 v253, -v249, v252, v251
	v_fmac_f32_e32 v252, v253, v250
	v_fma_f32 v251, -v249, v252, v251
	v_div_fmas_f32 v251, v251, v250, v252
	v_div_fixup_f32 v251, v251, v248, v246
	v_mul_f32_e32 v54, v54, v251
	v_cvt_pk_bf16_f32 v54, v54, v129
	global_store_short v[74:75], v54, off offset:1088
	v_cvt_f32_f16_e32 v246, v184
	v_cvt_f32_f16_e32 v247, v185
	v_mul_f32_e32 v248, 0xbfb8aa3b, v246
	v_exp_f32_e32 v248, v248
	v_add_f32_e32 v50, v50, v196
	v_add_f32_e32 v248, 1.0, v248
	v_div_scale_f32 v249, s[38:39], v248, v248, v246
	v_rcp_f32_e32 v250, v249
	v_mul_f32_e32 v50, v50, v247
	v_div_scale_f32 v251, vcc, v246, v248, v246
	v_fma_f32 v252, -v249, v250, 1.0
	v_fmac_f32_e32 v250, v252, v250
	v_mul_f32_e32 v252, v251, v250
	v_fma_f32 v253, -v249, v252, v251
	v_fmac_f32_e32 v252, v253, v250
	v_fma_f32 v251, -v249, v252, v251
	v_div_fmas_f32 v251, v251, v250, v252
	v_div_fixup_f32 v251, v251, v248, v246
	v_mul_f32_e32 v50, v50, v251
	v_cvt_pk_bf16_f32 v50, v50, v129
	global_store_short v[74:75], v50, off offset:1120
	v_cvt_f32_f16_e32 v246, v186
	v_cvt_f32_f16_e32 v247, v187
	v_mul_f32_e32 v248, 0xbfb8aa3b, v246
	v_exp_f32_e32 v248, v248
	v_add_f32_e32 v63, v63, v197
	v_add_f32_e32 v248, 1.0, v248
	v_div_scale_f32 v249, s[38:39], v248, v248, v246
	v_rcp_f32_e32 v250, v249
	v_mul_f32_e32 v63, v63, v247
	v_div_scale_f32 v251, vcc, v246, v248, v246
	v_fma_f32 v252, -v249, v250, 1.0
	v_fmac_f32_e32 v250, v252, v250
	v_mul_f32_e32 v252, v251, v250
	v_fma_f32 v253, -v249, v252, v251
	v_fmac_f32_e32 v252, v253, v250
	v_fma_f32 v251, -v249, v252, v251
	v_div_fmas_f32 v251, v251, v250, v252
	v_div_fixup_f32 v251, v251, v248, v246
	v_mul_f32_e32 v63, v63, v251
	v_cvt_pk_bf16_f32 v63, v63, v129
	global_store_short v[74:75], v63, off offset:1536
	v_cvt_f32_f16_e32 v246, v188
	v_cvt_f32_f16_e32 v247, v189
	v_mul_f32_e32 v248, 0xbfb8aa3b, v246
	v_exp_f32_e32 v248, v248
	v_add_f32_e32 v59, v59, v197
	v_add_f32_e32 v248, 1.0, v248
	v_div_scale_f32 v249, s[38:39], v248, v248, v246
	v_rcp_f32_e32 v250, v249
	v_mul_f32_e32 v59, v59, v247
	v_div_scale_f32 v251, vcc, v246, v248, v246
	v_fma_f32 v252, -v249, v250, 1.0
	v_fmac_f32_e32 v250, v252, v250
	v_mul_f32_e32 v252, v251, v250
	v_fma_f32 v253, -v249, v252, v251
	v_fmac_f32_e32 v252, v253, v250
	v_fma_f32 v251, -v249, v252, v251
	v_div_fmas_f32 v251, v251, v250, v252
	v_div_fixup_f32 v251, v251, v248, v246
	v_mul_f32_e32 v59, v59, v251
	v_cvt_pk_bf16_f32 v59, v59, v129
	global_store_short v[74:75], v59, off offset:1568
	v_cvt_f32_f16_e32 v246, v190
	v_cvt_f32_f16_e32 v247, v191
	v_mul_f32_e32 v248, 0xbfb8aa3b, v246
	v_exp_f32_e32 v248, v248
	v_add_f32_e32 v55, v55, v197
	v_add_f32_e32 v248, 1.0, v248
	v_div_scale_f32 v249, s[38:39], v248, v248, v246
	v_rcp_f32_e32 v250, v249
	v_mul_f32_e32 v55, v55, v247
	v_div_scale_f32 v251, vcc, v246, v248, v246
	v_fma_f32 v252, -v249, v250, 1.0
	v_fmac_f32_e32 v250, v252, v250
	v_mul_f32_e32 v252, v251, v250
	v_fma_f32 v253, -v249, v252, v251
	v_fmac_f32_e32 v252, v253, v250
	v_fma_f32 v251, -v249, v252, v251
	v_div_fmas_f32 v251, v251, v250, v252
	v_div_fixup_f32 v251, v251, v248, v246
	v_mul_f32_e32 v55, v55, v251
	v_cvt_pk_bf16_f32 v55, v55, v129
	global_store_short v[74:75], v55, off offset:1600
	v_cvt_f32_f16_e32 v246, v192
	v_cvt_f32_f16_e32 v247, v193
	v_mul_f32_e32 v248, 0xbfb8aa3b, v246
	v_exp_f32_e32 v248, v248
	v_add_f32_e32 v51, v51, v197
	v_add_f32_e32 v248, 1.0, v248
	v_div_scale_f32 v249, s[38:39], v248, v248, v246
	v_rcp_f32_e32 v250, v249
	v_mul_f32_e32 v51, v51, v247
	v_div_scale_f32 v251, vcc, v246, v248, v246
	v_fma_f32 v252, -v249, v250, 1.0
	v_fmac_f32_e32 v250, v252, v250
	v_mul_f32_e32 v252, v251, v250
	v_fma_f32 v253, -v249, v252, v251
	v_fmac_f32_e32 v252, v253, v250
	v_fma_f32 v251, -v249, v252, v251
	v_div_fmas_f32 v251, v251, v250, v252
	v_div_fixup_f32 v251, v251, v248, v246
	v_mul_f32_e32 v51, v51, v251
	v_cvt_pk_bf16_f32 v51, v51, v129
	global_store_short v[74:75], v51, off offset:1632
	v_add_co_u32_e32 v238, vcc, 0x17800, v72
	s_nop 1
	v_addc_co_u32_e32 v239, vcc, 0, v73, vcc
	v_add_co_u32_e32 v240, vcc, 0x183c0, v72
	s_nop 1
	v_addc_co_u32_e32 v241, vcc, 0, v73, vcc
	v_add_co_u32_e32 v242, vcc, 0x18f80, v72
	s_nop 1
	v_addc_co_u32_e32 v243, vcc, 0, v73, vcc
	v_add_co_u32_e32 v244, vcc, 0x19b40, v72
	s_nop 1
	v_addc_co_u32_e32 v245, vcc, 0, v73, vcc
	global_load_ushort v162, v[238:239], off offset:2496
	global_load_ushort v163, v[238:239], off offset:1472
	global_load_ushort v164, v[238:239], off offset:2528
	global_load_ushort v165, v[238:239], off offset:1504
	global_load_ushort v166, v[238:239], off offset:2560
	global_load_ushort v167, v[238:239], off offset:1536
	global_load_ushort v168, v[238:239], off offset:2592
	global_load_ushort v169, v[238:239], off offset:1568
	global_load_ushort v170, v[240:241], off offset:2496
	global_load_ushort v171, v[240:241], off offset:1472
	global_load_ushort v172, v[240:241], off offset:2528
	global_load_ushort v173, v[240:241], off offset:1504
	global_load_ushort v174, v[240:241], off offset:2560
	global_load_ushort v175, v[240:241], off offset:1536
	global_load_ushort v176, v[240:241], off offset:2592
	global_load_ushort v177, v[240:241], off offset:1568
	global_load_ushort v178, v[242:243], off offset:2496
	global_load_ushort v179, v[242:243], off offset:1472
	global_load_ushort v180, v[242:243], off offset:2528
	global_load_ushort v181, v[242:243], off offset:1504
	global_load_ushort v182, v[242:243], off offset:2560
	global_load_ushort v183, v[242:243], off offset:1536
	global_load_ushort v184, v[242:243], off offset:2592
	global_load_ushort v185, v[242:243], off offset:1568
	global_load_ushort v186, v[244:245], off offset:2496
	global_load_ushort v187, v[244:245], off offset:1472
	global_load_ushort v188, v[244:245], off offset:2528
	global_load_ushort v189, v[244:245], off offset:1504
	global_load_ushort v190, v[244:245], off offset:2560
	global_load_ushort v191, v[244:245], off offset:1536
	global_load_ushort v192, v[244:245], off offset:2592
	global_load_ushort v193, v[244:245], off offset:1568
	global_load_dword v194, v[66:67], off offset:128
	global_load_dword v195, v[66:67], off offset:132
	global_load_dword v196, v[66:67], off offset:136
	global_load_dword v197, v[66:67], off offset:140
	s_waitcnt vmcnt(52)
; DEVI u16 f2bf(float f) { return (u16)(cvtpk(f, 0.f) & 0xffffu); }
; DEVI float siluf_(float x) { return x / (1.f + __expf(-x)); }
; DEVI void prepSGU_tile(const Params& p, int l, int g, int tile, char* lds) {
;     ...
; #pragma unroll
;         for (int nb = 0; nb < 4; ++nb) {
;           int c = gi * 64 + nb * 16 + l15;
;           float u = (float)zr[736 + c], gc = (float)zr[1248 + c];
;           Yc[(size_t)(t0 + pp) * 256 + c] = f2bf(u * (acc[mb][nb][j] + bv) * siluf_(gc));
;         }
	v_or_b32_e32 v128, s0, v70
	v_or_b32_e32 v128, 16, v128
	v_lshlrev_b64 v[74:75], 9, v[128:129]
	v_lshl_add_u64 v[74:75], s[28:29], 0, v[74:75]
	v_lshl_add_u64 v[74:75], v[74:75], 0, v[64:65]
	v_cvt_f32_f16_e32 v246, v198
	v_cvt_f32_f16_e32 v247, v199
	v_mul_f32_e32 v248, 0xbfb8aa3b, v246
	v_exp_f32_e32 v248, v248
	v_add_f32_e32 v44, v44, v234
	v_add_f32_e32 v248, 1.0, v248
	v_div_scale_f32 v249, s[38:39], v248, v248, v246
	v_rcp_f32_e32 v250, v249
	v_mul_f32_e32 v44, v44, v247
	v_div_scale_f32 v251, vcc, v246, v248, v246
	v_fma_f32 v252, -v249, v250, 1.0
	v_fmac_f32_e32 v250, v252, v250
	v_mul_f32_e32 v252, v251, v250
	v_fma_f32 v253, -v249, v252, v251
	v_fmac_f32_e32 v252, v253, v250
	v_fma_f32 v251, -v249, v252, v251
	v_div_fmas_f32 v251, v251, v250, v252
	v_div_fixup_f32 v251, v251, v248, v246
	v_mul_f32_e32 v44, v44, v251
	v_cvt_pk_bf16_f32 v44, v44, v129
	global_store_short v[74:75], v44, off
	v_cvt_f32_f16_e32 v246, v200
	v_cvt_f32_f16_e32 v247, v201
	v_mul_f32_e32 v248, 0xbfb8aa3b, v246
	v_exp_f32_e32 v248, v248
	v_add_f32_e32 v40, v40, v234
	v_add_f32_e32 v248, 1.0, v248
	v_div_scale_f32 v249, s[38:39], v248, v248, v246
	v_rcp_f32_e32 v250, v249
	v_mul_f32_e32 v40, v40, v247
	v_div_scale_f32 v251, vcc, v246, v248, v246
	v_fma_f32 v252, -v249, v250, 1.0
	v_fmac_f32_e32 v250, v252, v250
	v_mul_f32_e32 v252, v251, v250
	v_fma_f32 v253, -v249, v252, v251
	v_fmac_f32_e32 v252, v253, v250
	v_fma_f32 v251, -v249, v252, v251
	v_div_fmas_f32 v251, v251, v250, v252
	v_div_fixup_f32 v251, v251, v248, v246
	v_mul_f32_e32 v40, v40, v251
	v_cvt_pk_bf16_f32 v40, v40, v129
	global_store_short v[74:75], v40, off offset:32
	v_cvt_f32_f16_e32 v246, v202
	v_cvt_f32_f16_e32 v247, v203
	v_mul_f32_e32 v248, 0xbfb8aa3b, v246
	v_exp_f32_e32 v248, v248
	v_add_f32_e32 v36, v36, v234
	v_add_f32_e32 v248, 1.0, v248
	v_div_scale_f32 v249, s[38:39], v248, v248, v246
	v_rcp_f32_e32 v250, v249
	v_mul_f32_e32 v36, v36, v247
	v_div_scale_f32 v251, vcc, v246, v248, v246
	v_fma_f32 v252, -v249, v250, 1.0
	v_fmac_f32_e32 v250, v252, v250
	v_mul_f32_e32 v252, v251, v250
	v_fma_f32 v253, -v249, v252, v251
	v_fmac_f32_e32 v252, v253, v250
	v_fma_f32 v251, -v249, v252, v251
	v_div_fmas_f32 v251, v251, v250, v252
	v_div_fixup_f32 v251, v251, v248, v246
	v_mul_f32_e32 v36, v36, v251
	v_cvt_pk_bf16_f32 v36, v36, v129
	global_store_short v[74:75], v36, off offset:64
	v_cvt_f32_f16_e32 v246, v204
	v_cvt_f32_f16_e32 v247, v205
	v_mul_f32_e32 v248, 0xbfb8aa3b, v246
	v_exp_f32_e32 v248, v248
	v_add_f32_e32 v32, v32, v234
	v_add_f32_e32 v248, 1.0, v248
	v_div_scale_f32 v249, s[38:39], v248, v248, v246
	v_rcp_f32_e32 v250, v249
	v_mul_f32_e32 v32, v32, v247
	v_div_scale_f32 v251, vcc, v246, v248, v246
	v_fma_f32 v252, -v249, v250, 1.0
	v_fmac_f32_e32 v250, v252, v250
	v_mul_f32_e32 v252, v251, v250
	v_fma_f32 v253, -v249, v252, v251
	v_fmac_f32_e32 v252, v253, v250
	v_fma_f32 v251, -v249, v252, v251
	v_div_fmas_f32 v251, v251, v250, v252
	v_div_fixup_f32 v251, v251, v248, v246
	v_mul_f32_e32 v32, v32, v251
	v_cvt_pk_bf16_f32 v32, v32, v129
	global_store_short v[74:75], v32, off offset:96
	v_cvt_f32_f16_e32 v246, v206
	v_cvt_f32_f16_e32 v247, v207
	v_mul_f32_e32 v248, 0xbfb8aa3b, v246
	v_exp_f32_e32 v248, v248
	v_add_f32_e32 v45, v45, v235
	v_add_f32_e32 v248, 1.0, v248
	v_div_scale_f32 v249, s[38:39], v248, v248, v246
	v_rcp_f32_e32 v250, v249
	v_mul_f32_e32 v45, v45, v247
	v_div_scale_f32 v251, vcc, v246, v248, v246
	v_fma_f32 v252, -v249, v250, 1.0
	v_fmac_f32_e32 v250, v252, v250
	v_mul_f32_e32 v252, v251, v250
	v_fma_f32 v253, -v249, v252, v251
	v_fmac_f32_e32 v252, v253, v250
	v_fma_f32 v251, -v249, v252, v251
	v_div_fmas_f32 v251, v251, v250, v252
	v_div_fixup_f32 v251, v251, v248, v246
	v_mul_f32_e32 v45, v45, v251
	v_cvt_pk_bf16_f32 v45, v45, v129
	global_store_short v[74:75], v45, off offset:512
	v_cvt_f32_f16_e32 v246, v208
	v_cvt_f32_f16_e32 v247, v209
	v_mul_f32_e32 v248, 0xbfb8aa3b, v246
	v_exp_f32_e32 v248, v248
	v_add_f32_e32 v41, v41, v235
	v_add_f32_e32 v248, 1.0, v248
	v_div_scale_f32 v249, s[38:39], v248, v248, v246
	v_rcp_f32_e32 v250, v249
	v_mul_f32_e32 v41, v41, v247
	v_div_scale_f32 v251, vcc, v246, v248, v246
	v_fma_f32 v252, -v249, v250, 1.0
	v_fmac_f32_e32 v250, v252, v250
	v_mul_f32_e32 v252, v251, v250
	v_fma_f32 v253, -v249, v252, v251
	v_fmac_f32_e32 v252, v253, v250
	v_fma_f32 v251, -v249, v252, v251
	v_div_fmas_f32 v251, v251, v250, v252
	v_div_fixup_f32 v251, v251, v248, v246
	v_mul_f32_e32 v41, v41, v251
	v_cvt_pk_bf16_f32 v41, v41, v129
	global_store_short v[74:75], v41, off offset:544
	v_cvt_f32_f16_e32 v246, v210
	v_cvt_f32_f16_e32 v247, v211
	v_mul_f32_e32 v248, 0xbfb8aa3b, v246
	v_exp_f32_e32 v248, v248
	v_add_f32_e32 v37, v37, v235
	v_add_f32_e32 v248, 1.0, v248
	v_div_scale_f32 v249, s[38:39], v248, v248, v246
	v_rcp_f32_e32 v250, v249
	v_mul_f32_e32 v37, v37, v247
	v_div_scale_f32 v251, vcc, v246, v248, v246
	v_fma_f32 v252, -v249, v250, 1.0
	v_fmac_f32_e32 v250, v252, v250
	v_mul_f32_e32 v252, v251, v250
	v_fma_f32 v253, -v249, v252, v251
	v_fmac_f32_e32 v252, v253, v250
	v_fma_f32 v251, -v249, v252, v251
	v_div_fmas_f32 v251, v251, v250, v252
	v_div_fixup_f32 v251, v251, v248, v246
	v_mul_f32_e32 v37, v37, v251
	v_cvt_pk_bf16_f32 v37, v37, v129
	global_store_short v[74:75], v37, off offset:576
	v_cvt_f32_f16_e32 v246, v212
	v_cvt_f32_f16_e32 v247, v213
	v_mul_f32_e32 v248, 0xbfb8aa3b, v246
	v_exp_f32_e32 v248, v248
	v_add_f32_e32 v33, v33, v235
	v_add_f32_e32 v248, 1.0, v248
	v_div_scale_f32 v249, s[38:39], v248, v248, v246
	v_rcp_f32_e32 v250, v249
	v_mul_f32_e32 v33, v33, v247
	v_div_scale_f32 v251, vcc, v246, v248, v246
; DEVI u16 f2bf(float f) { return (u16)(cvtpk(f, 0.f) & 0xffffu); }
; DEVI float siluf_(float x) { return x / (1.f + __expf(-x)); }
; DEVI void prepSGU_tile(const Params& p, int l, int g, int tile, char* lds) {
;     ...
; #pragma unroll
;         for (int nb = 0; nb < 4; ++nb) {
;           int c = gi * 64 + nb * 16 + l15;
;           float u = (float)zr[736 + c], gc = (float)zr[1248 + c];
;           Yc[(size_t)(t0 + pp) * 256 + c] = f2bf(u * (acc[mb][nb][j] + bv) * siluf_(gc));
;         }
	v_fma_f32 v252, -v249, v250, 1.0
	v_fmac_f32_e32 v250, v252, v250
	v_mul_f32_e32 v252, v251, v250
	v_fma_f32 v253, -v249, v252, v251
	v_fmac_f32_e32 v252, v253, v250
	v_fma_f32 v251, -v249, v252, v251
	v_div_fmas_f32 v251, v251, v250, v252
	v_div_fixup_f32 v251, v251, v248, v246
	v_mul_f32_e32 v33, v33, v251
	v_cvt_pk_bf16_f32 v33, v33, v129
	global_store_short v[74:75], v33, off offset:608
	v_cvt_f32_f16_e32 v246, v214
	v_cvt_f32_f16_e32 v247, v215
	v_mul_f32_e32 v248, 0xbfb8aa3b, v246
	v_exp_f32_e32 v248, v248
	v_add_f32_e32 v46, v46, v236
	v_add_f32_e32 v248, 1.0, v248
	v_div_scale_f32 v249, s[38:39], v248, v248, v246
	v_rcp_f32_e32 v250, v249
	v_mul_f32_e32 v46, v46, v247
	v_div_scale_f32 v251, vcc, v246, v248, v246
	v_fma_f32 v252, -v249, v250, 1.0
	v_fmac_f32_e32 v250, v252, v250
	v_mul_f32_e32 v252, v251, v250
	v_fma_f32 v253, -v249, v252, v251
	v_fmac_f32_e32 v252, v253, v250
	v_fma_f32 v251, -v249, v252, v251
	v_div_fmas_f32 v251, v251, v250, v252
	v_div_fixup_f32 v251, v251, v248, v246
	v_mul_f32_e32 v46, v46, v251
	v_cvt_pk_bf16_f32 v46, v46, v129
	global_store_short v[74:75], v46, off offset:1024
	v_cvt_f32_f16_e32 v246, v216
	v_cvt_f32_f16_e32 v247, v217
	v_mul_f32_e32 v248, 0xbfb8aa3b, v246
	v_exp_f32_e32 v248, v248
	v_add_f32_e32 v42, v42, v236
	v_add_f32_e32 v248, 1.0, v248
	v_div_scale_f32 v249, s[38:39], v248, v248, v246
	v_rcp_f32_e32 v250, v249
	v_mul_f32_e32 v42, v42, v247
	v_div_scale_f32 v251, vcc, v246, v248, v246
	v_fma_f32 v252, -v249, v250, 1.0
	v_fmac_f32_e32 v250, v252, v250
	v_mul_f32_e32 v252, v251, v250
	v_fma_f32 v253, -v249, v252, v251
	v_fmac_f32_e32 v252, v253, v250
	v_fma_f32 v251, -v249, v252, v251
	v_div_fmas_f32 v251, v251, v250, v252
	v_div_fixup_f32 v251, v251, v248, v246
	v_mul_f32_e32 v42, v42, v251
	v_cvt_pk_bf16_f32 v42, v42, v129
	global_store_short v[74:75], v42, off offset:1056
	v_cvt_f32_f16_e32 v246, v222
	v_cvt_f32_f16_e32 v247, v223
	v_mul_f32_e32 v248, 0xbfb8aa3b, v246
	v_exp_f32_e32 v248, v248
	v_add_f32_e32 v38, v38, v236
	v_add_f32_e32 v248, 1.0, v248
	v_div_scale_f32 v249, s[38:39], v248, v248, v246
	v_rcp_f32_e32 v250, v249
	v_mul_f32_e32 v38, v38, v247
	v_div_scale_f32 v251, vcc, v246, v248, v246
	v_fma_f32 v252, -v249, v250, 1.0
	v_fmac_f32_e32 v250, v252, v250
	v_mul_f32_e32 v252, v251, v250
	v_fma_f32 v253, -v249, v252, v251
	v_fmac_f32_e32 v252, v253, v250
	v_fma_f32 v251, -v249, v252, v251
	v_div_fmas_f32 v251, v251, v250, v252
	v_div_fixup_f32 v251, v251, v248, v246
	v_mul_f32_e32 v38, v38, v251
	v_cvt_pk_bf16_f32 v38, v38, v129
	global_store_short v[74:75], v38, off offset:1088
	v_cvt_f32_f16_e32 v246, v224
	v_cvt_f32_f16_e32 v247, v225
	v_mul_f32_e32 v248, 0xbfb8aa3b, v246
	v_exp_f32_e32 v248, v248
	v_add_f32_e32 v34, v34, v236
	v_add_f32_e32 v248, 1.0, v248
	v_div_scale_f32 v249, s[38:39], v248, v248, v246
	v_rcp_f32_e32 v250, v249
	v_mul_f32_e32 v34, v34, v247
	v_div_scale_f32 v251, vcc, v246, v248, v246
	v_fma_f32 v252, -v249, v250, 1.0
	v_fmac_f32_e32 v250, v252, v250
	v_mul_f32_e32 v252, v251, v250
	v_fma_f32 v253, -v249, v252, v251
	v_fmac_f32_e32 v252, v253, v250
	v_fma_f32 v251, -v249, v252, v251
	v_div_fmas_f32 v251, v251, v250, v252
	v_div_fixup_f32 v251, v251, v248, v246
	v_mul_f32_e32 v34, v34, v251
	v_cvt_pk_bf16_f32 v34, v34, v129
	global_store_short v[74:75], v34, off offset:1120
	v_cvt_f32_f16_e32 v246, v226
	v_cvt_f32_f16_e32 v247, v227
	v_mul_f32_e32 v248, 0xbfb8aa3b, v246
	v_exp_f32_e32 v248, v248
	v_add_f32_e32 v47, v47, v237
	v_add_f32_e32 v248, 1.0, v248
	v_div_scale_f32 v249, s[38:39], v248, v248, v246
	v_rcp_f32_e32 v250, v249
	v_mul_f32_e32 v47, v47, v247
	v_div_scale_f32 v251, vcc, v246, v248, v246
	v_fma_f32 v252, -v249, v250, 1.0
	v_fmac_f32_e32 v250, v252, v250
	v_mul_f32_e32 v252, v251, v250
	v_fma_f32 v253, -v249, v252, v251
	v_fmac_f32_e32 v252, v253, v250
	v_fma_f32 v251, -v249, v252, v251
	v_div_fmas_f32 v251, v251, v250, v252
	v_div_fixup_f32 v251, v251, v248, v246
	v_mul_f32_e32 v47, v47, v251
	v_cvt_pk_bf16_f32 v47, v47, v129
	global_store_short v[74:75], v47, off offset:1536
	v_cvt_f32_f16_e32 v246, v228
	v_cvt_f32_f16_e32 v247, v229
	v_mul_f32_e32 v248, 0xbfb8aa3b, v246
	v_exp_f32_e32 v248, v248
	v_add_f32_e32 v43, v43, v237
	v_add_f32_e32 v248, 1.0, v248
	v_div_scale_f32 v249, s[38:39], v248, v248, v246
	v_rcp_f32_e32 v250, v249
	v_mul_f32_e32 v43, v43, v247
	v_div_scale_f32 v251, vcc, v246, v248, v246
	v_fma_f32 v252, -v249, v250, 1.0
	v_fmac_f32_e32 v250, v252, v250
	v_mul_f32_e32 v252, v251, v250
	v_fma_f32 v253, -v249, v252, v251
	v_fmac_f32_e32 v252, v253, v250
	v_fma_f32 v251, -v249, v252, v251
	v_div_fmas_f32 v251, v251, v250, v252
	v_div_fixup_f32 v251, v251, v248, v246
	v_mul_f32_e32 v43, v43, v251
	v_cvt_pk_bf16_f32 v43, v43, v129
	global_store_short v[74:75], v43, off offset:1568
	v_cvt_f32_f16_e32 v246, v230
	v_cvt_f32_f16_e32 v247, v231
	v_mul_f32_e32 v248, 0xbfb8aa3b, v246
	v_exp_f32_e32 v248, v248
	v_add_f32_e32 v39, v39, v237
	v_add_f32_e32 v248, 1.0, v248
	v_div_scale_f32 v249, s[38:39], v248, v248, v246
	v_rcp_f32_e32 v250, v249
	v_mul_f32_e32 v39, v39, v247
	v_div_scale_f32 v251, vcc, v246, v248, v246
	v_fma_f32 v252, -v249, v250, 1.0
	v_fmac_f32_e32 v250, v252, v250
	v_mul_f32_e32 v252, v251, v250
	v_fma_f32 v253, -v249, v252, v251
	v_fmac_f32_e32 v252, v253, v250
	v_fma_f32 v251, -v249, v252, v251
	v_div_fmas_f32 v251, v251, v250, v252
	v_div_fixup_f32 v251, v251, v248, v246
	v_mul_f32_e32 v39, v39, v251
	v_cvt_pk_bf16_f32 v39, v39, v129
	global_store_short v[74:75], v39, off offset:1600
	v_cvt_f32_f16_e32 v246, v232
	v_cvt_f32_f16_e32 v247, v233
	v_mul_f32_e32 v248, 0xbfb8aa3b, v246
	v_exp_f32_e32 v248, v248
; DEVI u16 f2bf(float f) { return (u16)(cvtpk(f, 0.f) & 0xffffu); }
; DEVI float siluf_(float x) { return x / (1.f + __expf(-x)); }
; DEVI void prepSGU_tile(const Params& p, int l, int g, int tile, char* lds) {
;     ...
; #pragma unroll
;         for (int nb = 0; nb < 4; ++nb) {
;           int c = gi * 64 + nb * 16 + l15;
;           float u = (float)zr[736 + c], gc = (float)zr[1248 + c];
;           Yc[(size_t)(t0 + pp) * 256 + c] = f2bf(u * (acc[mb][nb][j] + bv) * siluf_(gc));
;         }
	v_add_f32_e32 v35, v35, v237
	v_add_f32_e32 v248, 1.0, v248
	v_div_scale_f32 v249, s[38:39], v248, v248, v246
	v_rcp_f32_e32 v250, v249
	v_mul_f32_e32 v35, v35, v247
	v_div_scale_f32 v251, vcc, v246, v248, v246
	v_fma_f32 v252, -v249, v250, 1.0
	v_fmac_f32_e32 v250, v252, v250
	v_mul_f32_e32 v252, v251, v250
	v_fma_f32 v253, -v249, v252, v251
	v_fmac_f32_e32 v252, v253, v250
	v_fma_f32 v251, -v249, v252, v251
	v_div_fmas_f32 v251, v251, v250, v252
	v_div_fixup_f32 v251, v251, v248, v246
	v_mul_f32_e32 v35, v35, v251
	v_cvt_pk_bf16_f32 v35, v35, v129
	global_store_short v[74:75], v35, off offset:1632
	v_add_co_u32_e32 v238, vcc, 0x23400, v72
	s_nop 1
	v_addc_co_u32_e32 v239, vcc, 0, v73, vcc
	v_add_co_u32_e32 v240, vcc, 0x23fc0, v72
	s_nop 1
	v_addc_co_u32_e32 v241, vcc, 0, v73, vcc
	v_add_co_u32_e32 v242, vcc, 0x24b80, v72
	s_nop 1
	v_addc_co_u32_e32 v243, vcc, 0, v73, vcc
	v_add_co_u32_e32 v244, vcc, 0x25740, v72
	s_nop 1
	v_addc_co_u32_e32 v245, vcc, 0, v73, vcc
	global_load_ushort v198, v[238:239], off offset:2496
	global_load_ushort v199, v[238:239], off offset:1472
	global_load_ushort v200, v[238:239], off offset:2528
	global_load_ushort v201, v[238:239], off offset:1504
	global_load_ushort v202, v[238:239], off offset:2560
	global_load_ushort v203, v[238:239], off offset:1536
	global_load_ushort v204, v[238:239], off offset:2592
	global_load_ushort v205, v[238:239], off offset:1568
	global_load_ushort v206, v[240:241], off offset:2496
	global_load_ushort v207, v[240:241], off offset:1472
	global_load_ushort v208, v[240:241], off offset:2528
	global_load_ushort v209, v[240:241], off offset:1504
	global_load_ushort v210, v[240:241], off offset:2560
	global_load_ushort v211, v[240:241], off offset:1536
	global_load_ushort v212, v[240:241], off offset:2592
	global_load_ushort v213, v[240:241], off offset:1568
	global_load_ushort v214, v[242:243], off offset:2496
	global_load_ushort v215, v[242:243], off offset:1472
	global_load_ushort v216, v[242:243], off offset:2528
	global_load_ushort v217, v[242:243], off offset:1504
	global_load_ushort v222, v[242:243], off offset:2560
	global_load_ushort v223, v[242:243], off offset:1536
	global_load_ushort v224, v[242:243], off offset:2592
	global_load_ushort v225, v[242:243], off offset:1568
	global_load_ushort v226, v[244:245], off offset:2496
	global_load_ushort v227, v[244:245], off offset:1472
	global_load_ushort v228, v[244:245], off offset:2528
	global_load_ushort v229, v[244:245], off offset:1504
	global_load_ushort v230, v[244:245], off offset:2560
	global_load_ushort v231, v[244:245], off offset:1536
	global_load_ushort v232, v[244:245], off offset:2592
	global_load_ushort v233, v[244:245], off offset:1568
	global_load_dword v234, v[66:67], off offset:192
	global_load_dword v235, v[66:67], off offset:196
	global_load_dword v236, v[66:67], off offset:200
	global_load_dword v237, v[66:67], off offset:204
	s_waitcnt vmcnt(52)
	v_or_b32_e32 v128, s0, v70
	v_or_b32_e32 v128, 32, v128
	v_lshlrev_b64 v[74:75], 9, v[128:129]
	v_lshl_add_u64 v[74:75], s[28:29], 0, v[74:75]
	v_lshl_add_u64 v[74:75], v[74:75], 0, v[64:65]
	v_cvt_f32_f16_e32 v246, v162
	v_cvt_f32_f16_e32 v247, v163
	v_mul_f32_e32 v248, 0xbfb8aa3b, v246
	v_exp_f32_e32 v248, v248
	v_add_f32_e32 v28, v28, v194
	v_add_f32_e32 v248, 1.0, v248
	v_div_scale_f32 v249, s[38:39], v248, v248, v246
	v_rcp_f32_e32 v250, v249
	v_mul_f32_e32 v28, v28, v247
	v_div_scale_f32 v251, vcc, v246, v248, v246
	v_fma_f32 v252, -v249, v250, 1.0
	v_fmac_f32_e32 v250, v252, v250
	v_mul_f32_e32 v252, v251, v250
	v_fma_f32 v253, -v249, v252, v251
	v_fmac_f32_e32 v252, v253, v250
	v_fma_f32 v251, -v249, v252, v251
	v_div_fmas_f32 v251, v251, v250, v252
	v_div_fixup_f32 v251, v251, v248, v246
	v_mul_f32_e32 v28, v28, v251
	v_cvt_pk_bf16_f32 v28, v28, v129
	global_store_short v[74:75], v28, off
	v_cvt_f32_f16_e32 v246, v164
	v_cvt_f32_f16_e32 v247, v165
	v_mul_f32_e32 v248, 0xbfb8aa3b, v246
	v_exp_f32_e32 v248, v248
	v_add_f32_e32 v24, v24, v194
	v_add_f32_e32 v248, 1.0, v248
	v_div_scale_f32 v249, s[38:39], v248, v248, v246
	v_rcp_f32_e32 v250, v249
	v_mul_f32_e32 v24, v24, v247
	v_div_scale_f32 v251, vcc, v246, v248, v246
	v_fma_f32 v252, -v249, v250, 1.0
	v_fmac_f32_e32 v250, v252, v250
	v_mul_f32_e32 v252, v251, v250
	v_fma_f32 v253, -v249, v252, v251
	v_fmac_f32_e32 v252, v253, v250
	v_fma_f32 v251, -v249, v252, v251
	v_div_fmas_f32 v251, v251, v250, v252
	v_div_fixup_f32 v251, v251, v248, v246
	v_mul_f32_e32 v24, v24, v251
	v_cvt_pk_bf16_f32 v24, v24, v129
	global_store_short v[74:75], v24, off offset:32
	v_cvt_f32_f16_e32 v246, v166
	v_cvt_f32_f16_e32 v247, v167
	v_mul_f32_e32 v248, 0xbfb8aa3b, v246
	v_exp_f32_e32 v248, v248
	v_add_f32_e32 v20, v20, v194
	v_add_f32_e32 v248, 1.0, v248
	v_div_scale_f32 v249, s[38:39], v248, v248, v246
	v_rcp_f32_e32 v250, v249
	v_mul_f32_e32 v20, v20, v247
	v_div_scale_f32 v251, vcc, v246, v248, v246
	v_fma_f32 v252, -v249, v250, 1.0
	v_fmac_f32_e32 v250, v252, v250
	v_mul_f32_e32 v252, v251, v250
	v_fma_f32 v253, -v249, v252, v251
	v_fmac_f32_e32 v252, v253, v250
	v_fma_f32 v251, -v249, v252, v251
	v_div_fmas_f32 v251, v251, v250, v252
	v_div_fixup_f32 v251, v251, v248, v246
	v_mul_f32_e32 v20, v20, v251
	v_cvt_pk_bf16_f32 v20, v20, v129
	global_store_short v[74:75], v20, off offset:64
	v_cvt_f32_f16_e32 v246, v168
	v_cvt_f32_f16_e32 v247, v169
	v_mul_f32_e32 v248, 0xbfb8aa3b, v246
	v_exp_f32_e32 v248, v248
	v_add_f32_e32 v16, v16, v194
	v_add_f32_e32 v248, 1.0, v248
	v_div_scale_f32 v249, s[38:39], v248, v248, v246
	v_rcp_f32_e32 v250, v249
	v_mul_f32_e32 v16, v16, v247
	v_div_scale_f32 v251, vcc, v246, v248, v246
; DEVI u16 f2bf(float f) { return (u16)(cvtpk(f, 0.f) & 0xffffu); }
; DEVI float siluf_(float x) { return x / (1.f + __expf(-x)); }
; DEVI void prepSGU_tile(const Params& p, int l, int g, int tile, char* lds) {
;     ...
; #pragma unroll
;         for (int nb = 0; nb < 4; ++nb) {
;           int c = gi * 64 + nb * 16 + l15;
;           float u = (float)zr[736 + c], gc = (float)zr[1248 + c];
;           Yc[(size_t)(t0 + pp) * 256 + c] = f2bf(u * (acc[mb][nb][j] + bv) * siluf_(gc));
;         }
	v_fma_f32 v252, -v249, v250, 1.0
	v_fmac_f32_e32 v250, v252, v250
	v_mul_f32_e32 v252, v251, v250
	v_fma_f32 v253, -v249, v252, v251
	v_fmac_f32_e32 v252, v253, v250
	v_fma_f32 v251, -v249, v252, v251
	v_div_fmas_f32 v251, v251, v250, v252
	v_div_fixup_f32 v251, v251, v248, v246
	v_mul_f32_e32 v16, v16, v251
	v_cvt_pk_bf16_f32 v16, v16, v129
	global_store_short v[74:75], v16, off offset:96
	v_cvt_f32_f16_e32 v246, v170
	v_cvt_f32_f16_e32 v247, v171
	v_mul_f32_e32 v248, 0xbfb8aa3b, v246
	v_exp_f32_e32 v248, v248
	v_add_f32_e32 v29, v29, v195
	v_add_f32_e32 v248, 1.0, v248
	v_div_scale_f32 v249, s[38:39], v248, v248, v246
	v_rcp_f32_e32 v250, v249
	v_mul_f32_e32 v29, v29, v247
	v_div_scale_f32 v251, vcc, v246, v248, v246
	v_fma_f32 v252, -v249, v250, 1.0
	v_fmac_f32_e32 v250, v252, v250
	v_mul_f32_e32 v252, v251, v250
	v_fma_f32 v253, -v249, v252, v251
	v_fmac_f32_e32 v252, v253, v250
	v_fma_f32 v251, -v249, v252, v251
	v_div_fmas_f32 v251, v251, v250, v252
	v_div_fixup_f32 v251, v251, v248, v246
	v_mul_f32_e32 v29, v29, v251
	v_cvt_pk_bf16_f32 v29, v29, v129
	global_store_short v[74:75], v29, off offset:512
	v_cvt_f32_f16_e32 v246, v172
	v_cvt_f32_f16_e32 v247, v173
	v_mul_f32_e32 v248, 0xbfb8aa3b, v246
	v_exp_f32_e32 v248, v248
	v_add_f32_e32 v25, v25, v195
	v_add_f32_e32 v248, 1.0, v248
	v_div_scale_f32 v249, s[38:39], v248, v248, v246
	v_rcp_f32_e32 v250, v249
	v_mul_f32_e32 v25, v25, v247
	v_div_scale_f32 v251, vcc, v246, v248, v246
	v_fma_f32 v252, -v249, v250, 1.0
	v_fmac_f32_e32 v250, v252, v250
	v_mul_f32_e32 v252, v251, v250
	v_fma_f32 v253, -v249, v252, v251
	v_fmac_f32_e32 v252, v253, v250
	v_fma_f32 v251, -v249, v252, v251
	v_div_fmas_f32 v251, v251, v250, v252
	v_div_fixup_f32 v251, v251, v248, v246
	v_mul_f32_e32 v25, v25, v251
	v_cvt_pk_bf16_f32 v25, v25, v129
	global_store_short v[74:75], v25, off offset:544
	v_cvt_f32_f16_e32 v246, v174
	v_cvt_f32_f16_e32 v247, v175
	v_mul_f32_e32 v248, 0xbfb8aa3b, v246
	v_exp_f32_e32 v248, v248
	v_add_f32_e32 v21, v21, v195
	v_add_f32_e32 v248, 1.0, v248
	v_div_scale_f32 v249, s[38:39], v248, v248, v246
	v_rcp_f32_e32 v250, v249
	v_mul_f32_e32 v21, v21, v247
	v_div_scale_f32 v251, vcc, v246, v248, v246
	v_fma_f32 v252, -v249, v250, 1.0
	v_fmac_f32_e32 v250, v252, v250
	v_mul_f32_e32 v252, v251, v250
	v_fma_f32 v253, -v249, v252, v251
	v_fmac_f32_e32 v252, v253, v250
	v_fma_f32 v251, -v249, v252, v251
	v_div_fmas_f32 v251, v251, v250, v252
	v_div_fixup_f32 v251, v251, v248, v246
	v_mul_f32_e32 v21, v21, v251
	v_cvt_pk_bf16_f32 v21, v21, v129
	global_store_short v[74:75], v21, off offset:576
	v_cvt_f32_f16_e32 v246, v176
	v_cvt_f32_f16_e32 v247, v177
	v_mul_f32_e32 v248, 0xbfb8aa3b, v246
	v_exp_f32_e32 v248, v248
	v_add_f32_e32 v17, v17, v195
	v_add_f32_e32 v248, 1.0, v248
	v_div_scale_f32 v249, s[38:39], v248, v248, v246
	v_rcp_f32_e32 v250, v249
	v_mul_f32_e32 v17, v17, v247
	v_div_scale_f32 v251, vcc, v246, v248, v246
	v_fma_f32 v252, -v249, v250, 1.0
	v_fmac_f32_e32 v250, v252, v250
	v_mul_f32_e32 v252, v251, v250
	v_fma_f32 v253, -v249, v252, v251
	v_fmac_f32_e32 v252, v253, v250
	v_fma_f32 v251, -v249, v252, v251
	v_div_fmas_f32 v251, v251, v250, v252
	v_div_fixup_f32 v251, v251, v248, v246
	v_mul_f32_e32 v17, v17, v251
	v_cvt_pk_bf16_f32 v17, v17, v129
	global_store_short v[74:75], v17, off offset:608
	v_cvt_f32_f16_e32 v246, v178
	v_cvt_f32_f16_e32 v247, v179
	v_mul_f32_e32 v248, 0xbfb8aa3b, v246
	v_exp_f32_e32 v248, v248
	v_add_f32_e32 v30, v30, v196
	v_add_f32_e32 v248, 1.0, v248
	v_div_scale_f32 v249, s[38:39], v248, v248, v246
	v_rcp_f32_e32 v250, v249
	v_mul_f32_e32 v30, v30, v247
	v_div_scale_f32 v251, vcc, v246, v248, v246
	v_fma_f32 v252, -v249, v250, 1.0
	v_fmac_f32_e32 v250, v252, v250
	v_mul_f32_e32 v252, v251, v250
	v_fma_f32 v253, -v249, v252, v251
	v_fmac_f32_e32 v252, v253, v250
	v_fma_f32 v251, -v249, v252, v251
	v_div_fmas_f32 v251, v251, v250, v252
	v_div_fixup_f32 v251, v251, v248, v246
	v_mul_f32_e32 v30, v30, v251
	v_cvt_pk_bf16_f32 v30, v30, v129
	global_store_short v[74:75], v30, off offset:1024
	v_cvt_f32_f16_e32 v246, v180
	v_cvt_f32_f16_e32 v247, v181
	v_mul_f32_e32 v248, 0xbfb8aa3b, v246
	v_exp_f32_e32 v248, v248
	v_add_f32_e32 v26, v26, v196
	v_add_f32_e32 v248, 1.0, v248
	v_div_scale_f32 v249, s[38:39], v248, v248, v246
	v_rcp_f32_e32 v250, v249
	v_mul_f32_e32 v26, v26, v247
	v_div_scale_f32 v251, vcc, v246, v248, v246
	v_fma_f32 v252, -v249, v250, 1.0
	v_fmac_f32_e32 v250, v252, v250
	v_mul_f32_e32 v252, v251, v250
	v_fma_f32 v253, -v249, v252, v251
	v_fmac_f32_e32 v252, v253, v250
	v_fma_f32 v251, -v249, v252, v251
	v_div_fmas_f32 v251, v251, v250, v252
	v_div_fixup_f32 v251, v251, v248, v246
	v_mul_f32_e32 v26, v26, v251
	v_cvt_pk_bf16_f32 v26, v26, v129
	global_store_short v[74:75], v26, off offset:1056
	v_cvt_f32_f16_e32 v246, v182
	v_cvt_f32_f16_e32 v247, v183
	v_mul_f32_e32 v248, 0xbfb8aa3b, v246
	v_exp_f32_e32 v248, v248
	v_add_f32_e32 v22, v22, v196
	v_add_f32_e32 v248, 1.0, v248
	v_div_scale_f32 v249, s[38:39], v248, v248, v246
	v_rcp_f32_e32 v250, v249
	v_mul_f32_e32 v22, v22, v247
	v_div_scale_f32 v251, vcc, v246, v248, v246
	v_fma_f32 v252, -v249, v250, 1.0
	v_fmac_f32_e32 v250, v252, v250
	v_mul_f32_e32 v252, v251, v250
	v_fma_f32 v253, -v249, v252, v251
	v_fmac_f32_e32 v252, v253, v250
	v_fma_f32 v251, -v249, v252, v251
	v_div_fmas_f32 v251, v251, v250, v252
	v_div_fixup_f32 v251, v251, v248, v246
	v_mul_f32_e32 v22, v22, v251
	v_cvt_pk_bf16_f32 v22, v22, v129
	global_store_short v[74:75], v22, off offset:1088
	v_cvt_f32_f16_e32 v246, v184
	v_cvt_f32_f16_e32 v247, v185
	v_mul_f32_e32 v248, 0xbfb8aa3b, v246
	v_exp_f32_e32 v248, v248
; DEVI u16 f2bf(float f) { return (u16)(cvtpk(f, 0.f) & 0xffffu); }
; DEVI float siluf_(float x) { return x / (1.f + __expf(-x)); }
; DEVI void prepSGU_tile(const Params& p, int l, int g, int tile, char* lds) {
;     ...
; #pragma unroll
;         for (int nb = 0; nb < 4; ++nb) {
;           int c = gi * 64 + nb * 16 + l15;
;           float u = (float)zr[736 + c], gc = (float)zr[1248 + c];
;           Yc[(size_t)(t0 + pp) * 256 + c] = f2bf(u * (acc[mb][nb][j] + bv) * siluf_(gc));
;         }
	v_add_f32_e32 v18, v18, v196
	v_add_f32_e32 v248, 1.0, v248
	v_div_scale_f32 v249, s[38:39], v248, v248, v246
	v_rcp_f32_e32 v250, v249
	v_mul_f32_e32 v18, v18, v247
	v_div_scale_f32 v251, vcc, v246, v248, v246
	v_fma_f32 v252, -v249, v250, 1.0
	v_fmac_f32_e32 v250, v252, v250
	v_mul_f32_e32 v252, v251, v250
	v_fma_f32 v253, -v249, v252, v251
	v_fmac_f32_e32 v252, v253, v250
	v_fma_f32 v251, -v249, v252, v251
	v_div_fmas_f32 v251, v251, v250, v252
	v_div_fixup_f32 v251, v251, v248, v246
	v_mul_f32_e32 v18, v18, v251
	v_cvt_pk_bf16_f32 v18, v18, v129
	global_store_short v[74:75], v18, off offset:1120
	v_cvt_f32_f16_e32 v246, v186
	v_cvt_f32_f16_e32 v247, v187
	v_mul_f32_e32 v248, 0xbfb8aa3b, v246
	v_exp_f32_e32 v248, v248
	v_add_f32_e32 v31, v31, v197
	v_add_f32_e32 v248, 1.0, v248
	v_div_scale_f32 v249, s[38:39], v248, v248, v246
	v_rcp_f32_e32 v250, v249
	v_mul_f32_e32 v31, v31, v247
	v_div_scale_f32 v251, vcc, v246, v248, v246
	v_fma_f32 v252, -v249, v250, 1.0
	v_fmac_f32_e32 v250, v252, v250
	v_mul_f32_e32 v252, v251, v250
	v_fma_f32 v253, -v249, v252, v251
	v_fmac_f32_e32 v252, v253, v250
	v_fma_f32 v251, -v249, v252, v251
	v_div_fmas_f32 v251, v251, v250, v252
	v_div_fixup_f32 v251, v251, v248, v246
	v_mul_f32_e32 v31, v31, v251
	v_cvt_pk_bf16_f32 v31, v31, v129
	global_store_short v[74:75], v31, off offset:1536
	v_cvt_f32_f16_e32 v246, v188
	v_cvt_f32_f16_e32 v247, v189
	v_mul_f32_e32 v248, 0xbfb8aa3b, v246
	v_exp_f32_e32 v248, v248
	v_add_f32_e32 v27, v27, v197
	v_add_f32_e32 v248, 1.0, v248
	v_div_scale_f32 v249, s[38:39], v248, v248, v246
	v_rcp_f32_e32 v250, v249
	v_mul_f32_e32 v27, v27, v247
	v_div_scale_f32 v251, vcc, v246, v248, v246
	v_fma_f32 v252, -v249, v250, 1.0
	v_fmac_f32_e32 v250, v252, v250
	v_mul_f32_e32 v252, v251, v250
	v_fma_f32 v253, -v249, v252, v251
	v_fmac_f32_e32 v252, v253, v250
	v_fma_f32 v251, -v249, v252, v251
	v_div_fmas_f32 v251, v251, v250, v252
	v_div_fixup_f32 v251, v251, v248, v246
	v_mul_f32_e32 v27, v27, v251
	v_cvt_pk_bf16_f32 v27, v27, v129
	global_store_short v[74:75], v27, off offset:1568
	v_cvt_f32_f16_e32 v246, v190
	v_cvt_f32_f16_e32 v247, v191
	v_mul_f32_e32 v248, 0xbfb8aa3b, v246
	v_exp_f32_e32 v248, v248
	v_add_f32_e32 v23, v23, v197
	v_add_f32_e32 v248, 1.0, v248
	v_div_scale_f32 v249, s[38:39], v248, v248, v246
	v_rcp_f32_e32 v250, v249
	v_mul_f32_e32 v23, v23, v247
	v_div_scale_f32 v251, vcc, v246, v248, v246
	v_fma_f32 v252, -v249, v250, 1.0
	v_fmac_f32_e32 v250, v252, v250
	v_mul_f32_e32 v252, v251, v250
	v_fma_f32 v253, -v249, v252, v251
	v_fmac_f32_e32 v252, v253, v250
	v_fma_f32 v251, -v249, v252, v251
	v_div_fmas_f32 v251, v251, v250, v252
	v_div_fixup_f32 v251, v251, v248, v246
	v_mul_f32_e32 v23, v23, v251
	v_cvt_pk_bf16_f32 v23, v23, v129
	global_store_short v[74:75], v23, off offset:1600
	v_cvt_f32_f16_e32 v246, v192
	v_cvt_f32_f16_e32 v247, v193
	v_mul_f32_e32 v248, 0xbfb8aa3b, v246
	v_exp_f32_e32 v248, v248
	v_add_f32_e32 v19, v19, v197
	v_add_f32_e32 v248, 1.0, v248
	v_div_scale_f32 v249, s[38:39], v248, v248, v246
	v_rcp_f32_e32 v250, v249
	v_mul_f32_e32 v19, v19, v247
	v_div_scale_f32 v251, vcc, v246, v248, v246
	v_fma_f32 v252, -v249, v250, 1.0
	v_fmac_f32_e32 v250, v252, v250
	v_mul_f32_e32 v252, v251, v250
	v_fma_f32 v253, -v249, v252, v251
	v_fmac_f32_e32 v252, v253, v250
	v_fma_f32 v251, -v249, v252, v251
	v_div_fmas_f32 v251, v251, v250, v252
	v_div_fixup_f32 v251, v251, v248, v246
	v_mul_f32_e32 v19, v19, v251
	v_cvt_pk_bf16_f32 v19, v19, v129
	global_store_short v[74:75], v19, off offset:1632
	s_waitcnt vmcnt(16)
	v_or_b32_e32 v128, s0, v70
	v_or_b32_e32 v128, 48, v128
	v_lshlrev_b64 v[74:75], 9, v[128:129]
	v_lshl_add_u64 v[74:75], s[28:29], 0, v[74:75]
	v_lshl_add_u64 v[74:75], v[74:75], 0, v[64:65]
	v_cvt_f32_f16_e32 v246, v198
	v_cvt_f32_f16_e32 v247, v199
	v_mul_f32_e32 v248, 0xbfb8aa3b, v246
	v_exp_f32_e32 v248, v248
	v_add_f32_e32 v12, v12, v234
	v_add_f32_e32 v248, 1.0, v248
	v_div_scale_f32 v249, s[38:39], v248, v248, v246
	v_rcp_f32_e32 v250, v249
	v_mul_f32_e32 v12, v12, v247
	v_div_scale_f32 v251, vcc, v246, v248, v246
	v_fma_f32 v252, -v249, v250, 1.0
	v_fmac_f32_e32 v250, v252, v250
	v_mul_f32_e32 v252, v251, v250
	v_fma_f32 v253, -v249, v252, v251
	v_fmac_f32_e32 v252, v253, v250
	v_fma_f32 v251, -v249, v252, v251
	v_div_fmas_f32 v251, v251, v250, v252
	v_div_fixup_f32 v251, v251, v248, v246
	v_mul_f32_e32 v12, v12, v251
	v_cvt_pk_bf16_f32 v12, v12, v129
	global_store_short v[74:75], v12, off
	v_cvt_f32_f16_e32 v246, v200
	v_cvt_f32_f16_e32 v247, v201
	v_mul_f32_e32 v248, 0xbfb8aa3b, v246
	v_exp_f32_e32 v248, v248
	v_add_f32_e32 v8, v8, v234
	v_add_f32_e32 v248, 1.0, v248
	v_div_scale_f32 v249, s[38:39], v248, v248, v246
	v_rcp_f32_e32 v250, v249
	v_mul_f32_e32 v8, v8, v247
	v_div_scale_f32 v251, vcc, v246, v248, v246
	v_fma_f32 v252, -v249, v250, 1.0
	v_fmac_f32_e32 v250, v252, v250
	v_mul_f32_e32 v252, v251, v250
	v_fma_f32 v253, -v249, v252, v251
	v_fmac_f32_e32 v252, v253, v250
	v_fma_f32 v251, -v249, v252, v251
	v_div_fmas_f32 v251, v251, v250, v252
	v_div_fixup_f32 v251, v251, v248, v246
	v_mul_f32_e32 v8, v8, v251
	v_cvt_pk_bf16_f32 v8, v8, v129
	global_store_short v[74:75], v8, off offset:32
	v_cvt_f32_f16_e32 v246, v202
	v_cvt_f32_f16_e32 v247, v203
	v_mul_f32_e32 v248, 0xbfb8aa3b, v246
	v_exp_f32_e32 v248, v248
	v_add_f32_e32 v4, v4, v234
	v_add_f32_e32 v248, 1.0, v248
	v_div_scale_f32 v249, s[38:39], v248, v248, v246
	v_rcp_f32_e32 v250, v249
	v_mul_f32_e32 v4, v4, v247
	v_div_scale_f32 v251, vcc, v246, v248, v246
	v_fma_f32 v252, -v249, v250, 1.0
	v_fmac_f32_e32 v250, v252, v250
	v_mul_f32_e32 v252, v251, v250
	v_fma_f32 v253, -v249, v252, v251
; DEVI u16 f2bf(float f) { return (u16)(cvtpk(f, 0.f) & 0xffffu); }
; DEVI float siluf_(float x) { return x / (1.f + __expf(-x)); }
; DEVI void prepSGU_tile(const Params& p, int l, int g, int tile, char* lds) {
;     ...
; #pragma unroll
;         for (int nb = 0; nb < 4; ++nb) {
;           int c = gi * 64 + nb * 16 + l15;
;           float u = (float)zr[736 + c], gc = (float)zr[1248 + c];
;           Yc[(size_t)(t0 + pp) * 256 + c] = f2bf(u * (acc[mb][nb][j] + bv) * siluf_(gc));
;         }
	v_fmac_f32_e32 v252, v253, v250
	v_fma_f32 v251, -v249, v252, v251
	v_div_fmas_f32 v251, v251, v250, v252
	v_div_fixup_f32 v251, v251, v248, v246
	v_mul_f32_e32 v4, v4, v251
	v_cvt_pk_bf16_f32 v4, v4, v129
	global_store_short v[74:75], v4, off offset:64
	v_cvt_f32_f16_e32 v246, v204
	v_cvt_f32_f16_e32 v247, v205
	v_mul_f32_e32 v248, 0xbfb8aa3b, v246
	v_exp_f32_e32 v248, v248
	v_add_f32_e32 v0, v0, v234
	v_add_f32_e32 v248, 1.0, v248
	v_div_scale_f32 v249, s[38:39], v248, v248, v246
	v_rcp_f32_e32 v250, v249
	v_mul_f32_e32 v0, v0, v247
	v_div_scale_f32 v251, vcc, v246, v248, v246
	v_fma_f32 v252, -v249, v250, 1.0
	v_fmac_f32_e32 v250, v252, v250
	v_mul_f32_e32 v252, v251, v250
	v_fma_f32 v253, -v249, v252, v251
	v_fmac_f32_e32 v252, v253, v250
	v_fma_f32 v251, -v249, v252, v251
	v_div_fmas_f32 v251, v251, v250, v252
	v_div_fixup_f32 v251, v251, v248, v246
	v_mul_f32_e32 v0, v0, v251
	v_cvt_pk_bf16_f32 v0, v0, v129
	global_store_short v[74:75], v0, off offset:96
	v_cvt_f32_f16_e32 v246, v206
	v_cvt_f32_f16_e32 v247, v207
	v_mul_f32_e32 v248, 0xbfb8aa3b, v246
	v_exp_f32_e32 v248, v248
	v_add_f32_e32 v13, v13, v235
	v_add_f32_e32 v248, 1.0, v248
	v_div_scale_f32 v249, s[38:39], v248, v248, v246
	v_rcp_f32_e32 v250, v249
	v_mul_f32_e32 v13, v13, v247
	v_div_scale_f32 v251, vcc, v246, v248, v246
	v_fma_f32 v252, -v249, v250, 1.0
	v_fmac_f32_e32 v250, v252, v250
	v_mul_f32_e32 v252, v251, v250
	v_fma_f32 v253, -v249, v252, v251
	v_fmac_f32_e32 v252, v253, v250
	v_fma_f32 v251, -v249, v252, v251
	v_div_fmas_f32 v251, v251, v250, v252
	v_div_fixup_f32 v251, v251, v248, v246
	v_mul_f32_e32 v13, v13, v251
	v_cvt_pk_bf16_f32 v13, v13, v129
	global_store_short v[74:75], v13, off offset:512
	v_cvt_f32_f16_e32 v246, v208
	v_cvt_f32_f16_e32 v247, v209
	v_mul_f32_e32 v248, 0xbfb8aa3b, v246
	v_exp_f32_e32 v248, v248
	v_add_f32_e32 v9, v9, v235
	v_add_f32_e32 v248, 1.0, v248
	v_div_scale_f32 v249, s[38:39], v248, v248, v246
	v_rcp_f32_e32 v250, v249
	v_mul_f32_e32 v9, v9, v247
	v_div_scale_f32 v251, vcc, v246, v248, v246
	v_fma_f32 v252, -v249, v250, 1.0
	v_fmac_f32_e32 v250, v252, v250
	v_mul_f32_e32 v252, v251, v250
	v_fma_f32 v253, -v249, v252, v251
	v_fmac_f32_e32 v252, v253, v250
	v_fma_f32 v251, -v249, v252, v251
	v_div_fmas_f32 v251, v251, v250, v252
	v_div_fixup_f32 v251, v251, v248, v246
	v_mul_f32_e32 v9, v9, v251
	v_cvt_pk_bf16_f32 v9, v9, v129
	global_store_short v[74:75], v9, off offset:544
	v_cvt_f32_f16_e32 v246, v210
	v_cvt_f32_f16_e32 v247, v211
	v_mul_f32_e32 v248, 0xbfb8aa3b, v246
	v_exp_f32_e32 v248, v248
	v_add_f32_e32 v5, v5, v235
	v_add_f32_e32 v248, 1.0, v248
	v_div_scale_f32 v249, s[38:39], v248, v248, v246
	v_rcp_f32_e32 v250, v249
	v_mul_f32_e32 v5, v5, v247
	v_div_scale_f32 v251, vcc, v246, v248, v246
	v_fma_f32 v252, -v249, v250, 1.0
	v_fmac_f32_e32 v250, v252, v250
	v_mul_f32_e32 v252, v251, v250
	v_fma_f32 v253, -v249, v252, v251
	v_fmac_f32_e32 v252, v253, v250
	v_fma_f32 v251, -v249, v252, v251
	v_div_fmas_f32 v251, v251, v250, v252
	v_div_fixup_f32 v251, v251, v248, v246
	v_mul_f32_e32 v5, v5, v251
	v_cvt_pk_bf16_f32 v5, v5, v129
	global_store_short v[74:75], v5, off offset:576
	v_cvt_f32_f16_e32 v246, v212
	v_cvt_f32_f16_e32 v247, v213
	v_mul_f32_e32 v248, 0xbfb8aa3b, v246
	v_exp_f32_e32 v248, v248
	v_add_f32_e32 v1, v1, v235
	v_add_f32_e32 v248, 1.0, v248
	v_div_scale_f32 v249, s[38:39], v248, v248, v246
	v_rcp_f32_e32 v250, v249
	v_mul_f32_e32 v1, v1, v247
	v_div_scale_f32 v251, vcc, v246, v248, v246
	v_fma_f32 v252, -v249, v250, 1.0
	v_fmac_f32_e32 v250, v252, v250
	v_mul_f32_e32 v252, v251, v250
	v_fma_f32 v253, -v249, v252, v251
	v_fmac_f32_e32 v252, v253, v250
	v_fma_f32 v251, -v249, v252, v251
	v_div_fmas_f32 v251, v251, v250, v252
	v_div_fixup_f32 v251, v251, v248, v246
	v_mul_f32_e32 v1, v1, v251
	v_cvt_pk_bf16_f32 v1, v1, v129
	global_store_short v[74:75], v1, off offset:608
	v_cvt_f32_f16_e32 v246, v214
	v_cvt_f32_f16_e32 v247, v215
	v_mul_f32_e32 v248, 0xbfb8aa3b, v246
	v_exp_f32_e32 v248, v248
	v_add_f32_e32 v14, v14, v236
	v_add_f32_e32 v248, 1.0, v248
	v_div_scale_f32 v249, s[38:39], v248, v248, v246
	v_rcp_f32_e32 v250, v249
	v_mul_f32_e32 v14, v14, v247
	v_div_scale_f32 v251, vcc, v246, v248, v246
	v_fma_f32 v252, -v249, v250, 1.0
	v_fmac_f32_e32 v250, v252, v250
	v_mul_f32_e32 v252, v251, v250
	v_fma_f32 v253, -v249, v252, v251
	v_fmac_f32_e32 v252, v253, v250
	v_fma_f32 v251, -v249, v252, v251
	v_div_fmas_f32 v251, v251, v250, v252
	v_div_fixup_f32 v251, v251, v248, v246
	v_mul_f32_e32 v14, v14, v251
	v_cvt_pk_bf16_f32 v14, v14, v129
	global_store_short v[74:75], v14, off offset:1024
	v_cvt_f32_f16_e32 v246, v216
	v_cvt_f32_f16_e32 v247, v217
	v_mul_f32_e32 v248, 0xbfb8aa3b, v246
	v_exp_f32_e32 v248, v248
	v_add_f32_e32 v10, v10, v236
	v_add_f32_e32 v248, 1.0, v248
	v_div_scale_f32 v249, s[38:39], v248, v248, v246
	v_rcp_f32_e32 v250, v249
; DEVI u16 f2bf(float f) { return (u16)(cvtpk(f, 0.f) & 0xffffu); }
; DEVI float siluf_(float x) { return x / (1.f + __expf(-x)); }
; DEVI void prepSGU_tile(const Params& p, int l, int g, int tile, char* lds) {
;     ...
; #pragma unroll
;         for (int nb = 0; nb < 4; ++nb) {
;           int c = gi * 64 + nb * 16 + l15;
;           float u = (float)zr[736 + c], gc = (float)zr[1248 + c];
;           Yc[(size_t)(t0 + pp) * 256 + c] = f2bf(u * (acc[mb][nb][j] + bv) * siluf_(gc));
;         }
;       }
;   }
;   __syncthreads();
	v_mul_f32_e32 v10, v10, v247
	v_div_scale_f32 v251, vcc, v246, v248, v246
	v_fma_f32 v252, -v249, v250, 1.0
	v_fmac_f32_e32 v250, v252, v250
	v_mul_f32_e32 v252, v251, v250
	v_fma_f32 v253, -v249, v252, v251
	v_fmac_f32_e32 v252, v253, v250
	v_fma_f32 v251, -v249, v252, v251
	v_div_fmas_f32 v251, v251, v250, v252
	v_div_fixup_f32 v251, v251, v248, v246
	v_mul_f32_e32 v10, v10, v251
	v_cvt_pk_bf16_f32 v10, v10, v129
	global_store_short v[74:75], v10, off offset:1056
	v_cvt_f32_f16_e32 v246, v222
	v_cvt_f32_f16_e32 v247, v223
	v_mul_f32_e32 v248, 0xbfb8aa3b, v246
	v_exp_f32_e32 v248, v248
	v_add_f32_e32 v6, v6, v236
	v_add_f32_e32 v248, 1.0, v248
	v_div_scale_f32 v249, s[38:39], v248, v248, v246
	v_rcp_f32_e32 v250, v249
	v_mul_f32_e32 v6, v6, v247
	v_div_scale_f32 v251, vcc, v246, v248, v246
	v_fma_f32 v252, -v249, v250, 1.0
	v_fmac_f32_e32 v250, v252, v250
	v_mul_f32_e32 v252, v251, v250
	v_fma_f32 v253, -v249, v252, v251
	v_fmac_f32_e32 v252, v253, v250
	v_fma_f32 v251, -v249, v252, v251
	v_div_fmas_f32 v251, v251, v250, v252
	v_div_fixup_f32 v251, v251, v248, v246
	v_mul_f32_e32 v6, v6, v251
	v_cvt_pk_bf16_f32 v6, v6, v129
	global_store_short v[74:75], v6, off offset:1088
	v_cvt_f32_f16_e32 v246, v224
	v_cvt_f32_f16_e32 v247, v225
	v_mul_f32_e32 v248, 0xbfb8aa3b, v246
	v_exp_f32_e32 v248, v248
	v_add_f32_e32 v2, v2, v236
	v_add_f32_e32 v248, 1.0, v248
	v_div_scale_f32 v249, s[38:39], v248, v248, v246
	v_rcp_f32_e32 v250, v249
	v_mul_f32_e32 v2, v2, v247
	v_div_scale_f32 v251, vcc, v246, v248, v246
	v_fma_f32 v252, -v249, v250, 1.0
	v_fmac_f32_e32 v250, v252, v250
	v_mul_f32_e32 v252, v251, v250
	v_fma_f32 v253, -v249, v252, v251
	v_fmac_f32_e32 v252, v253, v250
	v_fma_f32 v251, -v249, v252, v251
	v_div_fmas_f32 v251, v251, v250, v252
	v_div_fixup_f32 v251, v251, v248, v246
	v_mul_f32_e32 v2, v2, v251
	v_cvt_pk_bf16_f32 v2, v2, v129
	global_store_short v[74:75], v2, off offset:1120
	v_cvt_f32_f16_e32 v246, v226
	v_cvt_f32_f16_e32 v247, v227
	v_mul_f32_e32 v248, 0xbfb8aa3b, v246
	v_exp_f32_e32 v248, v248
	v_add_f32_e32 v15, v15, v237
	v_add_f32_e32 v248, 1.0, v248
	v_div_scale_f32 v249, s[38:39], v248, v248, v246
	v_rcp_f32_e32 v250, v249
	v_mul_f32_e32 v15, v15, v247
	v_div_scale_f32 v251, vcc, v246, v248, v246
	v_fma_f32 v252, -v249, v250, 1.0
	v_fmac_f32_e32 v250, v252, v250
	v_mul_f32_e32 v252, v251, v250
	v_fma_f32 v253, -v249, v252, v251
	v_fmac_f32_e32 v252, v253, v250
	v_fma_f32 v251, -v249, v252, v251
	v_div_fmas_f32 v251, v251, v250, v252
	v_div_fixup_f32 v251, v251, v248, v246
	v_mul_f32_e32 v15, v15, v251
	v_cvt_pk_bf16_f32 v15, v15, v129
	global_store_short v[74:75], v15, off offset:1536
	v_cvt_f32_f16_e32 v246, v228
	v_cvt_f32_f16_e32 v247, v229
	v_mul_f32_e32 v248, 0xbfb8aa3b, v246
	v_exp_f32_e32 v248, v248
	v_add_f32_e32 v11, v11, v237
	v_add_f32_e32 v248, 1.0, v248
	v_div_scale_f32 v249, s[38:39], v248, v248, v246
	v_rcp_f32_e32 v250, v249
	v_mul_f32_e32 v11, v11, v247
	v_div_scale_f32 v251, vcc, v246, v248, v246
	v_fma_f32 v252, -v249, v250, 1.0
	v_fmac_f32_e32 v250, v252, v250
	v_mul_f32_e32 v252, v251, v250
	v_fma_f32 v253, -v249, v252, v251
	v_fmac_f32_e32 v252, v253, v250
	v_fma_f32 v251, -v249, v252, v251
	v_div_fmas_f32 v251, v251, v250, v252
	v_div_fixup_f32 v251, v251, v248, v246
	v_mul_f32_e32 v11, v11, v251
	v_cvt_pk_bf16_f32 v11, v11, v129
	global_store_short v[74:75], v11, off offset:1568
	v_cvt_f32_f16_e32 v246, v230
	v_cvt_f32_f16_e32 v247, v231
	v_mul_f32_e32 v248, 0xbfb8aa3b, v246
	v_exp_f32_e32 v248, v248
	v_add_f32_e32 v7, v7, v237
	v_add_f32_e32 v248, 1.0, v248
	v_div_scale_f32 v249, s[38:39], v248, v248, v246
	v_rcp_f32_e32 v250, v249
	v_mul_f32_e32 v7, v7, v247
	v_div_scale_f32 v251, vcc, v246, v248, v246
	v_fma_f32 v252, -v249, v250, 1.0
	v_fmac_f32_e32 v250, v252, v250
	v_mul_f32_e32 v252, v251, v250
	v_fma_f32 v253, -v249, v252, v251
	v_fmac_f32_e32 v252, v253, v250
	v_fma_f32 v251, -v249, v252, v251
	v_div_fmas_f32 v251, v251, v250, v252
	v_div_fixup_f32 v251, v251, v248, v246
	v_mul_f32_e32 v7, v7, v251
	v_cvt_pk_bf16_f32 v7, v7, v129
	global_store_short v[74:75], v7, off offset:1600
	v_cvt_f32_f16_e32 v246, v232
	v_cvt_f32_f16_e32 v247, v233
	v_mul_f32_e32 v248, 0xbfb8aa3b, v246
	v_exp_f32_e32 v248, v248
	v_add_f32_e32 v3, v3, v237
	v_add_f32_e32 v248, 1.0, v248
	v_div_scale_f32 v249, s[38:39], v248, v248, v246
	v_rcp_f32_e32 v250, v249
	v_mul_f32_e32 v3, v3, v247
	v_div_scale_f32 v251, vcc, v246, v248, v246
	v_fma_f32 v252, -v249, v250, 1.0
	v_fmac_f32_e32 v250, v252, v250
	v_mul_f32_e32 v252, v251, v250
	v_fma_f32 v253, -v249, v252, v251
	v_fmac_f32_e32 v252, v253, v250
	v_fma_f32 v251, -v249, v252, v251
	v_div_fmas_f32 v251, v251, v250, v252
	v_div_fixup_f32 v251, v251, v248, v246
	v_mul_f32_e32 v3, v3, v251
	v_cvt_pk_bf16_f32 v3, v3, v129
	global_store_short v[74:75], v3, off offset:1632
	s_barrier
	s_branch .LBB0_778

; DEVI unsigned cvtpk(float lo, float hi) { unsigned r; asm volatile("v_cvt_pk_bf16_f32 %0, %1, %2" : "=v"(r) : "v"(lo), "v"(hi)); return r; }
; DEVI float siluf_(float x) { return x / (1.f + __expf(-x)); }
; DEVI void prepMLA_tile(const Params& p, int l, int g, int tile, char* lds) {
;     ...
; #pragma unroll
;   for (int i = 0; i < 6; ++i) {
;     int it = tid + i * 512; int tok = it / 48, ch = it % 48;
;     h16x8 z = *(const h16x8*)(Z + (size_t)tok * NBC + 352 + ch * 8);
;     u32x4 w; w.x = cvtpk(siluf_((float)z[0]), siluf_((float)z[1])); w.y = cvtpk(siluf_((float)z[2]), siluf_((float)z[3]));
;     w.z = cvtpk(siluf_((float)z[4]), siluf_((float)z[5])); w.w = cvtpk(siluf_((float)z[6]), siluf_((float)z[7]));
;     *(u32x4*)(Yb + (size_t)(t0 + tok) * 384 + ch * 8) = w;
;   }
.LBB0_944:
	s_mov_b32 s28, 0x2aaaaaab
	v_mov_b32_e32 v236, v19
	v_mul_hi_i32 v237, v236, s28
	v_lshrrev_b32_e32 v238, 31, v237
	v_ashrrev_i32_e32 v237, 3, v237
	v_add_u32_e32 v237, v237, v238
	v_mul_lo_u32 v238, v237, 48
	v_sub_u32_e32 v238, v236, v238
	v_add_u32_e32 v237, s80, v237
	v_subrev_u32_e32 v237, s31, v237
	v_lshlrev_b32_e32 v238, 4, v238
	v_mov_b32_e32 v239, 0
	v_mov_b64_e32 v[240:241], s[8:9]
	v_mad_i64_i32 v[240:241], s[0:1], v237, s25, v[240:241]
	v_lshl_add_u64 v[240:241], v[240:241], 0, v[238:239]
	global_load_dwordx4 v[162:165], v[240:241], off offset:2816
	v_add_u32_e32 v236, 0x200, v19
	v_mul_hi_i32 v237, v236, s28
	v_lshrrev_b32_e32 v238, 31, v237
	v_ashrrev_i32_e32 v237, 3, v237
	v_add_u32_e32 v237, v237, v238
	v_mul_lo_u32 v238, v237, 48
	v_sub_u32_e32 v238, v236, v238
	v_add_u32_e32 v237, s80, v237
	v_subrev_u32_e32 v237, s31, v237
	v_lshlrev_b32_e32 v238, 4, v238
	v_mov_b32_e32 v239, 0
	v_mov_b64_e32 v[240:241], s[8:9]
	v_mad_i64_i32 v[240:241], s[0:1], v237, s25, v[240:241]
	v_lshl_add_u64 v[240:241], v[240:241], 0, v[238:239]
	global_load_dwordx4 v[166:169], v[240:241], off offset:2816
	v_add_u32_e32 v236, 0x400, v19
	v_mul_hi_i32 v237, v236, s28
	v_lshrrev_b32_e32 v238, 31, v237
	v_ashrrev_i32_e32 v237, 3, v237
	v_add_u32_e32 v237, v237, v238
	v_mul_lo_u32 v238, v237, 48
	v_sub_u32_e32 v238, v236, v238
	v_add_u32_e32 v237, s80, v237
	v_subrev_u32_e32 v237, s31, v237
	v_lshlrev_b32_e32 v238, 4, v238
	v_mov_b32_e32 v239, 0
	v_mov_b64_e32 v[240:241], s[8:9]
	v_mad_i64_i32 v[240:241], s[0:1], v237, s25, v[240:241]
	v_lshl_add_u64 v[240:241], v[240:241], 0, v[238:239]
	global_load_dwordx4 v[170:173], v[240:241], off offset:2816
	v_add_u32_e32 v236, 0x600, v19
	v_mul_hi_i32 v237, v236, s28
	v_lshrrev_b32_e32 v238, 31, v237
	v_ashrrev_i32_e32 v237, 3, v237
	v_add_u32_e32 v237, v237, v238
	v_mul_lo_u32 v238, v237, 48
	v_sub_u32_e32 v238, v236, v238
	v_add_u32_e32 v237, s80, v237
	v_subrev_u32_e32 v237, s31, v237
	v_lshlrev_b32_e32 v238, 4, v238
	v_mov_b32_e32 v239, 0
	v_mov_b64_e32 v[240:241], s[8:9]
	v_mad_i64_i32 v[240:241], s[0:1], v237, s25, v[240:241]
	v_lshl_add_u64 v[240:241], v[240:241], 0, v[238:239]
	global_load_dwordx4 v[174:177], v[240:241], off offset:2816
	v_add_u32_e32 v236, 0x800, v19
	v_mul_hi_i32 v237, v236, s28
	v_lshrrev_b32_e32 v238, 31, v237
	v_ashrrev_i32_e32 v237, 3, v237
	v_add_u32_e32 v237, v237, v238
	v_mul_lo_u32 v238, v237, 48
	v_sub_u32_e32 v238, v236, v238
	v_add_u32_e32 v237, s80, v237
	v_subrev_u32_e32 v237, s31, v237
	v_lshlrev_b32_e32 v238, 4, v238
	v_mov_b32_e32 v239, 0
	v_mov_b64_e32 v[240:241], s[8:9]
	v_mad_i64_i32 v[240:241], s[0:1], v237, s25, v[240:241]
	v_lshl_add_u64 v[240:241], v[240:241], 0, v[238:239]
	global_load_dwordx4 v[178:181], v[240:241], off offset:2816
	v_add_u32_e32 v236, 0xa00, v19
	v_mul_hi_i32 v237, v236, s28
	v_lshrrev_b32_e32 v238, 31, v237
	v_ashrrev_i32_e32 v237, 3, v237
	v_add_u32_e32 v237, v237, v238
	v_mul_lo_u32 v238, v237, 48
	v_sub_u32_e32 v238, v236, v238
	v_add_u32_e32 v237, s80, v237
	v_subrev_u32_e32 v237, s31, v237
	v_lshlrev_b32_e32 v238, 4, v238
	v_mov_b32_e32 v239, 0
	v_mov_b64_e32 v[240:241], s[8:9]
	v_mad_i64_i32 v[240:241], s[0:1], v237, s25, v[240:241]
	v_lshl_add_u64 v[240:241], v[240:241], 0, v[238:239]
	global_load_dwordx4 v[182:185], v[240:241], off offset:2816
	v_mul_hi_i32 v0, v19, s28
	v_lshrrev_b32_e32 v1, 31, v0
	v_ashrrev_i32_e32 v0, 3, v0
	v_add_u32_e32 v10, v0, v1
	v_mul_lo_u32 v0, v10, 48
	v_sub_u32_e32 v11, v19, v0
	v_add_u32_e32 v12, s80, v10
	v_lshlrev_b32_e32 v48, 3, v11
	v_subrev_u32_e32 v0, s31, v12
	v_mov_b64_e32 v[4:5], s[8:9]
	v_ashrrev_i32_e32 v49, 31, v48
	v_mad_i64_i32 v[0:1], s[0:1], v0, s25, v[4:5]
	v_lshlrev_b64 v[8:9], 1, v[48:49]
	v_lshl_add_u64 v[0:1], v[0:1], 0, v[8:9]
	s_waitcnt vmcnt(0)
	v_mov_b32_e32 v0, v162
	v_mov_b32_e32 v1, v163
	v_mov_b32_e32 v2, v164
	v_mov_b32_e32 v3, v165
	v_lshlrev_b32_e32 v11, 4, v11
	s_waitcnt vmcnt(0)
	v_cvt_f32_f16_sdwa v13, v0 dst_sel:DWORD dst_unused:UNUSED_PAD src0_sel:WORD_1
	v_cvt_f32_f16_e32 v16, v0
	v_cvt_f32_f16_sdwa v17, v1 dst_sel:DWORD dst_unused:UNUSED_PAD src0_sel:WORD_1
	v_cvt_f32_f16_e32 v18, v1
	v_cvt_f32_f16_sdwa v20, v2 dst_sel:DWORD dst_unused:UNUSED_PAD src0_sel:WORD_1
	v_cvt_f32_f16_e32 v21, v2
	v_mul_f32_e32 v0, 0xbfb8aa3b, v16
	v_mul_f32_e32 v1, 0xbfb8aa3b, v13
	v_exp_f32_e32 v0, v0
	v_exp_f32_e32 v1, v1
	v_mul_f32_e32 v2, 0xbfb8aa3b, v18
	v_mul_f32_e32 v7, 0xbfb8aa3b, v17
	v_mul_f32_e32 v14, 0xbfb8aa3b, v21
	v_mul_f32_e32 v15, 0xbfb8aa3b, v20
	v_exp_f32_e32 v6, v2
	v_exp_f32_e32 v7, v7
	v_exp_f32_e32 v14, v14
	v_exp_f32_e32 v15, v15
	v_pk_add_f32 v[0:1], v[0:1], 1.0 op_sel_hi:[1,0]
	v_pk_add_f32 v[6:7], v[6:7], 1.0 op_sel_hi:[1,0]
	v_div_scale_f32 v2, s[0:1], v1, v1, v13
	v_pk_add_f32 v[14:15], v[14:15], 1.0 op_sel_hi:[1,0]
	v_div_scale_f32 v27, s[0:1], v0, v0, v16
	v_rcp_f32_e32 v36, v2
	v_div_scale_f32 v29, s[6:7], v7, v7, v17
	v_div_scale_f32 v35, s[6:7], v14, v14, v21
	v_rcp_f32_e32 v37, v27
	v_div_scale_f32 v31, s[6:7], v6, v6, v18
	v_rcp_f32_e32 v38, v29
	v_rcp_f32_e32 v41, v35
	v_div_scale_f32 v33, s[6:7], v15, v15, v20
	v_rcp_f32_e32 v39, v31
	v_rcp_f32_e32 v40, v33
	v_fma_f32 v42, -v2, v36, 1.0
	v_div_scale_f32 v26, vcc, v13, v1, v13
	v_fma_f32 v43, -v27, v37, 1.0
	v_fmac_f32_e32 v36, v42, v36
	v_div_scale_f32 v28, s[0:1], v16, v0, v16
	v_fma_f32 v44, -v29, v38, 1.0
	v_fma_f32 v47, -v35, v41, 1.0
	v_fmac_f32_e32 v37, v43, v37
	v_mul_f32_e32 v42, v26, v36
	v_div_scale_f32 v30, s[38:39], v17, v7, v17
	v_fma_f32 v45, -v31, v39, 1.0
	v_fmac_f32_e32 v38, v44, v38
	v_fmac_f32_e32 v41, v47, v41
	v_mul_f32_e32 v43, v28, v37
	v_fma_f32 v47, -v2, v42, v26
; DEVI unsigned cvtpk(float lo, float hi) { unsigned r; asm volatile("v_cvt_pk_bf16_f32 %0, %1, %2" : "=v"(r) : "v"(lo), "v"(hi)); return r; }
; DEVI float siluf_(float x) { return x / (1.f + __expf(-x)); }
; DEVI void prepMLA_tile(const Params& p, int l, int g, int tile, char* lds) {
;     ...
; #pragma unroll
;   for (int i = 0; i < 6; ++i) {
;     int it = tid + i * 512; int tok = it / 48, ch = it % 48;
;     h16x8 z = *(const h16x8*)(Z + (size_t)tok * NBC + 352 + ch * 8);
;     u32x4 w; w.x = cvtpk(siluf_((float)z[0]), siluf_((float)z[1])); w.y = cvtpk(siluf_((float)z[2]), siluf_((float)z[3]));
;     w.z = cvtpk(siluf_((float)z[4]), siluf_((float)z[5])); w.w = cvtpk(siluf_((float)z[6]), siluf_((float)z[7]));
;     *(u32x4*)(Yb + (size_t)(t0 + tok) * 384 + ch * 8) = w;
;   }
	v_div_scale_f32 v32, s[40:41], v18, v6, v18
	v_fma_f32 v46, -v33, v40, 1.0
	v_fmac_f32_e32 v39, v45, v39
	v_mul_f32_e32 v44, v30, v38
	v_fma_f32 v50, -v27, v43, v28
	v_fmac_f32_e32 v42, v47, v36
	v_div_scale_f32 v34, s[42:43], v20, v15, v20
	v_fmac_f32_e32 v40, v46, v40
	v_mul_f32_e32 v45, v32, v39
	v_fma_f32 v51, -v29, v44, v30
	v_fmac_f32_e32 v43, v50, v37
	v_fma_f32 v2, -v2, v42, v26
	v_mul_f32_e32 v46, v34, v40
	v_fma_f32 v52, -v31, v45, v32
	v_fmac_f32_e32 v44, v51, v38
	v_fma_f32 v26, -v27, v43, v28
	v_div_fmas_f32 v2, v2, v36, v42
	s_mov_b64 vcc, s[0:1]
	v_fma_f32 v53, -v33, v46, v34
	v_fmac_f32_e32 v45, v52, v39
	v_fma_f32 v27, -v29, v44, v30
	v_div_fixup_f32 v1, v2, v1, v13
	v_div_fmas_f32 v2, v26, v37, v43
	s_mov_b64 vcc, s[38:39]
	v_fmac_f32_e32 v46, v53, v40
	v_fma_f32 v28, -v31, v45, v32
	v_div_fixup_f32 v0, v2, v0, v16
	v_div_fmas_f32 v2, v27, v38, v44
	s_mov_b64 vcc, s[40:41]
	v_fma_f32 v29, -v33, v46, v34
	v_cvt_pk_f16_f32 v0, v0, v1
	v_div_fixup_f32 v1, v2, v7, v17
	v_div_fmas_f32 v2, v28, v39, v45
	s_mov_b64 vcc, s[42:43]
	v_div_fixup_f32 v2, v2, v6, v18
	v_div_fmas_f32 v6, v29, v40, v46
	v_cvt_f32_f16_e32 v24, v3
	v_div_fixup_f32 v13, v6, v15, v20
	v_cvt_f32_f16_sdwa v15, v3 dst_sel:DWORD dst_unused:UNUSED_PAD src0_sel:WORD_1
	v_cvt_pk_f16_f32 v1, v2, v1
	v_mul_f32_e32 v2, 0xbfb8aa3b, v24
	v_div_scale_f32 v6, vcc, v21, v14, v21
	v_mul_f32_e32 v3, 0xbfb8aa3b, v15
	v_exp_f32_e32 v2, v2
	v_exp_f32_e32 v3, v3
	v_mul_f32_e32 v16, v6, v41
	v_fma_f32 v7, -v35, v16, v6
	v_fmac_f32_e32 v16, v7, v41
	v_fma_f32 v17, -v35, v16, v6
	v_pk_add_f32 v[6:7], v[2:3], 1.0 op_sel_hi:[1,0]
	v_div_fmas_f32 v2, v17, v41, v16
	v_div_scale_f32 v3, s[0:1], v7, v7, v15
	v_rcp_f32_e32 v18, v3
	v_div_fixup_f32 v2, v2, v14, v21
	v_cvt_pk_f16_f32 v2, v2, v13
	v_fma_f32 v13, -v3, v18, 1.0
	v_fmac_f32_e32 v18, v13, v18
	v_div_scale_f32 v13, vcc, v15, v7, v15
	v_mul_f32_e32 v14, v13, v18
	v_fma_f32 v16, -v3, v14, v13
	v_fmac_f32_e32 v14, v16, v18
	v_fma_f32 v3, -v3, v14, v13
	v_div_scale_f32 v13, s[0:1], v6, v6, v24
	v_rcp_f32_e32 v16, v13
	v_div_fmas_f32 v3, v3, v18, v14
	v_div_fixup_f32 v3, v3, v7, v15
	v_fma_f32 v7, -v13, v16, 1.0
	v_fmac_f32_e32 v16, v7, v16
	v_div_scale_f32 v7, vcc, v24, v6, v24
	v_mul_f32_e32 v14, v7, v16
	v_fma_f32 v15, -v13, v14, v7
	v_fmac_f32_e32 v14, v15, v16
	v_fma_f32 v7, -v13, v14, v7
	v_div_fmas_f32 v7, v7, v16, v14
	v_div_fixup_f32 v6, v7, v6, v24
	v_cvt_pk_f16_f32 v3, v6, v3
	v_mov_b64_e32 v[6:7], s[18:19]
	v_mad_i64_i32 v[14:15], s[0:1], v12, s35, v[6:7]
	v_lshl_add_u64 v[8:9], v[14:15], 0, v[8:9]
	global_store_dwordx4 v[8:9], v[0:3], off
	s_nop 1
	v_mul_hi_i32 v0, v22, s28
	v_lshrrev_b32_e32 v1, 31, v0
	v_ashrrev_i32_e32 v0, 3, v0
	v_add_u32_e32 v13, v0, v1
	v_mul_lo_u32 v0, v13, 48
	v_sub_u32_e32 v14, v22, v0
	v_add_u32_e32 v15, s80, v13
	v_lshlrev_b32_e32 v50, 3, v14
	v_subrev_u32_e32 v0, s31, v15
	v_ashrrev_i32_e32 v51, 31, v50
	v_mad_i64_i32 v[0:1], s[0:1], v0, s25, v[4:5]
	v_lshlrev_b64 v[8:9], 1, v[50:51]
	v_lshl_add_u64 v[0:1], v[0:1], 0, v[8:9]
	v_mov_b32_e32 v0, v166
	v_mov_b32_e32 v1, v167
	v_mov_b32_e32 v2, v168
	v_mov_b32_e32 v3, v169
	v_cvt_f32_f16_e32 v18, v0
	v_cvt_f32_f16_sdwa v20, v0 dst_sel:DWORD dst_unused:UNUSED_PAD src0_sel:WORD_1
	v_cvt_f32_f16_e32 v22, v1
	v_cvt_f32_f16_sdwa v21, v1 dst_sel:DWORD dst_unused:UNUSED_PAD src0_sel:WORD_1
	v_mul_f32_e32 v0, 0xbfb8aa3b, v18
	v_mul_f32_e32 v1, 0xbfb8aa3b, v20
	v_exp_f32_e32 v0, v0
	v_exp_f32_e32 v1, v1
	v_mul_f32_e32 v16, 0xbfb8aa3b, v22
	v_mul_f32_e32 v17, 0xbfb8aa3b, v21
	v_exp_f32_e32 v16, v16
	v_pk_add_f32 v[0:1], v[0:1], 1.0 op_sel_hi:[1,0]
	v_exp_f32_e32 v17, v17
	v_div_scale_f32 v24, s[0:1], v1, v1, v20
	v_div_scale_f32 v27, s[0:1], v0, v0, v18
	v_rcp_f32_e32 v29, v24
	v_rcp_f32_e32 v30, v27
	v_div_scale_f32 v26, vcc, v20, v1, v20
	v_fma_f32 v33, -v24, v29, 1.0
	v_fma_f32 v34, -v27, v30, 1.0
	v_fmac_f32_e32 v29, v33, v29
	v_div_scale_f32 v28, s[0:1], v18, v0, v18
	v_fmac_f32_e32 v30, v34, v30
	v_mul_f32_e32 v33, v26, v29
	v_pk_add_f32 v[16:17], v[16:17], 1.0 op_sel_hi:[1,0]
	v_mul_f32_e32 v34, v28, v30
	v_fma_f32 v35, -v24, v33, v26
	v_div_scale_f32 v31, s[6:7], v17, v17, v21
	v_fma_f32 v36, -v27, v34, v28
	v_fmac_f32_e32 v33, v35, v29
	v_rcp_f32_e32 v32, v31
	v_fmac_f32_e32 v34, v36, v30
	v_fma_f32 v24, -v24, v33, v26
	v_fma_f32 v26, -v27, v34, v28
	v_div_fmas_f32 v24, v24, v29, v33
	s_mov_b64 vcc, s[0:1]
	v_div_fixup_f32 v1, v24, v1, v20
	v_div_fmas_f32 v20, v26, v30, v34
	v_div_fixup_f32 v0, v20, v0, v18
	v_cvt_pk_f16_f32 v0, v0, v1
	v_fma_f32 v1, -v31, v32, 1.0
	v_fmac_f32_e32 v32, v1, v32
	v_div_scale_f32 v1, vcc, v21, v17, v21
	v_mul_f32_e32 v18, v1, v32
	v_fma_f32 v20, -v31, v18, v1
	v_fmac_f32_e32 v18, v20, v32
	v_fma_f32 v1, -v31, v18, v1
	v_div_scale_f32 v24, s[0:1], v16, v16, v22
	v_div_fmas_f32 v1, v1, v32, v18
	v_cvt_f32_f16_e32 v18, v2
	v_cvt_f32_f16_sdwa v2, v2 dst_sel:DWORD dst_unused:UNUSED_PAD src0_sel:WORD_1
	v_rcp_f32_e32 v26, v24
	v_div_fixup_f32 v1, v1, v17, v21
	v_mul_f32_e32 v20, 0xbfb8aa3b, v18
	v_mul_f32_e32 v21, 0xbfb8aa3b, v2
	v_fma_f32 v17, -v24, v26, 1.0
	v_exp_f32_e32 v20, v20
	v_exp_f32_e32 v21, v21
	v_fmac_f32_e32 v26, v17, v26
	v_div_scale_f32 v17, vcc, v22, v16, v22
	v_mul_f32_e32 v27, v17, v26
	v_fma_f32 v28, -v24, v27, v17
	v_fmac_f32_e32 v27, v28, v26
	v_pk_add_f32 v[20:21], v[20:21], 1.0 op_sel_hi:[1,0]
	v_fma_f32 v17, -v24, v27, v17
	v_div_scale_f32 v24, s[0:1], v21, v21, v2
	v_rcp_f32_e32 v28, v24
	v_div_fmas_f32 v17, v17, v26, v27
	v_div_fixup_f32 v16, v17, v16, v22
	v_cvt_pk_f16_f32 v1, v16, v1
	v_fma_f32 v16, -v24, v28, 1.0
	v_fmac_f32_e32 v28, v16, v28
	v_div_scale_f32 v16, vcc, v2, v21, v2
; DEVI float siluf_(float x) { return x / (1.f + __expf(-x)); }
; DEVI void prepA_tile(const Params& p, int l, int g, int tile, char* lds) {
;     ...
;     for (int i = 0; i < 6; ++i) {
;       int it = tid + i * 512; int tok = it / 48, ch = it % 48; int t = t0 + tok;
;       h16x8 z = *(const h16x8*)(Z + (size_t)(t - g * TG) * NA + 1408 + ch * 8);
;       h16x8 ov;
; #pragma unroll
;       for (int j = 0; j < 8; ++j) ov[j] = (h16)siluf_((float)z[j]);
;       *(h16x8*)(Sga + (size_t)t * 384 + ch * 8) = ov;
;     }
	v_mul_f32_e32 v17, v16, v28
	v_fma_f32 v22, -v24, v17, v16
	v_fmac_f32_e32 v17, v22, v28
	v_div_scale_f32 v22, s[0:1], v20, v20, v18
	v_fma_f32 v16, -v24, v17, v16
	v_rcp_f32_e32 v24, v22
	v_cvt_f32_f16_e32 v26, v3
	v_cvt_f32_f16_sdwa v27, v3 dst_sel:DWORD dst_unused:UNUSED_PAD src0_sel:WORD_1
	v_div_fmas_f32 v16, v16, v28, v17
	v_div_fixup_f32 v21, v16, v21, v2
	v_fma_f32 v2, -v22, v24, 1.0
	v_fmac_f32_e32 v24, v2, v24
	v_mul_f32_e32 v2, 0xbfb8aa3b, v26
	v_mul_f32_e32 v3, 0xbfb8aa3b, v27
	v_div_scale_f32 v16, vcc, v18, v20, v18
	v_exp_f32_e32 v2, v2
	v_exp_f32_e32 v3, v3
	v_mul_f32_e32 v28, v16, v24
	v_fma_f32 v17, -v22, v28, v16
	v_fmac_f32_e32 v28, v17, v24
	v_fma_f32 v22, -v22, v28, v16
	v_pk_add_f32 v[16:17], v[2:3], 1.0 op_sel_hi:[1,0]
	v_div_fmas_f32 v2, v22, v24, v28
	v_div_scale_f32 v3, s[0:1], v17, v17, v27
	v_rcp_f32_e32 v29, v3
	v_div_fixup_f32 v2, v2, v20, v18
	v_cvt_pk_f16_f32 v2, v2, v21
	v_mad_i64_i32 v[60:61], s[0:1], v12, s35, 0
	v_fma_f32 v18, -v3, v29, 1.0
	v_fmac_f32_e32 v29, v18, v29
	v_div_scale_f32 v18, vcc, v27, v17, v27
	v_mul_f32_e32 v20, v18, v29
	v_fma_f32 v21, -v3, v20, v18
	v_fmac_f32_e32 v20, v21, v29
	v_fma_f32 v3, -v3, v20, v18
	v_div_scale_f32 v18, s[0:1], v16, v16, v26
	v_rcp_f32_e32 v21, v18
	v_div_fmas_f32 v3, v3, v29, v20
	v_div_fixup_f32 v3, v3, v17, v27
	v_mad_i64_i32 v[62:63], s[0:1], v15, s35, 0
	v_fma_f32 v17, -v18, v21, 1.0
	v_fmac_f32_e32 v21, v17, v21
	v_div_scale_f32 v17, vcc, v26, v16, v26
	v_mul_f32_e32 v20, v17, v21
	v_fma_f32 v22, -v18, v20, v17
	v_fmac_f32_e32 v20, v22, v21
	v_fma_f32 v17, -v18, v20, v17
	v_div_fmas_f32 v17, v17, v21, v20
	v_div_fixup_f32 v16, v17, v16, v26
	v_cvt_pk_f16_f32 v3, v16, v3
	v_mad_i64_i32 v[16:17], s[0:1], v15, s35, v[6:7]
	v_lshl_add_u64 v[8:9], v[16:17], 0, v[8:9]
	global_store_dwordx4 v[8:9], v[0:3], off
	s_nop 1
	v_mul_hi_i32 v0, v23, s28
	v_lshrrev_b32_e32 v1, 31, v0
	v_ashrrev_i32_e32 v0, 3, v0
	v_add_u32_e32 v2, v0, v1
	v_mul_lo_u32 v0, v2, 48
	v_sub_u32_e32 v3, v23, v0
	v_add_u32_e32 v16, s80, v2
	v_lshlrev_b32_e32 v52, 3, v3
	v_subrev_u32_e32 v0, s31, v16
	v_ashrrev_i32_e32 v53, 31, v52
	v_mad_i64_i32 v[8:9], s[0:1], v0, s25, v[4:5]
	v_lshlrev_b64 v[0:1], 1, v[52:53]
	v_lshl_add_u64 v[8:9], v[8:9], 0, v[0:1]
	v_mov_b32_e32 v20, v170
	v_mov_b32_e32 v21, v171
	v_mov_b32_e32 v22, v172
	v_mov_b32_e32 v23, v173
	v_mad_i64_i32 v[64:65], s[0:1], v16, s35, 0
	v_lshlrev_b32_e32 v3, 4, v3
	v_cvt_f32_f16_e32 v17, v20
	v_cvt_f32_f16_sdwa v18, v20 dst_sel:DWORD dst_unused:UNUSED_PAD src0_sel:WORD_1
	v_cvt_f32_f16_sdwa v29, v21 dst_sel:DWORD dst_unused:UNUSED_PAD src0_sel:WORD_1
	v_mul_f32_e32 v8, 0xbfb8aa3b, v17
	v_mul_f32_e32 v9, 0xbfb8aa3b, v18
	v_exp_f32_e32 v8, v8
	v_exp_f32_e32 v9, v9
	s_nop 0
	v_pk_add_f32 v[8:9], v[8:9], 1.0 op_sel_hi:[1,0]
	s_nop 0
	v_div_scale_f32 v20, s[0:1], v9, v9, v18
	v_rcp_f32_e32 v24, v20
	s_nop 0
	v_fma_f32 v26, -v20, v24, 1.0
	v_fmac_f32_e32 v24, v26, v24
	v_div_scale_f32 v26, vcc, v18, v9, v18
	v_mul_f32_e32 v27, v26, v24
	v_fma_f32 v28, -v20, v27, v26
	v_fmac_f32_e32 v27, v28, v24
	v_fma_f32 v20, -v20, v27, v26
	v_div_scale_f32 v26, s[0:1], v8, v8, v17
	v_rcp_f32_e32 v28, v26
	v_div_fmas_f32 v20, v20, v24, v27
	v_div_fixup_f32 v9, v20, v9, v18
	v_div_scale_f32 v24, vcc, v17, v8, v17
	v_fma_f32 v18, -v26, v28, 1.0
	v_fmac_f32_e32 v28, v18, v28
	v_cvt_f32_f16_e32 v18, v21
	v_mul_f32_e32 v21, 0xbfb8aa3b, v29
	v_exp_f32_e32 v21, v21
	v_mul_f32_e32 v30, v24, v28
	v_mul_f32_e32 v20, 0xbfb8aa3b, v18
	v_exp_f32_e32 v20, v20
	v_fma_f32 v27, -v26, v30, v24
	v_fmac_f32_e32 v30, v27, v28
	v_fma_f32 v24, -v26, v30, v24
	v_pk_add_f32 v[26:27], v[20:21], 1.0 op_sel_hi:[1,0]
	v_div_fmas_f32 v20, v24, v28, v30
	v_div_scale_f32 v21, s[0:1], v27, v27, v29
	v_rcp_f32_e32 v31, v21
	v_div_fixup_f32 v8, v20, v8, v17
	v_cvt_pk_f16_f32 v20, v8, v9
	v_cvt_f32_f16_e32 v28, v22
	v_fma_f32 v8, -v21, v31, 1.0
	v_fmac_f32_e32 v31, v8, v31
	v_div_scale_f32 v8, vcc, v29, v27, v29
	v_mul_f32_e32 v9, v8, v31
	v_fma_f32 v17, -v21, v9, v8
	v_fmac_f32_e32 v9, v17, v31
	v_div_scale_f32 v17, s[0:1], v26, v26, v18
	v_fma_f32 v8, -v21, v9, v8
	v_rcp_f32_e32 v21, v17
	v_cvt_f32_f16_sdwa v22, v22 dst_sel:DWORD dst_unused:UNUSED_PAD src0_sel:WORD_1
	v_div_fmas_f32 v8, v8, v31, v9
	v_div_fixup_f32 v24, v8, v27, v29
	v_fma_f32 v8, -v17, v21, 1.0
	v_fmac_f32_e32 v21, v8, v21
	v_mul_f32_e32 v8, 0xbfb8aa3b, v28
	v_mul_f32_e32 v9, 0xbfb8aa3b, v22
	v_exp_f32_e32 v8, v8
	v_exp_f32_e32 v9, v9
	v_div_scale_f32 v27, vcc, v18, v26, v18
	v_mul_f32_e32 v29, v27, v21
	v_fma_f32 v30, -v17, v29, v27
	v_fmac_f32_e32 v29, v30, v21
	v_pk_add_f32 v[8:9], v[8:9], 1.0 op_sel_hi:[1,0]
	v_fma_f32 v17, -v17, v29, v27
	v_div_scale_f32 v27, s[0:1], v9, v9, v22
	v_rcp_f32_e32 v30, v27
	v_div_fmas_f32 v17, v17, v21, v29
	v_div_fixup_f32 v17, v17, v26, v18
	v_cvt_pk_f16_f32 v21, v17, v24
	v_fma_f32 v17, -v27, v30, 1.0
	v_fmac_f32_e32 v30, v17, v30
	v_div_scale_f32 v17, vcc, v22, v9, v22
	v_mul_f32_e32 v18, v17, v30
	v_fma_f32 v24, -v27, v18, v17
	v_fmac_f32_e32 v18, v24, v30
	v_div_scale_f32 v24, s[0:1], v8, v8, v28
	v_rcp_f32_e32 v29, v24
	v_fma_f32 v17, -v27, v18, v17
	v_div_fmas_f32 v17, v17, v30, v18
	v_div_fixup_f32 v9, v17, v9, v22
	v_fma_f32 v17, -v24, v29, 1.0
	v_fmac_f32_e32 v29, v17, v29
	v_cvt_f32_f16_e32 v17, v23
	v_cvt_f32_f16_sdwa v30, v23 dst_sel:DWORD dst_unused:UNUSED_PAD src0_sel:WORD_1
	v_div_scale_f32 v18, vcc, v28, v8, v28
	v_mul_f32_e32 v22, 0xbfb8aa3b, v17
	v_mul_f32_e32 v23, 0xbfb8aa3b, v30
	v_exp_f32_e32 v22, v22
	v_exp_f32_e32 v23, v23
	v_mul_f32_e32 v31, v18, v29
	v_fma_f32 v26, -v24, v31, v18
	v_fmac_f32_e32 v31, v26, v29
	v_pk_add_f32 v[26:27], v[22:23], 1.0 op_sel_hi:[1,0]
; DEVI float siluf_(float x) { return x / (1.f + __expf(-x)); }
; DEVI void prepA_tile(const Params& p, int l, int g, int tile, char* lds) {
;     ...
;     for (int i = 0; i < 6; ++i) {
;       int it = tid + i * 512; int tok = it / 48, ch = it % 48; int t = t0 + tok;
;       h16x8 z = *(const h16x8*)(Z + (size_t)(t - g * TG) * NA + 1408 + ch * 8);
;       h16x8 ov;
; #pragma unroll
;       for (int j = 0; j < 8; ++j) ov[j] = (h16)siluf_((float)z[j]);
;       *(h16x8*)(Sga + (size_t)t * 384 + ch * 8) = ov;
;     }
	v_fma_f32 v18, -v24, v31, v18
	v_div_scale_f32 v23, s[0:1], v27, v27, v30
	v_rcp_f32_e32 v24, v23
	v_div_fmas_f32 v18, v18, v29, v31
	v_div_fixup_f32 v8, v18, v8, v28
	v_cvt_pk_f16_f32 v22, v8, v9
	v_fma_f32 v8, -v23, v24, 1.0
	v_fmac_f32_e32 v24, v8, v24
	v_div_scale_f32 v8, vcc, v30, v27, v30
	v_mul_f32_e32 v9, v8, v24
	v_fma_f32 v18, -v23, v9, v8
	v_fmac_f32_e32 v9, v18, v24
	v_div_scale_f32 v18, s[0:1], v26, v26, v17
	v_fma_f32 v8, -v23, v9, v8
	v_rcp_f32_e32 v23, v18
	v_div_fmas_f32 v8, v8, v24, v9
	v_div_fixup_f32 v8, v8, v27, v30
	v_fma_f32 v9, -v18, v23, 1.0
	v_fmac_f32_e32 v23, v9, v23
	v_div_scale_f32 v9, vcc, v17, v26, v17
	v_mul_f32_e32 v24, v9, v23
	v_fma_f32 v27, -v18, v24, v9
	v_fmac_f32_e32 v24, v27, v23
	v_fma_f32 v9, -v18, v24, v9
	v_div_fmas_f32 v9, v9, v23, v24
	v_div_fixup_f32 v9, v9, v26, v17
	v_cvt_pk_f16_f32 v23, v9, v8
	v_mad_i64_i32 v[8:9], s[0:1], v16, s35, v[6:7]
	v_lshl_add_u64 v[0:1], v[8:9], 0, v[0:1]
	global_store_dwordx4 v[0:1], v[20:23], off
	v_mul_hi_i32 v0, v25, s28
	v_lshrrev_b32_e32 v1, 31, v0
	v_ashrrev_i32_e32 v0, 3, v0
	v_add_u32_e32 v8, v0, v1
	v_mul_lo_u32 v0, v8, 48
	v_sub_u32_e32 v9, v25, v0
	v_add_u32_e32 v20, s80, v8
	v_lshlrev_b32_e32 v54, 3, v9
	v_subrev_u32_e32 v0, s31, v20
	v_ashrrev_i32_e32 v55, 31, v54
	v_mad_i64_i32 v[22:23], s[0:1], v0, s25, v[4:5]
	v_lshlrev_b64 v[0:1], 1, v[54:55]
	v_lshl_add_u64 v[22:23], v[22:23], 0, v[0:1]
	v_mov_b32_e32 v22, v174
	v_mov_b32_e32 v23, v175
	v_mov_b32_e32 v24, v176
	v_mov_b32_e32 v25, v177
	v_mad_i64_i32 v[66:67], s[0:1], v20, s35, 0
	v_cvt_f32_f16_e32 v17, v22
	v_cvt_f32_f16_sdwa v18, v22 dst_sel:DWORD dst_unused:UNUSED_PAD src0_sel:WORD_1
	v_cvt_f32_f16_sdwa v31, v23 dst_sel:DWORD dst_unused:UNUSED_PAD src0_sel:WORD_1
	v_mul_f32_e32 v21, 0xbfb8aa3b, v17
	v_exp_f32_e32 v26, v21
	v_mul_f32_e32 v21, 0xbfb8aa3b, v18
	v_exp_f32_e32 v27, v21
	s_nop 0
	v_pk_add_f32 v[26:27], v[26:27], 1.0 op_sel_hi:[1,0]
	s_nop 0
	v_div_scale_f32 v21, s[0:1], v27, v27, v18
	v_rcp_f32_e32 v22, v21
	s_nop 0
	v_fma_f32 v28, -v21, v22, 1.0
	v_fmac_f32_e32 v22, v28, v22
	v_div_scale_f32 v28, vcc, v18, v27, v18
	v_mul_f32_e32 v29, v28, v22
	v_fma_f32 v30, -v21, v29, v28
	v_fmac_f32_e32 v29, v30, v22
	v_fma_f32 v21, -v21, v29, v28
	v_div_scale_f32 v28, s[0:1], v26, v26, v17
	v_rcp_f32_e32 v30, v28
	v_div_fmas_f32 v21, v21, v22, v29
	v_div_fixup_f32 v18, v21, v27, v18
	v_div_scale_f32 v27, vcc, v17, v26, v17
	v_fma_f32 v21, -v28, v30, 1.0
	v_fmac_f32_e32 v30, v21, v30
	v_cvt_f32_f16_e32 v21, v23
	v_mul_f32_e32 v23, 0xbfb8aa3b, v31
	v_exp_f32_e32 v23, v23
	v_mul_f32_e32 v32, v27, v30
	v_mul_f32_e32 v22, 0xbfb8aa3b, v21
	v_exp_f32_e32 v22, v22
	v_fma_f32 v29, -v28, v32, v27
	v_fmac_f32_e32 v32, v29, v30
	v_fma_f32 v27, -v28, v32, v27
	v_pk_add_f32 v[28:29], v[22:23], 1.0 op_sel_hi:[1,0]
	v_div_fmas_f32 v22, v27, v30, v32
	v_div_scale_f32 v23, s[0:1], v29, v29, v31
	v_rcp_f32_e32 v33, v23
	v_div_fixup_f32 v17, v22, v26, v17
	v_cvt_pk_f16_f32 v22, v17, v18
	v_fma_f32 v17, -v23, v33, 1.0
	v_fmac_f32_e32 v33, v17, v33
	v_div_scale_f32 v17, vcc, v31, v29, v31
	v_mul_f32_e32 v18, v17, v33
	v_fma_f32 v26, -v23, v18, v17
	v_fmac_f32_e32 v18, v26, v33
	v_fma_f32 v17, -v23, v18, v17
	v_div_scale_f32 v23, s[0:1], v28, v28, v21
	v_rcp_f32_e32 v30, v23
	v_div_fmas_f32 v17, v17, v33, v18
	v_div_fixup_f32 v17, v17, v29, v31
	v_div_scale_f32 v29, vcc, v21, v28, v21
	v_fma_f32 v18, -v23, v30, 1.0
	v_fmac_f32_e32 v30, v18, v30
	v_cvt_f32_f16_e32 v18, v24
	v_cvt_f32_f16_sdwa v24, v24 dst_sel:DWORD dst_unused:UNUSED_PAD src0_sel:WORD_1
	v_mul_f32_e32 v31, v29, v30
	v_fma_f32 v32, -v23, v31, v29
	v_mul_f32_e32 v26, 0xbfb8aa3b, v18
	v_mul_f32_e32 v27, 0xbfb8aa3b, v24
	v_exp_f32_e32 v26, v26
	v_exp_f32_e32 v27, v27
	v_fmac_f32_e32 v31, v32, v30
	v_fma_f32 v23, -v23, v31, v29
	v_div_fmas_f32 v23, v23, v30, v31
	v_pk_add_f32 v[26:27], v[26:27], 1.0 op_sel_hi:[1,0]
	v_div_fixup_f32 v21, v23, v28, v21
	v_div_scale_f32 v29, s[0:1], v27, v27, v24
	v_rcp_f32_e32 v32, v29
	v_cvt_pk_f16_f32 v23, v21, v17
	v_cvt_f32_f16_sdwa v31, v25 dst_sel:DWORD dst_unused:UNUSED_PAD src0_sel:WORD_1
	v_fma_f32 v17, -v29, v32, 1.0
	v_fmac_f32_e32 v32, v17, v32
	v_div_scale_f32 v17, vcc, v24, v27, v24
	v_mul_f32_e32 v21, v17, v32
	v_fma_f32 v28, -v29, v21, v17
	v_fmac_f32_e32 v21, v28, v32
	v_div_scale_f32 v28, s[0:1], v26, v26, v18
	v_rcp_f32_e32 v30, v28
	v_fma_f32 v17, -v29, v21, v17
	v_div_fmas_f32 v17, v17, v32, v21
	v_div_fixup_f32 v17, v17, v27, v24
	v_fma_f32 v21, -v28, v30, 1.0
	v_fmac_f32_e32 v30, v21, v30
	v_cvt_f32_f16_e32 v21, v25
	v_mul_f32_e32 v25, 0xbfb8aa3b, v31
	v_div_scale_f32 v27, vcc, v18, v26, v18
	v_mul_f32_e32 v24, 0xbfb8aa3b, v21
	v_exp_f32_e32 v24, v24
	v_exp_f32_e32 v25, v25
	v_mul_f32_e32 v32, v27, v30
	v_fma_f32 v29, -v28, v32, v27
	v_fmac_f32_e32 v32, v29, v30
	v_fma_f32 v27, -v28, v32, v27
	v_pk_add_f32 v[28:29], v[24:25], 1.0 op_sel_hi:[1,0]
	v_div_fmas_f32 v24, v27, v30, v32
	v_div_scale_f32 v25, s[0:1], v29, v29, v31
	v_rcp_f32_e32 v33, v25
	v_div_fixup_f32 v18, v24, v26, v18
	v_cvt_pk_f16_f32 v24, v18, v17
	v_fma_f32 v17, -v25, v33, 1.0
	v_fmac_f32_e32 v33, v17, v33
	v_div_scale_f32 v17, vcc, v31, v29, v31
	v_mul_f32_e32 v18, v17, v33
	v_fma_f32 v26, -v25, v18, v17
	v_fmac_f32_e32 v18, v26, v33
	v_fma_f32 v17, -v25, v18, v17
	v_div_scale_f32 v25, s[0:1], v28, v28, v21
	v_rcp_f32_e32 v26, v25
	v_div_fmas_f32 v17, v17, v33, v18
	v_div_fixup_f32 v17, v17, v29, v31
	v_fma_f32 v18, -v25, v26, 1.0
	v_fmac_f32_e32 v26, v18, v26
	v_div_scale_f32 v18, vcc, v21, v28, v21
	v_mul_f32_e32 v27, v18, v26
	v_fma_f32 v29, -v25, v27, v18
	v_fmac_f32_e32 v27, v29, v26
	v_fma_f32 v18, -v25, v27, v18
; DEVI float siluf_(float x) { return x / (1.f + __expf(-x)); }
; DEVI void prepA_tile(const Params& p, int l, int g, int tile, char* lds) {
;     ...
;     for (int i = 0; i < 6; ++i) {
;       int it = tid + i * 512; int tok = it / 48, ch = it % 48; int t = t0 + tok;
;       h16x8 z = *(const h16x8*)(Z + (size_t)(t - g * TG) * NA + 1408 + ch * 8);
;       h16x8 ov;
; #pragma unroll
;       for (int j = 0; j < 8; ++j) ov[j] = (h16)siluf_((float)z[j]);
;       *(h16x8*)(Sga + (size_t)t * 384 + ch * 8) = ov;
;     }
	v_div_fmas_f32 v18, v18, v26, v27
	v_div_fixup_f32 v18, v18, v28, v21
	v_mad_i64_i32 v[26:27], s[0:1], v20, s35, v[6:7]
	v_cvt_pk_f16_f32 v25, v18, v17
	v_lshl_add_u64 v[0:1], v[26:27], 0, v[0:1]
	global_store_dwordx4 v[0:1], v[22:25], off
	v_add_u32_e32 v0, 0x800, v19
	v_mul_hi_i32 v1, v0, s28
	v_lshrrev_b32_e32 v17, 31, v1
	v_ashrrev_i32_e32 v1, 3, v1
	v_add_u32_e32 v17, v1, v17
	v_mul_lo_u32 v1, v17, 48
	v_sub_u32_e32 v18, v0, v1
	v_add_u32_e32 v21, s80, v17
	v_lshlrev_b32_e32 v56, 3, v18
	v_subrev_u32_e32 v0, s31, v21
	v_ashrrev_i32_e32 v57, 31, v56
	v_mad_i64_i32 v[22:23], s[0:1], v0, s25, v[4:5]
	v_lshlrev_b64 v[0:1], 1, v[56:57]
	v_lshl_add_u64 v[22:23], v[22:23], 0, v[0:1]
	v_mov_b32_e32 v22, v178
	v_mov_b32_e32 v23, v179
	v_mov_b32_e32 v24, v180
	v_mov_b32_e32 v25, v181
	v_mad_i64_i32 v[68:69], s[0:1], v21, s35, 0
	v_cvt_f32_f16_e32 v30, v22
	v_cvt_f32_f16_sdwa v22, v22 dst_sel:DWORD dst_unused:UNUSED_PAD src0_sel:WORD_1
	v_cvt_f32_f16_sdwa v34, v23 dst_sel:DWORD dst_unused:UNUSED_PAD src0_sel:WORD_1
	v_mul_f32_e32 v26, 0xbfb8aa3b, v30
	v_mul_f32_e32 v27, 0xbfb8aa3b, v22
	v_exp_f32_e32 v26, v26
	v_exp_f32_e32 v27, v27
	s_nop 0
	v_pk_add_f32 v[26:27], v[26:27], 1.0 op_sel_hi:[1,0]
	s_nop 0
	v_div_scale_f32 v28, s[0:1], v27, v27, v22
	v_rcp_f32_e32 v29, v28
	s_nop 0
	v_fma_f32 v31, -v28, v29, 1.0
	v_fmac_f32_e32 v29, v31, v29
	v_div_scale_f32 v31, vcc, v22, v27, v22
	v_mul_f32_e32 v32, v31, v29
	v_fma_f32 v33, -v28, v32, v31
	v_fmac_f32_e32 v32, v33, v29
	v_fma_f32 v28, -v28, v32, v31
	v_div_scale_f32 v31, s[0:1], v26, v26, v30
	v_rcp_f32_e32 v33, v31
	v_div_fmas_f32 v28, v28, v29, v32
	v_cvt_f32_f16_e32 v32, v23
	v_div_fixup_f32 v27, v28, v27, v22
	v_fma_f32 v22, -v31, v33, 1.0
	v_fmac_f32_e32 v33, v22, v33
	v_mul_f32_e32 v22, 0xbfb8aa3b, v32
	v_mul_f32_e32 v23, 0xbfb8aa3b, v34
	v_div_scale_f32 v28, vcc, v30, v26, v30
	v_exp_f32_e32 v22, v22
	v_exp_f32_e32 v23, v23
	v_mul_f32_e32 v35, v28, v33
	v_fma_f32 v29, -v31, v35, v28
	v_fmac_f32_e32 v35, v29, v33
	v_fma_f32 v31, -v31, v35, v28
	v_pk_add_f32 v[28:29], v[22:23], 1.0 op_sel_hi:[1,0]
	v_div_fmas_f32 v22, v31, v33, v35
	v_div_scale_f32 v23, s[0:1], v29, v29, v34
	v_rcp_f32_e32 v36, v23
	v_div_fixup_f32 v22, v22, v26, v30
	v_cvt_pk_f16_f32 v22, v22, v27
	v_cvt_f32_f16_e32 v33, v24
	v_fma_f32 v26, -v23, v36, 1.0
	v_fmac_f32_e32 v36, v26, v36
	v_div_scale_f32 v26, vcc, v34, v29, v34
	v_mul_f32_e32 v27, v26, v36
	v_fma_f32 v30, -v23, v27, v26
	v_fmac_f32_e32 v27, v30, v36
	v_div_scale_f32 v30, s[0:1], v28, v28, v32
	v_rcp_f32_e32 v31, v30
	v_cvt_f32_f16_sdwa v24, v24 dst_sel:DWORD dst_unused:UNUSED_PAD src0_sel:WORD_1
	v_fma_f32 v23, -v23, v27, v26
	v_div_fmas_f32 v23, v23, v36, v27
	v_fma_f32 v26, -v30, v31, 1.0
	v_fmac_f32_e32 v31, v26, v31
	v_mul_f32_e32 v26, 0xbfb8aa3b, v33
	v_mul_f32_e32 v27, 0xbfb8aa3b, v24
	v_exp_f32_e32 v26, v26
	v_exp_f32_e32 v27, v27
	v_div_fixup_f32 v23, v23, v29, v34
	v_div_scale_f32 v29, vcc, v32, v28, v32
	v_mul_f32_e32 v34, v29, v31
	v_fma_f32 v35, -v30, v34, v29
	v_fmac_f32_e32 v34, v35, v31
	v_pk_add_f32 v[26:27], v[26:27], 1.0 op_sel_hi:[1,0]
	v_fma_f32 v29, -v30, v34, v29
	v_div_scale_f32 v30, s[0:1], v27, v27, v24
	v_rcp_f32_e32 v35, v30
	v_div_fmas_f32 v29, v29, v31, v34
	v_div_fixup_f32 v28, v29, v28, v32
	v_cvt_pk_f16_f32 v23, v28, v23
	v_fma_f32 v28, -v30, v35, 1.0
	v_fmac_f32_e32 v35, v28, v35
	v_div_scale_f32 v28, vcc, v24, v27, v24
	v_mul_f32_e32 v29, v28, v35
	v_fma_f32 v31, -v30, v29, v28
	v_fmac_f32_e32 v29, v31, v35
	v_fma_f32 v28, -v30, v29, v28
	v_div_scale_f32 v30, s[0:1], v26, v26, v33
	v_rcp_f32_e32 v31, v30
	v_cvt_f32_f16_e32 v32, v25
	v_cvt_f32_f16_sdwa v34, v25 dst_sel:DWORD dst_unused:UNUSED_PAD src0_sel:WORD_1
	v_div_fmas_f32 v28, v28, v35, v29
	v_div_fixup_f32 v27, v28, v27, v24
	v_fma_f32 v24, -v30, v31, 1.0
	v_fmac_f32_e32 v31, v24, v31
	v_mul_f32_e32 v24, 0xbfb8aa3b, v32
	v_mul_f32_e32 v25, 0xbfb8aa3b, v34
	v_div_scale_f32 v28, vcc, v33, v26, v33
	v_exp_f32_e32 v24, v24
	v_exp_f32_e32 v25, v25
	v_mul_f32_e32 v35, v28, v31
	v_fma_f32 v29, -v30, v35, v28
	v_fmac_f32_e32 v35, v29, v31
	v_fma_f32 v30, -v30, v35, v28
	v_pk_add_f32 v[28:29], v[24:25], 1.0 op_sel_hi:[1,0]
	v_div_fmas_f32 v24, v30, v31, v35
	v_div_scale_f32 v25, s[0:1], v29, v29, v34
	v_rcp_f32_e32 v36, v25
	v_div_fixup_f32 v24, v24, v26, v33
	v_cvt_pk_f16_f32 v24, v24, v27
	v_fma_f32 v26, -v25, v36, 1.0
	v_fmac_f32_e32 v36, v26, v36
	v_div_scale_f32 v26, vcc, v34, v29, v34
	v_mul_f32_e32 v27, v26, v36
	v_fma_f32 v30, -v25, v27, v26
	v_fmac_f32_e32 v27, v30, v36
	v_fma_f32 v25, -v25, v27, v26
	v_div_scale_f32 v26, s[0:1], v28, v28, v32
	v_rcp_f32_e32 v30, v26
	v_div_fmas_f32 v25, v25, v36, v27
	v_div_fixup_f32 v25, v25, v29, v34
	v_fma_f32 v27, -v26, v30, 1.0
	v_fmac_f32_e32 v30, v27, v30
	v_div_scale_f32 v27, vcc, v32, v28, v32
	v_mul_f32_e32 v29, v27, v30
	v_fma_f32 v31, -v26, v29, v27
	v_fmac_f32_e32 v29, v31, v30
	v_fma_f32 v26, -v26, v29, v27
	v_div_fmas_f32 v26, v26, v30, v29
	v_div_fixup_f32 v26, v26, v28, v32
	v_cvt_pk_f16_f32 v25, v26, v25
	v_mad_i64_i32 v[26:27], s[0:1], v21, s35, v[6:7]
	v_lshl_add_u64 v[0:1], v[26:27], 0, v[0:1]
	global_store_dwordx4 v[0:1], v[22:25], off
	v_add_u32_e32 v0, 0xa00, v19
	v_mul_hi_i32 v1, v0, s28
	v_lshrrev_b32_e32 v22, 31, v1
	v_ashrrev_i32_e32 v1, 3, v1
	v_add_u32_e32 v26, v1, v22
	v_mul_lo_u32 v1, v26, 48
	v_sub_u32_e32 v27, v0, v1
	v_add_u32_e32 v28, s80, v26
	v_lshlrev_b32_e32 v58, 3, v27
	v_subrev_u32_e32 v0, s31, v28
	v_ashrrev_i32_e32 v59, 31, v58
	v_mad_i64_i32 v[4:5], s[0:1], v0, s25, v[4:5]
	v_lshlrev_b64 v[0:1], 1, v[58:59]
	v_lshl_add_u64 v[4:5], v[4:5], 0, v[0:1]
	v_mov_b32_e32 v22, v182
	v_mov_b32_e32 v23, v183
; DEVI float siluf_(float x) { return x / (1.f + __expf(-x)); }
; DEVI void prepA_tile(const Params& p, int l, int g, int tile, char* lds) {
;     ...
;     for (int i = 0; i < 6; ++i) {
;       int it = tid + i * 512; int tok = it / 48, ch = it % 48; int t = t0 + tok;
;       h16x8 z = *(const h16x8*)(Z + (size_t)(t - g * TG) * NA + 1408 + ch * 8);
;       h16x8 ov;
; #pragma unroll
;       for (int j = 0; j < 8; ++j) ov[j] = (h16)siluf_((float)z[j]);
;       *(h16x8*)(Sga + (size_t)t * 384 + ch * 8) = ov;
;     }
;     ...
;     const int l15 = lane & 15, l4 = lane >> 4;
; #pragma unroll 1
;     for (int lo = 0; lo < 4; ++lo) {
;       const int d = lo & 1;
;       const u16* Wt = (const u16*)(p.ws + (lo < 2 ? OFF_WD : OFF_WA)) + (size_t)(l * 2 + d) * 384 * 64;
;       f32x4 acc[4][3];
; #pragma unroll
;       for (int mb = 0; mb < 4; ++mb)
; #pragma unroll
;         for (int nb = 0; nb < 3; ++nb) acc[mb][nb] = (f32x4){0.f, 0.f, 0.f, 0.f};
; #pragma unroll
;       for (int ks = 0; ks < 2; ++ks) {
;         bf16x8 bfr[3];
; #pragma unroll
;         for (int nb = 0; nb < 3; ++nb) bfr[nb] = *(const bf16x8*)(Wt + (size_t)(wid * 48 + nb * 16 + l15) * 64 + ks * 32 + l4 * 8);
; #pragma unroll
;         for (int mb = 0; mb < 4; ++mb) {
;           bf16x8 a = *(const bf16x8*)(lds + (lo * 64 + mb * 16 + l15) * RS + ks * 64 + l4 * 16);
	v_mov_b32_e32 v24, v184
	v_mov_b32_e32 v25, v185
	v_mad_i64_i32 v[70:71], s[0:1], v28, s35, 0
	v_cvt_f32_f16_e32 v29, v22
	v_cvt_f32_f16_sdwa v22, v22 dst_sel:DWORD dst_unused:UNUSED_PAD src0_sel:WORD_1
	v_cvt_f32_f16_sdwa v31, v23 dst_sel:DWORD dst_unused:UNUSED_PAD src0_sel:WORD_1
	v_mul_f32_e32 v4, 0xbfb8aa3b, v29
	v_mul_f32_e32 v5, 0xbfb8aa3b, v22
	v_exp_f32_e32 v4, v4
	v_exp_f32_e32 v5, v5
	s_nop 0
	v_pk_add_f32 v[4:5], v[4:5], 1.0 op_sel_hi:[1,0]
	s_nop 0
	v_div_scale_f32 v12, s[0:1], v5, v5, v22
	v_rcp_f32_e32 v15, v12
	s_nop 0
	v_fma_f32 v16, -v12, v15, 1.0
	v_fmac_f32_e32 v15, v16, v15
	v_div_scale_f32 v16, vcc, v22, v5, v22
	v_mul_f32_e32 v20, v16, v15
	v_fma_f32 v21, -v12, v20, v16
	v_fmac_f32_e32 v20, v21, v15
	v_fma_f32 v12, -v12, v20, v16
	v_div_scale_f32 v16, s[0:1], v4, v4, v29
	v_rcp_f32_e32 v30, v16
	v_div_fmas_f32 v12, v12, v15, v20
	v_div_fixup_f32 v5, v12, v5, v22
	v_mul_f32_e32 v21, 0xbfb8aa3b, v31
	v_fma_f32 v12, -v16, v30, 1.0
	v_fmac_f32_e32 v30, v12, v30
	v_cvt_f32_f16_e32 v12, v23
	v_exp_f32_e32 v21, v21
	v_div_scale_f32 v15, vcc, v29, v4, v29
	v_mul_f32_e32 v20, 0xbfb8aa3b, v12
	v_exp_f32_e32 v20, v20
	v_mul_f32_e32 v32, v15, v30
	v_fma_f32 v22, -v16, v32, v15
	v_fmac_f32_e32 v32, v22, v30
	v_pk_add_f32 v[22:23], v[20:21], 1.0 op_sel_hi:[1,0]
	v_fma_f32 v15, -v16, v32, v15
	v_div_scale_f32 v16, s[0:1], v23, v23, v31
	v_rcp_f32_e32 v21, v16
	v_div_fmas_f32 v15, v15, v30, v32
	v_div_fixup_f32 v4, v15, v4, v29
	v_cvt_pk_f16_f32 v20, v4, v5
	v_fma_f32 v4, -v16, v21, 1.0
	v_fmac_f32_e32 v21, v4, v21
	v_div_scale_f32 v4, vcc, v31, v23, v31
	v_mul_f32_e32 v5, v4, v21
	v_fma_f32 v15, -v16, v5, v4
	v_fmac_f32_e32 v5, v15, v21
	v_div_scale_f32 v15, s[0:1], v22, v22, v12
	v_fma_f32 v4, -v16, v5, v4
	v_rcp_f32_e32 v16, v15
	v_cvt_f32_f16_e32 v29, v24
	v_cvt_f32_f16_sdwa v24, v24 dst_sel:DWORD dst_unused:UNUSED_PAD src0_sel:WORD_1
	v_div_fmas_f32 v4, v4, v21, v5
	v_div_fixup_f32 v21, v4, v23, v31
	v_fma_f32 v4, -v15, v16, 1.0
	v_fmac_f32_e32 v16, v4, v16
	v_mul_f32_e32 v4, 0xbfb8aa3b, v29
	v_mul_f32_e32 v5, 0xbfb8aa3b, v24
	v_exp_f32_e32 v4, v4
	v_exp_f32_e32 v5, v5
	v_div_scale_f32 v23, vcc, v12, v22, v12
	v_mul_f32_e32 v30, v23, v16
	v_fma_f32 v31, -v15, v30, v23
	v_fmac_f32_e32 v30, v31, v16
	v_pk_add_f32 v[4:5], v[4:5], 1.0 op_sel_hi:[1,0]
	v_fma_f32 v15, -v15, v30, v23
	v_div_scale_f32 v23, s[0:1], v5, v5, v24
	v_rcp_f32_e32 v31, v23
	v_div_fmas_f32 v15, v15, v16, v30
	v_div_fixup_f32 v12, v15, v22, v12
	v_cvt_pk_f16_f32 v21, v12, v21
	v_fma_f32 v12, -v23, v31, 1.0
	v_fmac_f32_e32 v31, v12, v31
	v_div_scale_f32 v12, vcc, v24, v5, v24
	v_mul_f32_e32 v15, v12, v31
	v_fma_f32 v16, -v23, v15, v12
	v_fmac_f32_e32 v15, v16, v31
	v_div_scale_f32 v16, s[0:1], v4, v4, v29
	v_rcp_f32_e32 v30, v16
	v_fma_f32 v12, -v23, v15, v12
	v_div_fmas_f32 v12, v12, v31, v15
	v_div_fixup_f32 v5, v12, v5, v24
	v_fma_f32 v12, -v16, v30, 1.0
	v_fmac_f32_e32 v30, v12, v30
	v_cvt_f32_f16_e32 v12, v25
	v_cvt_f32_f16_sdwa v31, v25 dst_sel:DWORD dst_unused:UNUSED_PAD src0_sel:WORD_1
	v_div_scale_f32 v15, vcc, v29, v4, v29
	v_mul_f32_e32 v22, 0xbfb8aa3b, v12
	v_mul_f32_e32 v23, 0xbfb8aa3b, v31
	v_exp_f32_e32 v22, v22
	v_exp_f32_e32 v23, v23
	v_mul_f32_e32 v32, v15, v30
	v_fma_f32 v24, -v16, v32, v15
	v_fmac_f32_e32 v32, v24, v30
	v_pk_add_f32 v[24:25], v[22:23], 1.0 op_sel_hi:[1,0]
	v_fma_f32 v15, -v16, v32, v15
	v_div_scale_f32 v16, s[0:1], v25, v25, v31
	v_rcp_f32_e32 v23, v16
	v_div_fmas_f32 v15, v15, v30, v32
	v_div_fixup_f32 v4, v15, v4, v29
	v_cvt_pk_f16_f32 v22, v4, v5
	v_fma_f32 v4, -v16, v23, 1.0
	v_fmac_f32_e32 v23, v4, v23
	v_div_scale_f32 v4, vcc, v31, v25, v31
	v_mul_f32_e32 v5, v4, v23
	v_fma_f32 v15, -v16, v5, v4
	v_fmac_f32_e32 v5, v15, v23
	v_div_scale_f32 v15, s[0:1], v24, v24, v12
	v_fma_f32 v4, -v16, v5, v4
	v_rcp_f32_e32 v16, v15
	v_div_fmas_f32 v4, v4, v23, v5
	v_div_fixup_f32 v4, v4, v25, v31
	v_fma_f32 v5, -v15, v16, 1.0
	v_fmac_f32_e32 v16, v5, v16
	v_div_scale_f32 v5, vcc, v12, v24, v12
	v_mul_f32_e32 v23, v5, v16
	v_fma_f32 v25, -v15, v23, v5
	v_fmac_f32_e32 v23, v25, v16
	v_fma_f32 v5, -v15, v23, v5
	v_div_fmas_f32 v5, v5, v16, v23
	v_div_fixup_f32 v5, v5, v24, v12
	v_cvt_pk_f16_f32 v23, v5, v4
	v_mad_i64_i32 v[4:5], s[0:1], v28, s35, v[6:7]
	v_lshl_add_u64 v[0:1], v[4:5], 0, v[0:1]
	global_store_dwordx4 v[0:1], v[20:23], off
	v_ashrrev_i32_e32 v0, 6, v19
	v_and_b32_e32 v1, 15, v19
	v_mul_lo_u32 v0, v0, 48
	s_movk_i32 s0, 0x310
	v_or_b32_e32 v72, v0, v1
	v_mul_lo_u32 v4, v10, s0
	v_add_u32_e32 v10, 16, v4
	v_add_u32_e32 v4, 16, v72
	v_add_u32_e32 v6, 32, v72
	v_bfe_u32 v12, v19, 4, 2
	v_ashrrev_i32_e32 v5, 31, v4
	v_ashrrev_i32_e32 v7, 31, v6
	s_movk_i32 s1, 0xc40
	v_lshlrev_b32_e32 v0, 3, v12
	v_lshlrev_b32_e32 v15, 4, v12
	v_lshlrev_b64 v[76:77], 7, v[4:5]
	v_lshlrev_b64 v[78:79], 7, v[6:7]
	v_mul_u32_u24_e32 v83, 0xc40, v12
	v_mad_u32_u24 v84, v12, s1, v147
	v_mad_u32_u24 v85, v12, s1, v148
	v_mad_u32_u24 v86, v12, s1, v149
	v_mad_u32_u24 v87, v12, s1, v150
	v_mad_u32_u24 v88, v12, s1, v151
	v_mad_u32_u24 v89, v12, s1, v152
	v_mad_u32_u24 v90, v12, s1, v153
	v_mad_u32_u24 v91, v12, s1, v154
	v_lshl_add_u32 v92, v4, 1, 16
	v_lshl_add_u32 v93, v6, 1, 16
	v_mul_lo_u32 v4, v13, s0
	v_mul_lo_u32 v2, v2, s0
	v_mul_lo_u32 v6, v8, s0
	v_mul_lo_u32 v8, v17, s0
	v_mul_lo_u32 v12, v26, s0
	v_ashrrev_i32_e32 v73, 31, v72
	v_add_u32_e32 v4, 16, v4
	v_lshlrev_b32_e32 v5, 4, v14
	v_add_u32_e32 v2, 16, v2
	v_add_u32_e32 v6, 16, v6
	v_lshlrev_b32_e32 v7, 4, v9
	v_add_u32_e32 v8, 16, v8
	v_lshlrev_b32_e32 v9, 4, v18
	v_add_u32_e32 v12, 16, v12
	v_lshlrev_b32_e32 v13, 4, v27
	v_mul_u32_u24_e32 v1, 0x90, v1
	v_lshlrev_b64 v[74:75], 7, v[72:73]
	v_lshl_add_u32 v82, v72, 1, 16
	v_add3_u32 v94, v1, v15, 16
	s_mov_b32 s0, 0
	v_lshlrev_b32_e32 v128, 1, v0
	v_add_u32_e32 v95, v10, v11
	v_add_u32_e32 v96, v4, v5
	v_add_u32_e32 v97, v2, v3
	v_add_u32_e32 v98, v6, v7
	v_add_u32_e32 v99, v8, v9
	v_add_u32_e32 v100, v12, v13
	s_waitcnt lgkmcnt(0)
	s_barrier
